# write-through (sc1) stores for the outputs of the mixer phases (SEL lists, normalised Q/K rows, DSA and stick-breaking attention outputs) so the grid barrier's L2 write-back has nothing dirty to flush
# baseline (speedup 1.0000x reference)
; __device__ __forceinline__ void idx_unit(bf16* QB, float* SC, int* SEL, const float* qg, const float* kg, int b, int tp, LAS unsigned char* wl, int lane, bool do_norm) {
;     ...
;     } else {
; #pragma unroll
;         for (int i = 0; i < 4; ++i) { const int p = lane + 64 * i; if (p < ce) {
; #pragma unroll
;             for (int a = 0; a < 4; ++a) SEL[(row + a) * 256 + p] = p; } }
; __global__ void __launch_bounds__(NWAVES * 64, 2) fwd_megakernel(Args args) {
;     ...
;                 const int per = SEQ / 4;
;                 for (int rep = 0; rep < REP_IDX; ++rep) for (int i = 0; i * ngw < NBATCH * per; ++i) { const int u = i * ngw + gw; if (u >= NBATCH * per) break;
;                     const int bb = u / per; int tp = u % per; if (i & 1) tp = per - 1 - tp;
.LBB0_230:
	s_add_i32 s3, s2, s66
	s_cmpk_gt_i32 s3, 0xfff
	s_mov_b64 s[0:1], -1
	s_cbranch_scc1 .LBB0_229
	s_ashr_i32 s0, s3, 31
	s_lshr_b32 s0, s0, 22
	s_add_i32 s1, s3, s0
	s_ashr_i32 s0, s1, 10
	s_and_b32 s1, s1, 0xfffffc00
	s_sub_i32 s1, s3, s1
	s_and_b32 s2, s11, 1
	s_sub_i32 s3, 0x3ff, s1
	s_cmp_eq_u32 s2, 0
	s_cselect_b32 s1, s1, s3
	s_lshl_b32 s7, s1, 2
	s_ashr_i32 s1, s0, 31
	s_lshl_b64 s[0:1], s[0:1], 12
	s_ashr_i32 s3, s7, 31
	s_add_u32 s2, s0, s7
	s_addc_u32 s79, s1, s3
	s_andn2_b32 s7, s7, 63
	s_add_i32 s6, s7, 64
	s_mov_b64 s[14:15], 0x2000
	s_movk_i32 s10, 0x2000
	s_mov_b32 s3, s79
	s_cmpk_gt_i32 s7, 0xff
	s_mov_b64 s[4:5], -1
	s_cbranch_scc1 .LBB0_241
	v_cmp_gt_i32_e32 vcc, s6, v96
	s_and_saveexec_b64 s[4:5], vcc
	s_cbranch_execz .LBB0_236
	s_lshl_b64 s[8:9], s[2:3], 10
	v_lshl_add_u64 v[0:1], v[98:99], 0, s[8:9]
	global_store_dword v[0:1], v96, off sc1
	global_store_dword v[0:1], v96, off offset:1024 sc1
	global_store_dword v[0:1], v96, off offset:2048 sc1
	global_store_dword v[0:1], v96, off offset:3072 sc1
	s_or_b64 exec, exec, s[4:5]
	v_cmp_gt_i32_e32 vcc, s7, v96
	s_and_saveexec_b64 s[4:5], vcc
	s_cbranch_execnz .LBB0_237

; __device__ __forceinline__ void idx_unit(bf16* QB, float* SC, int* SEL, const float* qg, const float* kg, int b, int tp, LAS unsigned char* wl, int lane, bool do_norm) {
;     ...
;     } else {
; #pragma unroll
;         for (int i = 0; i < 4; ++i) { const int p = lane + 64 * i; if (p < ce) {
; #pragma unroll
;             for (int a = 0; a < 4; ++a) SEL[(row + a) * 256 + p] = p; } }
.LBB0_235:
	s_lshl_b64 s[8:9], s[2:3], 10
	v_lshl_add_u64 v[0:1], v[188:189], 0, s[8:9]
	global_store_dword v[0:1], v102, off sc1
	global_store_dword v[0:1], v102, off offset:1024 sc1
	global_store_dword v[0:1], v102, off offset:2048 sc1
	global_store_dword v[0:1], v102, off offset:3072 sc1
	s_or_b64 exec, exec, s[4:5]
	v_cmp_gt_i32_e32 vcc, s6, v104
	s_and_saveexec_b64 s[4:5], vcc
	s_cbranch_execnz .LBB0_239
	s_branch .LBB0_240

; __device__ __forceinline__ void idx_unit(bf16* QB, float* SC, int* SEL, const float* qg, const float* kg, int b, int tp, LAS unsigned char* wl, int lane, bool do_norm) {
;     ...
;     } else {
; #pragma unroll
;         for (int i = 0; i < 4; ++i) { const int p = lane + 64 * i; if (p < ce) {
; #pragma unroll
;             for (int a = 0; a < 4; ++a) SEL[(row + a) * 256 + p] = p; } }
.LBB0_237:
	s_lshl_b64 s[8:9], s[2:3], 10
	v_lshl_add_u64 v[0:1], v[248:249], 0, s[8:9]
	global_store_dword v[0:1], v100, off sc1
	global_store_dword v[0:1], v100, off offset:1024 sc1
	global_store_dword v[0:1], v100, off offset:2048 sc1
	global_store_dword v[0:1], v100, off offset:3072 sc1
	s_or_b64 exec, exec, s[4:5]
	v_cmp_gt_i32_e32 vcc, s6, v102
	s_and_saveexec_b64 s[4:5], vcc
	s_cbranch_execnz .LBB0_235

; __device__ __forceinline__ void idx_unit(bf16* QB, float* SC, int* SEL, const float* qg, const float* kg, int b, int tp, LAS unsigned char* wl, int lane, bool do_norm) {
;     ...
;     } else {
; #pragma unroll
;         for (int i = 0; i < 4; ++i) { const int p = lane + 64 * i; if (p < ce) {
; #pragma unroll
;             for (int a = 0; a < 4; ++a) SEL[(row + a) * 256 + p] = p; } }
.LBB0_239:
	s_lshl_b64 s[8:9], s[2:3], 10
	v_lshl_add_u64 v[0:1], v[124:125], 0, s[8:9]
	global_store_dword v[0:1], v104, off sc1
	global_store_dword v[0:1], v104, off offset:1024 sc1
	global_store_dword v[0:1], v104, off offset:2048 sc1
	global_store_dword v[0:1], v104, off offset:3072 sc1

; __device__ __forceinline__ int mbcnt(unsigned long long m) { return __builtin_amdgcn_mbcnt_hi((unsigned)(m >> 32), __builtin_amdgcn_mbcnt_lo((unsigned)m, 0u)); }
; #define PIN8(m) asm volatile("" : "+s"(m[0]), "+s"(m[1]), "+s"(m[2]), "+s"(m[3]), "+s"(m[4]), "+s"(m[5]), "+s"(m[6]), "+s"(m[7]))
; __device__ __forceinline__ void select_query(const float* sc, int* sel, int ce, int lane) {
;     ...
;     int pos = 0;
; #pragma unroll
;     for (int g = 0; g < 8; ++g) if (8 * g < nreg) {
;         unsigned long long m[8];
; #pragma unroll
;         for (int j = 0; j < 8; ++j) m[j] = __ballot(key[8 * g + j] > thr);
;         PIN8(m);
; #pragma unroll
;         for (int j = 0; j < 8; ++j) { if (key[8 * g + j] > thr) sel[pos + mbcnt(m[j])] = lane + 64 * (8 * g + j); pos += __builtin_popcountll(m[j]); }
;         asm volatile("" : "+s"(pos));
;     }
.LBB0_277:
	v_cndmask_b32_e64 v65, 0, 1, s[4:5]
	s_lshl_b64 s[0:1], s[78:79], 10
	v_readlane_b32 s6, v251, 19
	v_sub_u32_e32 v65, v48, v65
	v_readlane_b32 s7, v251, 20
	s_add_u32 s0, s6, s0
	v_cmp_gt_u32_e64 s[34:35], v61, v65
	v_cmp_gt_u32_e64 s[24:25], v30, v65
	v_cmp_gt_u32_e64 s[28:29], v31, v65
	v_cmp_gt_u32_e64 s[16:17], v32, v65
	v_cmp_gt_u32_e64 s[20:21], v33, v65
	v_cmp_gt_u32_e64 s[12:13], v64, v65
	v_cmp_gt_u32_e64 s[4:5], v46, v65
	v_cmp_gt_u32_e64 s[10:11], v47, v65
	s_addc_u32 s1, s7, s1
	s_mov_b64 s[18:19], s[16:17]
	s_mov_b64 s[8:9], s[10:11]
	s_mov_b64 s[66:67], s[28:29]
	s_mov_b64 s[22:23], s[20:21]
	s_mov_b64 s[14:15], s[12:13]
	s_mov_b64 s[30:31], s[34:35]
	s_mov_b64 s[6:7], s[4:5]
	s_mov_b64 s[26:27], s[24:25]
	s_and_saveexec_b64 vcc, s[34:35]
	s_cbranch_execz .LBB0_279
	v_mbcnt_lo_u32_b32 v66, s30, 0
	v_mbcnt_hi_u32_b32 v66, s31, v66
	v_lshlrev_b32_e32 v66, 2, v66
	global_store_dword v66, v96, s[0:1] sc1
.LBB0_279:
	s_or_b64 exec, exec, vcc
	s_bcnt1_i32_b64 s72, s[30:31]
	s_and_saveexec_b64 s[30:31], s[28:29]
	s_cbranch_execz .LBB0_281
	v_mbcnt_lo_u32_b32 v66, s66, 0
	v_mbcnt_hi_u32_b32 v66, s67, v66
	v_add_lshl_u32 v66, v66, s72, 2
	global_store_dword v66, v100, s[0:1] sc1
.LBB0_281:
	s_or_b64 exec, exec, s[30:31]
	s_bcnt1_i32_b64 s28, s[66:67]
	s_add_i32 s30, s72, s28
	s_and_saveexec_b64 s[28:29], s[24:25]
	s_cbranch_execz .LBB0_283
	v_mbcnt_lo_u32_b32 v66, s26, 0
	v_mbcnt_hi_u32_b32 v66, s27, v66
	v_add_lshl_u32 v66, v66, s30, 2
	global_store_dword v66, v102, s[0:1] sc1
.LBB0_283:
	s_or_b64 exec, exec, s[28:29]
	s_bcnt1_i32_b64 s24, s[26:27]
	s_add_i32 s26, s30, s24
	s_and_saveexec_b64 s[24:25], s[20:21]
	s_cbranch_execz .LBB0_285
	v_mbcnt_lo_u32_b32 v66, s22, 0
	v_mbcnt_hi_u32_b32 v66, s23, v66
	v_add_lshl_u32 v66, v66, s26, 2
	global_store_dword v66, v104, s[0:1] sc1
.LBB0_285:
	s_or_b64 exec, exec, s[24:25]
	s_bcnt1_i32_b64 s20, s[22:23]
	s_add_i32 s22, s26, s20
	s_and_saveexec_b64 s[20:21], s[16:17]
	s_cbranch_execz .LBB0_287
	v_mbcnt_lo_u32_b32 v66, s18, 0
	v_mbcnt_hi_u32_b32 v66, s19, v66
	v_add_lshl_u32 v66, v66, s22, 2
	global_store_dword v66, v109, s[0:1] sc1
.LBB0_287:
	s_or_b64 exec, exec, s[20:21]
	s_bcnt1_i32_b64 s16, s[18:19]
	s_add_i32 s18, s22, s16
	s_and_saveexec_b64 s[16:17], s[12:13]
	s_cbranch_execz .LBB0_289
	v_mbcnt_lo_u32_b32 v66, s14, 0
	v_mbcnt_hi_u32_b32 v66, s15, v66
	v_add_lshl_u32 v66, v66, s18, 2
	global_store_dword v66, v111, s[0:1] sc1
.LBB0_289:
	s_or_b64 exec, exec, s[16:17]
	s_bcnt1_i32_b64 s12, s[14:15]
	s_add_i32 s14, s18, s12
	s_and_saveexec_b64 s[12:13], s[10:11]
	s_cbranch_execz .LBB0_291
	v_mbcnt_lo_u32_b32 v66, s8, 0
	v_mbcnt_hi_u32_b32 v66, s9, v66
	v_add_lshl_u32 v66, v66, s14, 2
	global_store_dword v66, v138, s[0:1] sc1
.LBB0_291:
	s_or_b64 exec, exec, s[12:13]
	s_bcnt1_i32_b64 s8, s[8:9]
	s_add_i32 s10, s14, s8
	s_and_saveexec_b64 s[8:9], s[4:5]
	s_cbranch_execz .LBB0_293
	v_mbcnt_lo_u32_b32 v66, s6, 0
	v_mbcnt_hi_u32_b32 v66, s7, v66
	v_add_lshl_u32 v66, v66, s10, 2
	global_store_dword v66, v139, s[0:1] sc1
.LBB0_293:
	s_or_b64 exec, exec, s[8:9]
	s_bcnt1_i32_b64 s4, s[6:7]
	s_add_i32 s78, s10, s4
	s_and_b64 vcc, exec, s[64:65]
	s_cbranch_vccnz .LBB0_365
	v_cmp_gt_u32_e64 s[34:35], v59, v65
	v_cmp_gt_u32_e64 s[26:27], v63, v65
	v_cmp_gt_u32_e64 s[18:19], v40, v65
	v_cmp_gt_u32_e64 s[22:23], v41, v65
	v_cmp_gt_u32_e64 s[66:67], v42, v65
	v_cmp_gt_u32_e64 s[16:17], v43, v65
	v_cmp_gt_u32_e64 s[6:7], v44, v65
	v_cmp_gt_u32_e64 s[10:11], v45, v65
	s_mov_b64 s[12:13], s[66:67]
	s_mov_b64 s[30:31], s[34:35]
	s_mov_b64 s[4:5], s[6:7]
	s_mov_b64 s[24:25], s[22:23]
	s_mov_b64 s[14:15], s[16:17]
	s_mov_b64 s[8:9], s[10:11]
	s_mov_b64 s[28:29], s[26:27]
	s_mov_b64 s[20:21], s[18:19]
	s_and_saveexec_b64 vcc, s[34:35]
	s_cbranch_execz .LBB0_296
	v_mbcnt_lo_u32_b32 v66, s30, 0
	v_mbcnt_hi_u32_b32 v66, s31, v66
	v_add_u32_e32 v66, s78, v66
	v_ashrrev_i32_e32 v67, 31, v66
	v_lshl_add_u64 v[66:67], v[66:67], 2, s[0:1]
	global_store_dword v[66:67], v140, off sc1
.LBB0_296:
	s_or_b64 exec, exec, vcc
	s_bcnt1_i32_b64 s30, s[30:31]
	s_add_i32 s72, s78, s30
	s_and_saveexec_b64 s[30:31], s[26:27]
	s_cbranch_execz .LBB0_298
	v_mbcnt_lo_u32_b32 v66, s28, 0
	v_mbcnt_hi_u32_b32 v66, s29, v66
	v_add_u32_e32 v66, s72, v66
	v_ashrrev_i32_e32 v67, 31, v66
	v_lshl_add_u64 v[66:67], v[66:67], 2, s[0:1]
	global_store_dword v[66:67], v141, off sc1
.LBB0_298:
	s_or_b64 exec, exec, s[30:31]
	s_bcnt1_i32_b64 s26, s[28:29]
	s_add_i32 s28, s72, s26
	s_and_saveexec_b64 s[26:27], s[22:23]
	s_cbranch_execz .LBB0_300
	v_mbcnt_lo_u32_b32 v66, s24, 0
	v_mbcnt_hi_u32_b32 v66, s25, v66
	v_add_u32_e32 v66, s28, v66
	v_ashrrev_i32_e32 v67, 31, v66
	v_lshl_add_u64 v[66:67], v[66:67], 2, s[0:1]
	global_store_dword v[66:67], v142, off sc1
.LBB0_300:
	s_or_b64 exec, exec, s[26:27]
	s_bcnt1_i32_b64 s22, s[24:25]
	s_add_i32 s24, s28, s22
	s_and_saveexec_b64 s[22:23], s[18:19]
	s_cbranch_execz .LBB0_302
	v_mbcnt_lo_u32_b32 v66, s20, 0
	v_mbcnt_hi_u32_b32 v66, s21, v66
	v_add_u32_e32 v66, s24, v66
	v_ashrrev_i32_e32 v67, 31, v66
	v_lshl_add_u64 v[66:67], v[66:67], 2, s[0:1]
	global_store_dword v[66:67], v143, off sc1
.LBB0_302:
	s_or_b64 exec, exec, s[22:23]
	s_bcnt1_i32_b64 s18, s[20:21]
	s_add_i32 s20, s24, s18
	s_and_saveexec_b64 s[18:19], s[16:17]
	s_cbranch_execz .LBB0_304
	v_mbcnt_lo_u32_b32 v66, s14, 0
	v_mbcnt_hi_u32_b32 v66, s15, v66
	v_add_u32_e32 v66, s20, v66
	v_ashrrev_i32_e32 v67, 31, v66
	v_lshl_add_u64 v[66:67], v[66:67], 2, s[0:1]
	global_store_dword v[66:67], v144, off sc1
.LBB0_304:
	s_or_b64 exec, exec, s[18:19]
	s_bcnt1_i32_b64 s14, s[14:15]
	s_add_i32 s16, s20, s14
	s_and_saveexec_b64 s[14:15], s[66:67]
	s_cbranch_execz .LBB0_306
	v_mbcnt_lo_u32_b32 v66, s12, 0
	v_mbcnt_hi_u32_b32 v66, s13, v66
	v_add_u32_e32 v66, s16, v66
	v_ashrrev_i32_e32 v67, 31, v66
	v_lshl_add_u64 v[66:67], v[66:67], 2, s[0:1]
	global_store_dword v[66:67], v145, off sc1
.LBB0_306:
	s_or_b64 exec, exec, s[14:15]
	s_bcnt1_i32_b64 s12, s[12:13]
	s_add_i32 s14, s16, s12
	s_and_saveexec_b64 s[12:13], s[10:11]
	s_cbranch_execz .LBB0_308
	v_mbcnt_lo_u32_b32 v66, s8, 0
	v_mbcnt_hi_u32_b32 v66, s9, v66
	v_add_u32_e32 v66, s14, v66
	v_ashrrev_i32_e32 v67, 31, v66
	v_lshl_add_u64 v[66:67], v[66:67], 2, s[0:1]
	global_store_dword v[66:67], v146, off sc1
.LBB0_308:
	s_or_b64 exec, exec, s[12:13]
	s_bcnt1_i32_b64 s8, s[8:9]
	s_add_i32 s10, s14, s8
	s_and_saveexec_b64 s[8:9], s[6:7]
	s_cbranch_execz .LBB0_310
	v_mbcnt_lo_u32_b32 v66, s4, 0
	v_mbcnt_hi_u32_b32 v66, s5, v66
	v_add_u32_e32 v66, s10, v66
	v_ashrrev_i32_e32 v67, 31, v66
	v_lshl_add_u64 v[66:67], v[66:67], 2, s[0:1]
	global_store_dword v[66:67], v147, off sc1

; __device__ __forceinline__ int mbcnt(unsigned long long m) { return __builtin_amdgcn_mbcnt_hi((unsigned)(m >> 32), __builtin_amdgcn_mbcnt_lo((unsigned)m, 0u)); }
; #define PIN8(m) asm volatile("" : "+s"(m[0]), "+s"(m[1]), "+s"(m[2]), "+s"(m[3]), "+s"(m[4]), "+s"(m[5]), "+s"(m[6]), "+s"(m[7]))
; __device__ __forceinline__ void select_query(const float* sc, int* sel, int ce, int lane) {
;     ...
;     int pos = 0;
; #pragma unroll
;     for (int g = 0; g < 8; ++g) if (8 * g < nreg) {
;         unsigned long long m[8];
; #pragma unroll
;         for (int j = 0; j < 8; ++j) m[j] = __ballot(key[8 * g + j] > thr);
;         PIN8(m);
; #pragma unroll
;         for (int j = 0; j < 8; ++j) { if (key[8 * g + j] > thr) sel[pos + mbcnt(m[j])] = lane + 64 * (8 * g + j); pos += __builtin_popcountll(m[j]); }
;         asm volatile("" : "+s"(pos));
;     }
.LBB0_312:
	v_cmp_gt_u32_e64 s[34:35], v56, v65
	v_cmp_gt_u32_e64 s[26:27], v60, v65
	v_cmp_gt_u32_e64 s[18:19], v24, v65
	v_cmp_gt_u32_e64 s[22:23], v25, v65
	v_cmp_gt_u32_e64 s[12:13], v26, v65
	v_cmp_gt_u32_e64 s[66:67], v27, v65
	v_cmp_gt_u32_e64 s[4:5], v28, v65
	v_cmp_gt_u32_e64 s[10:11], v29, v65
	s_mov_b64 s[16:17], s[66:67]
	s_mov_b64 s[8:9], s[10:11]
	s_mov_b64 s[28:29], s[26:27]
	s_mov_b64 s[20:21], s[18:19]
	s_mov_b64 s[14:15], s[12:13]
	s_mov_b64 s[30:31], s[34:35]
	s_mov_b64 s[6:7], s[4:5]
	s_mov_b64 s[24:25], s[22:23]
	s_and_saveexec_b64 vcc, s[34:35]
	s_cbranch_execz .LBB0_314
	v_mbcnt_lo_u32_b32 v66, s30, 0
	v_mbcnt_hi_u32_b32 v66, s31, v66
	v_add_u32_e32 v66, s78, v66
	v_ashrrev_i32_e32 v67, 31, v66
	v_lshl_add_u64 v[66:67], v[66:67], 2, s[0:1]
	global_store_dword v[66:67], v156, off sc1
.LBB0_314:
	s_or_b64 exec, exec, vcc
	s_bcnt1_i32_b64 s30, s[30:31]
	s_add_i32 s72, s78, s30
	s_and_saveexec_b64 s[30:31], s[26:27]
	s_cbranch_execz .LBB0_316
	v_mbcnt_lo_u32_b32 v66, s28, 0
	v_mbcnt_hi_u32_b32 v66, s29, v66
	v_add_u32_e32 v66, s72, v66
	v_ashrrev_i32_e32 v67, 31, v66
	v_lshl_add_u64 v[66:67], v[66:67], 2, s[0:1]
	global_store_dword v[66:67], v157, off sc1
.LBB0_316:
	s_or_b64 exec, exec, s[30:31]
	s_bcnt1_i32_b64 s26, s[28:29]
	s_add_i32 s28, s72, s26
	s_and_saveexec_b64 s[26:27], s[22:23]
	s_cbranch_execz .LBB0_318
	v_mbcnt_lo_u32_b32 v66, s24, 0
	v_mbcnt_hi_u32_b32 v66, s25, v66
	v_add_u32_e32 v66, s28, v66
	v_ashrrev_i32_e32 v67, 31, v66
	v_lshl_add_u64 v[66:67], v[66:67], 2, s[0:1]
	global_store_dword v[66:67], v158, off sc1
.LBB0_318:
	s_or_b64 exec, exec, s[26:27]
	s_bcnt1_i32_b64 s22, s[24:25]
	s_add_i32 s24, s28, s22
	s_and_saveexec_b64 s[22:23], s[18:19]
	s_cbranch_execz .LBB0_320
	v_mbcnt_lo_u32_b32 v66, s20, 0
	v_mbcnt_hi_u32_b32 v66, s21, v66
	v_add_u32_e32 v66, s24, v66
	v_ashrrev_i32_e32 v67, 31, v66
	v_lshl_add_u64 v[66:67], v[66:67], 2, s[0:1]
	global_store_dword v[66:67], v159, off sc1
.LBB0_320:
	s_or_b64 exec, exec, s[22:23]
	s_bcnt1_i32_b64 s18, s[20:21]
	s_add_i32 s20, s24, s18
	s_and_saveexec_b64 s[18:19], s[66:67]
	s_cbranch_execz .LBB0_322
	v_mbcnt_lo_u32_b32 v66, s16, 0
	v_mbcnt_hi_u32_b32 v66, s17, v66
	v_add_u32_e32 v66, s20, v66
	v_ashrrev_i32_e32 v67, 31, v66
	v_lshl_add_u64 v[66:67], v[66:67], 2, s[0:1]
	global_store_dword v[66:67], v160, off sc1
.LBB0_322:
	s_or_b64 exec, exec, s[18:19]
	s_bcnt1_i32_b64 s16, s[16:17]
	s_add_i32 s18, s20, s16
	s_and_saveexec_b64 s[16:17], s[12:13]
	s_cbranch_execz .LBB0_324
	v_mbcnt_lo_u32_b32 v66, s14, 0
	v_mbcnt_hi_u32_b32 v66, s15, v66
	v_add_u32_e32 v66, s18, v66
	v_ashrrev_i32_e32 v67, 31, v66
	v_lshl_add_u64 v[66:67], v[66:67], 2, s[0:1]
	global_store_dword v[66:67], v161, off sc1
.LBB0_324:
	s_or_b64 exec, exec, s[16:17]
	s_bcnt1_i32_b64 s12, s[14:15]
	s_add_i32 s14, s18, s12
	s_and_saveexec_b64 s[12:13], s[10:11]
	s_cbranch_execz .LBB0_326
	v_mbcnt_lo_u32_b32 v66, s8, 0
	v_mbcnt_hi_u32_b32 v66, s9, v66
	v_add_u32_e32 v66, s14, v66
	v_ashrrev_i32_e32 v67, 31, v66
	v_lshl_add_u64 v[66:67], v[66:67], 2, s[0:1]
	global_store_dword v[66:67], v162, off sc1
.LBB0_326:
	s_or_b64 exec, exec, s[12:13]
	s_bcnt1_i32_b64 s8, s[8:9]
	s_add_i32 s10, s14, s8
	s_and_saveexec_b64 s[8:9], s[4:5]
	s_cbranch_execz .LBB0_328
	v_mbcnt_lo_u32_b32 v66, s6, 0
	v_mbcnt_hi_u32_b32 v66, s7, v66
	v_add_u32_e32 v66, s10, v66
	v_ashrrev_i32_e32 v67, 31, v66
	v_lshl_add_u64 v[66:67], v[66:67], 2, s[0:1]
	global_store_dword v[66:67], v163, off sc1

; __device__ __forceinline__ int mbcnt(unsigned long long m) { return __builtin_amdgcn_mbcnt_hi((unsigned)(m >> 32), __builtin_amdgcn_mbcnt_lo((unsigned)m, 0u)); }
; #define PIN8(m) asm volatile("" : "+s"(m[0]), "+s"(m[1]), "+s"(m[2]), "+s"(m[3]), "+s"(m[4]), "+s"(m[5]), "+s"(m[6]), "+s"(m[7]))
; __device__ __forceinline__ void select_query(const float* sc, int* sel, int ce, int lane) {
;     ...
;     int pos = 0;
; #pragma unroll
;     for (int g = 0; g < 8; ++g) if (8 * g < nreg) {
;         unsigned long long m[8];
; #pragma unroll
;         for (int j = 0; j < 8; ++j) m[j] = __ballot(key[8 * g + j] > thr);
;         PIN8(m);
; #pragma unroll
;         for (int j = 0; j < 8; ++j) { if (key[8 * g + j] > thr) sel[pos + mbcnt(m[j])] = lane + 64 * (8 * g + j); pos += __builtin_popcountll(m[j]); }
;         asm volatile("" : "+s"(pos));
;     }
.LBB0_330:
	v_cmp_gt_u32_e64 s[34:35], v52, v65
	v_cmp_gt_u32_e64 s[26:27], v55, v65
	v_cmp_gt_u32_e64 s[20:21], v12, v65
	v_cmp_gt_u32_e64 s[22:23], v13, v65
	v_cmp_gt_u32_e64 s[66:67], v14, v65
	v_cmp_gt_u32_e64 s[14:15], v15, v65
	v_cmp_gt_u32_e64 s[6:7], v16, v65
	v_cmp_gt_u32_e64 s[10:11], v17, v65
	s_mov_b64 s[18:19], s[20:21]
	s_mov_b64 s[12:13], s[66:67]
	s_mov_b64 s[30:31], s[34:35]
	s_mov_b64 s[4:5], s[6:7]
	s_mov_b64 s[24:25], s[22:23]
	s_mov_b64 s[16:17], s[14:15]
	s_mov_b64 s[8:9], s[10:11]
	s_mov_b64 s[28:29], s[26:27]
	s_and_saveexec_b64 vcc, s[34:35]
	s_cbranch_execz .LBB0_332
	v_mbcnt_lo_u32_b32 v66, s30, 0
	v_mbcnt_hi_u32_b32 v66, s31, v66
	v_add_u32_e32 v66, s78, v66
	v_ashrrev_i32_e32 v67, 31, v66
	v_lshl_add_u64 v[66:67], v[66:67], 2, s[0:1]
	global_store_dword v[66:67], v172, off sc1
.LBB0_332:
	s_or_b64 exec, exec, vcc
	s_bcnt1_i32_b64 s30, s[30:31]
	s_add_i32 s72, s78, s30
	s_and_saveexec_b64 s[30:31], s[26:27]
	s_cbranch_execz .LBB0_334
	v_mbcnt_lo_u32_b32 v66, s28, 0
	v_mbcnt_hi_u32_b32 v66, s29, v66
	v_add_u32_e32 v66, s72, v66
	v_ashrrev_i32_e32 v67, 31, v66
	v_lshl_add_u64 v[66:67], v[66:67], 2, s[0:1]
	global_store_dword v[66:67], v173, off sc1
.LBB0_334:
	s_or_b64 exec, exec, s[30:31]
	s_bcnt1_i32_b64 s26, s[28:29]
	s_add_i32 s28, s72, s26
	s_and_saveexec_b64 s[26:27], s[22:23]
	s_cbranch_execz .LBB0_336
	v_mbcnt_lo_u32_b32 v66, s24, 0
	v_mbcnt_hi_u32_b32 v66, s25, v66
	v_add_u32_e32 v66, s28, v66
	v_ashrrev_i32_e32 v67, 31, v66
	v_lshl_add_u64 v[66:67], v[66:67], 2, s[0:1]
	global_store_dword v[66:67], v174, off sc1
.LBB0_336:
	s_or_b64 exec, exec, s[26:27]
	s_bcnt1_i32_b64 s22, s[24:25]
	s_add_i32 s24, s28, s22
	s_and_saveexec_b64 s[22:23], s[20:21]
	s_cbranch_execz .LBB0_338
	v_mbcnt_lo_u32_b32 v66, s18, 0
	v_mbcnt_hi_u32_b32 v66, s19, v66
	v_add_u32_e32 v66, s24, v66
	v_ashrrev_i32_e32 v67, 31, v66
	v_lshl_add_u64 v[66:67], v[66:67], 2, s[0:1]
	global_store_dword v[66:67], v175, off sc1
.LBB0_338:
	s_or_b64 exec, exec, s[22:23]
	s_bcnt1_i32_b64 s18, s[18:19]
	s_add_i32 s20, s24, s18
	s_and_saveexec_b64 s[18:19], s[14:15]
	s_cbranch_execz .LBB0_340
	v_mbcnt_lo_u32_b32 v66, s16, 0
	v_mbcnt_hi_u32_b32 v66, s17, v66
	v_add_u32_e32 v66, s20, v66
	v_ashrrev_i32_e32 v67, 31, v66
	v_lshl_add_u64 v[66:67], v[66:67], 2, s[0:1]
	global_store_dword v[66:67], v176, off sc1
.LBB0_340:
	s_or_b64 exec, exec, s[18:19]
	s_bcnt1_i32_b64 s14, s[16:17]
	s_add_i32 s16, s20, s14
	s_and_saveexec_b64 s[14:15], s[66:67]
	s_cbranch_execz .LBB0_342
	v_mbcnt_lo_u32_b32 v66, s12, 0
	v_mbcnt_hi_u32_b32 v66, s13, v66
	v_add_u32_e32 v66, s16, v66
	v_ashrrev_i32_e32 v67, 31, v66
	v_lshl_add_u64 v[66:67], v[66:67], 2, s[0:1]
	global_store_dword v[66:67], v177, off sc1
.LBB0_342:
	s_or_b64 exec, exec, s[14:15]
	s_bcnt1_i32_b64 s12, s[12:13]
	s_add_i32 s14, s16, s12
	s_and_saveexec_b64 s[12:13], s[10:11]
	s_cbranch_execz .LBB0_344
	v_mbcnt_lo_u32_b32 v66, s8, 0
	v_mbcnt_hi_u32_b32 v66, s9, v66
	v_add_u32_e32 v66, s14, v66
	v_ashrrev_i32_e32 v67, 31, v66
	v_lshl_add_u64 v[66:67], v[66:67], 2, s[0:1]
	global_store_dword v[66:67], v178, off sc1
.LBB0_344:
	s_or_b64 exec, exec, s[12:13]
	s_bcnt1_i32_b64 s8, s[8:9]
	s_add_i32 s10, s14, s8
	s_and_saveexec_b64 s[8:9], s[6:7]
	s_cbranch_execz .LBB0_346
	v_mbcnt_lo_u32_b32 v66, s4, 0
	v_mbcnt_hi_u32_b32 v66, s5, v66
	v_add_u32_e32 v66, s10, v66
	v_ashrrev_i32_e32 v67, 31, v66
	v_lshl_add_u64 v[66:67], v[66:67], 2, s[0:1]
	global_store_dword v[66:67], v179, off sc1

; __device__ __forceinline__ int mbcnt(unsigned long long m) { return __builtin_amdgcn_mbcnt_hi((unsigned)(m >> 32), __builtin_amdgcn_mbcnt_lo((unsigned)m, 0u)); }
; #define PIN8(m) asm volatile("" : "+s"(m[0]), "+s"(m[1]), "+s"(m[2]), "+s"(m[3]), "+s"(m[4]), "+s"(m[5]), "+s"(m[6]), "+s"(m[7]))
; __device__ __forceinline__ void select_query(const float* sc, int* sel, int ce, int lane) {
;     ...
;     int pos = 0;
; #pragma unroll
;     for (int g = 0; g < 8; ++g) if (8 * g < nreg) {
;         unsigned long long m[8];
; #pragma unroll
;         for (int j = 0; j < 8; ++j) m[j] = __ballot(key[8 * g + j] > thr);
;         PIN8(m);
; #pragma unroll
;         for (int j = 0; j < 8; ++j) { if (key[8 * g + j] > thr) sel[pos + mbcnt(m[j])] = lane + 64 * (8 * g + j); pos += __builtin_popcountll(m[j]); }
;         asm volatile("" : "+s"(pos));
;     }
.LBB0_348:
	v_cmp_gt_u32_e64 s[34:35], v49, v65
	v_cmp_gt_u32_e64 s[26:27], v51, v65
	v_cmp_gt_u32_e64 s[18:19], v4, v65
	v_cmp_gt_u32_e64 s[24:25], v5, v65
	v_cmp_gt_u32_e64 s[12:13], v2, v65
	v_cmp_gt_u32_e64 s[66:67], v3, v65
	v_cmp_gt_u32_e64 s[6:7], v0, v65
	v_cmp_gt_u32_e64 s[10:11], v1, v65
	s_mov_b64 s[4:5], s[6:7]
	s_mov_b64 s[22:23], s[24:25]
	s_mov_b64 s[16:17], s[66:67]
	s_mov_b64 s[8:9], s[10:11]
	s_mov_b64 s[28:29], s[26:27]
	s_mov_b64 s[20:21], s[18:19]
	s_mov_b64 s[14:15], s[12:13]
	s_mov_b64 s[30:31], s[34:35]
	s_and_saveexec_b64 vcc, s[34:35]
	s_cbranch_execz .LBB0_350
	v_mbcnt_lo_u32_b32 v65, s30, 0
	v_mbcnt_hi_u32_b32 v65, s31, v65
	v_add_u32_e32 v66, s78, v65
	v_ashrrev_i32_e32 v67, 31, v66
	v_lshl_add_u64 v[66:67], v[66:67], 2, s[0:1]
	global_store_dword v[66:67], v196, off sc1
.LBB0_350:
	s_or_b64 exec, exec, vcc
	s_bcnt1_i32_b64 s30, s[30:31]
	s_add_i32 s72, s78, s30
	s_and_saveexec_b64 s[30:31], s[26:27]
	s_cbranch_execz .LBB0_352
	v_mbcnt_lo_u32_b32 v65, s28, 0
	v_mbcnt_hi_u32_b32 v65, s29, v65
	v_add_u32_e32 v66, s72, v65
	v_ashrrev_i32_e32 v67, 31, v66
	v_lshl_add_u64 v[66:67], v[66:67], 2, s[0:1]
	global_store_dword v[66:67], v197, off sc1
.LBB0_352:
	s_or_b64 exec, exec, s[30:31]
	s_bcnt1_i32_b64 s26, s[28:29]
	s_add_i32 s28, s72, s26
	s_and_saveexec_b64 s[26:27], s[24:25]
	s_cbranch_execz .LBB0_354
	v_mbcnt_lo_u32_b32 v65, s22, 0
	v_mbcnt_hi_u32_b32 v65, s23, v65
	v_add_u32_e32 v66, s28, v65
	v_ashrrev_i32_e32 v67, 31, v66
	v_lshl_add_u64 v[66:67], v[66:67], 2, s[0:1]
	global_store_dword v[66:67], v198, off sc1
.LBB0_354:
	s_or_b64 exec, exec, s[26:27]
	s_bcnt1_i32_b64 s22, s[22:23]
	s_add_i32 s24, s28, s22
	s_and_saveexec_b64 s[22:23], s[18:19]
	s_cbranch_execz .LBB0_356
	v_mbcnt_lo_u32_b32 v65, s20, 0
	v_mbcnt_hi_u32_b32 v65, s21, v65
	v_add_u32_e32 v66, s24, v65
	v_ashrrev_i32_e32 v67, 31, v66
	v_lshl_add_u64 v[66:67], v[66:67], 2, s[0:1]
	global_store_dword v[66:67], v199, off sc1
.LBB0_356:
	s_or_b64 exec, exec, s[22:23]
	s_bcnt1_i32_b64 s18, s[20:21]
	s_add_i32 s20, s24, s18
	s_and_saveexec_b64 s[18:19], s[66:67]
	s_cbranch_execz .LBB0_358
	v_mbcnt_lo_u32_b32 v65, s16, 0
	v_mbcnt_hi_u32_b32 v65, s17, v65
	v_add_u32_e32 v66, s20, v65
	v_ashrrev_i32_e32 v67, 31, v66
	v_lshl_add_u64 v[66:67], v[66:67], 2, s[0:1]
	global_store_dword v[66:67], v200, off sc1
.LBB0_358:
	s_or_b64 exec, exec, s[18:19]
	s_bcnt1_i32_b64 s16, s[16:17]
	s_add_i32 s18, s20, s16
	s_and_saveexec_b64 s[16:17], s[12:13]
	s_cbranch_execz .LBB0_360
	v_mbcnt_lo_u32_b32 v65, s14, 0
	v_mbcnt_hi_u32_b32 v65, s15, v65
	v_add_u32_e32 v66, s18, v65
	v_ashrrev_i32_e32 v67, 31, v66
	v_lshl_add_u64 v[66:67], v[66:67], 2, s[0:1]
	global_store_dword v[66:67], v201, off sc1
.LBB0_360:
	s_or_b64 exec, exec, s[16:17]
	s_bcnt1_i32_b64 s12, s[14:15]
	s_add_i32 s14, s18, s12
	s_and_saveexec_b64 s[12:13], s[10:11]
	s_cbranch_execz .LBB0_362
	v_mbcnt_lo_u32_b32 v65, s8, 0
	v_mbcnt_hi_u32_b32 v65, s9, v65
	v_add_u32_e32 v66, s14, v65
	v_ashrrev_i32_e32 v67, 31, v66
	v_lshl_add_u64 v[66:67], v[66:67], 2, s[0:1]
	global_store_dword v[66:67], v202, off sc1
.LBB0_362:
	s_or_b64 exec, exec, s[12:13]
	s_bcnt1_i32_b64 s8, s[8:9]
	s_add_i32 s10, s14, s8
	s_and_saveexec_b64 s[8:9], s[6:7]
	s_cbranch_execz .LBB0_364
	v_mbcnt_lo_u32_b32 v65, s4, 0
	v_mbcnt_hi_u32_b32 v65, s5, v65
	v_add_u32_e32 v66, s10, v65
	v_ashrrev_i32_e32 v67, 31, v66
	v_lshl_add_u64 v[66:67], v[66:67], 2, s[0:1]
	global_store_dword v[66:67], v203, off sc1

; __device__ __forceinline__ int mbcnt(unsigned long long m) { return __builtin_amdgcn_mbcnt_hi((unsigned)(m >> 32), __builtin_amdgcn_mbcnt_lo((unsigned)m, 0u)); }
; #define PIN8(m) asm volatile("" : "+s"(m[0]), "+s"(m[1]), "+s"(m[2]), "+s"(m[3]), "+s"(m[4]), "+s"(m[5]), "+s"(m[6]), "+s"(m[7]))
; __device__ __forceinline__ void select_query(const float* sc, int* sel, int ce, int lane) {
;     ...
;     int pos = 0;
; #pragma unroll
;     for (int g = 0; g < 8; ++g) if (8 * g < nreg) {
;         unsigned long long m[8];
; #pragma unroll
;         for (int j = 0; j < 8; ++j) m[j] = __ballot(key[8 * g + j] > thr);
;         PIN8(m);
; #pragma unroll
;         for (int j = 0; j < 8; ++j) { if (key[8 * g + j] > thr) sel[pos + mbcnt(m[j])] = lane + 64 * (8 * g + j); pos += __builtin_popcountll(m[j]); }
;         asm volatile("" : "+s"(pos));
;     }
.LBB0_366:
	v_cmp_gt_u32_e64 s[34:35], v58, v65
	v_cmp_gt_u32_e64 s[28:29], v62, v65
	v_cmp_gt_u32_e64 s[20:21], v34, v65
	v_cmp_gt_u32_e64 s[22:23], v35, v65
	v_cmp_gt_u32_e64 s[66:67], v36, v65
	v_cmp_gt_u32_e64 s[14:15], v37, v65
	v_cmp_gt_u32_e64 s[6:7], v38, v65
	v_cmp_gt_u32_e64 s[8:9], v39, v65
	s_mov_b64 s[26:27], s[28:29]
	s_mov_b64 s[18:19], s[20:21]
	s_mov_b64 s[12:13], s[66:67]
	s_mov_b64 s[30:31], s[34:35]
	s_mov_b64 s[4:5], s[6:7]
	s_mov_b64 s[24:25], s[22:23]
	s_mov_b64 s[16:17], s[14:15]
	s_mov_b64 s[10:11], s[8:9]
	s_and_saveexec_b64 vcc, s[34:35]
	s_cbranch_execz .LBB0_368
	v_mbcnt_lo_u32_b32 v66, s30, 0
	v_mbcnt_hi_u32_b32 v66, s31, v66
	v_add_u32_e32 v66, s78, v66
	v_ashrrev_i32_e32 v67, 31, v66
	v_lshl_add_u64 v[66:67], v[66:67], 2, s[0:1]
	global_store_dword v[66:67], v148, off sc1
.LBB0_368:
	s_or_b64 exec, exec, vcc
	s_bcnt1_i32_b64 s30, s[30:31]
	s_add_i32 s72, s78, s30
	s_and_saveexec_b64 s[30:31], s[28:29]
	s_cbranch_execz .LBB0_370
	v_mbcnt_lo_u32_b32 v66, s26, 0
	v_mbcnt_hi_u32_b32 v66, s27, v66
	v_add_u32_e32 v66, s72, v66
	v_ashrrev_i32_e32 v67, 31, v66
	v_lshl_add_u64 v[66:67], v[66:67], 2, s[0:1]
	global_store_dword v[66:67], v149, off sc1
.LBB0_370:
	s_or_b64 exec, exec, s[30:31]
	s_bcnt1_i32_b64 s26, s[26:27]
	s_add_i32 s28, s72, s26
	s_and_saveexec_b64 s[26:27], s[22:23]
	s_cbranch_execz .LBB0_372
	v_mbcnt_lo_u32_b32 v66, s24, 0
	v_mbcnt_hi_u32_b32 v66, s25, v66
	v_add_u32_e32 v66, s28, v66
	v_ashrrev_i32_e32 v67, 31, v66
	v_lshl_add_u64 v[66:67], v[66:67], 2, s[0:1]
	global_store_dword v[66:67], v150, off sc1
.LBB0_372:
	s_or_b64 exec, exec, s[26:27]
	s_bcnt1_i32_b64 s22, s[24:25]
	s_add_i32 s24, s28, s22
	s_and_saveexec_b64 s[22:23], s[20:21]
	s_cbranch_execz .LBB0_374
	v_mbcnt_lo_u32_b32 v66, s18, 0
	v_mbcnt_hi_u32_b32 v66, s19, v66
	v_add_u32_e32 v66, s24, v66
	v_ashrrev_i32_e32 v67, 31, v66
	v_lshl_add_u64 v[66:67], v[66:67], 2, s[0:1]
	global_store_dword v[66:67], v151, off sc1
.LBB0_374:
	s_or_b64 exec, exec, s[22:23]
	s_bcnt1_i32_b64 s18, s[18:19]
	s_add_i32 s20, s24, s18
	s_and_saveexec_b64 s[18:19], s[14:15]
	s_cbranch_execz .LBB0_376
	v_mbcnt_lo_u32_b32 v66, s16, 0
	v_mbcnt_hi_u32_b32 v66, s17, v66
	v_add_u32_e32 v66, s20, v66
	v_ashrrev_i32_e32 v67, 31, v66
	v_lshl_add_u64 v[66:67], v[66:67], 2, s[0:1]
	global_store_dword v[66:67], v152, off sc1
.LBB0_376:
	s_or_b64 exec, exec, s[18:19]
	s_bcnt1_i32_b64 s14, s[16:17]
	s_add_i32 s16, s20, s14
	s_and_saveexec_b64 s[14:15], s[66:67]
	s_cbranch_execz .LBB0_378
	v_mbcnt_lo_u32_b32 v66, s12, 0
	v_mbcnt_hi_u32_b32 v66, s13, v66
	v_add_u32_e32 v66, s16, v66
	v_ashrrev_i32_e32 v67, 31, v66
	v_lshl_add_u64 v[66:67], v[66:67], 2, s[0:1]
	global_store_dword v[66:67], v153, off sc1
.LBB0_378:
	s_or_b64 exec, exec, s[14:15]
	s_bcnt1_i32_b64 s12, s[12:13]
	s_add_i32 s14, s16, s12
	s_and_saveexec_b64 s[12:13], s[8:9]
	s_cbranch_execz .LBB0_380
	v_mbcnt_lo_u32_b32 v66, s10, 0
	v_mbcnt_hi_u32_b32 v66, s11, v66
	v_add_u32_e32 v66, s14, v66
	v_ashrrev_i32_e32 v67, 31, v66
	v_lshl_add_u64 v[66:67], v[66:67], 2, s[0:1]
	global_store_dword v[66:67], v154, off sc1
.LBB0_380:
	s_or_b64 exec, exec, s[12:13]
	s_bcnt1_i32_b64 s8, s[10:11]
	s_add_i32 s10, s14, s8
	s_and_saveexec_b64 s[8:9], s[6:7]
	s_cbranch_execz .LBB0_382
	v_mbcnt_lo_u32_b32 v66, s4, 0
	v_mbcnt_hi_u32_b32 v66, s5, v66
	v_add_u32_e32 v66, s10, v66
	v_ashrrev_i32_e32 v67, 31, v66
	v_lshl_add_u64 v[66:67], v[66:67], 2, s[0:1]
	global_store_dword v[66:67], v155, off sc1

; __device__ __forceinline__ int mbcnt(unsigned long long m) { return __builtin_amdgcn_mbcnt_hi((unsigned)(m >> 32), __builtin_amdgcn_mbcnt_lo((unsigned)m, 0u)); }
; #define PIN8(m) asm volatile("" : "+s"(m[0]), "+s"(m[1]), "+s"(m[2]), "+s"(m[3]), "+s"(m[4]), "+s"(m[5]), "+s"(m[6]), "+s"(m[7]))
; __device__ __forceinline__ void select_query(const float* sc, int* sel, int ce, int lane) {
;     ...
;     int pos = 0;
; #pragma unroll
;     for (int g = 0; g < 8; ++g) if (8 * g < nreg) {
;         unsigned long long m[8];
; #pragma unroll
;         for (int j = 0; j < 8; ++j) m[j] = __ballot(key[8 * g + j] > thr);
;         PIN8(m);
; #pragma unroll
;         for (int j = 0; j < 8; ++j) { if (key[8 * g + j] > thr) sel[pos + mbcnt(m[j])] = lane + 64 * (8 * g + j); pos += __builtin_popcountll(m[j]); }
;         asm volatile("" : "+s"(pos));
;     }
.LBB0_384:
	v_cmp_gt_u32_e64 s[34:35], v54, v65
	v_cmp_gt_u32_e64 s[26:27], v57, v65
	v_cmp_gt_u32_e64 s[18:19], v18, v65
	v_cmp_gt_u32_e64 s[24:25], v19, v65
	v_cmp_gt_u32_e64 s[12:13], v20, v65
	v_cmp_gt_u32_e64 s[66:67], v21, v65
	v_cmp_gt_u32_e64 s[6:7], v22, v65
	v_cmp_gt_u32_e64 s[10:11], v23, v65
	s_mov_b64 s[30:31], s[34:35]
	s_mov_b64 s[4:5], s[6:7]
	s_mov_b64 s[22:23], s[24:25]
	s_mov_b64 s[16:17], s[66:67]
	s_mov_b64 s[8:9], s[10:11]
	s_mov_b64 s[28:29], s[26:27]
	s_mov_b64 s[20:21], s[18:19]
	s_mov_b64 s[14:15], s[12:13]
	s_and_saveexec_b64 vcc, s[34:35]
	s_cbranch_execz .LBB0_386
	v_mbcnt_lo_u32_b32 v66, s30, 0
	v_mbcnt_hi_u32_b32 v66, s31, v66
	v_add_u32_e32 v66, s78, v66
	v_ashrrev_i32_e32 v67, 31, v66
	v_lshl_add_u64 v[66:67], v[66:67], 2, s[0:1]
	global_store_dword v[66:67], v164, off sc1
.LBB0_386:
	s_or_b64 exec, exec, vcc
	s_bcnt1_i32_b64 s30, s[30:31]
	s_add_i32 s72, s78, s30
	s_and_saveexec_b64 s[30:31], s[26:27]
	s_cbranch_execz .LBB0_388
	v_mbcnt_lo_u32_b32 v66, s28, 0
	v_mbcnt_hi_u32_b32 v66, s29, v66
	v_add_u32_e32 v66, s72, v66
	v_ashrrev_i32_e32 v67, 31, v66
	v_lshl_add_u64 v[66:67], v[66:67], 2, s[0:1]
	global_store_dword v[66:67], v165, off sc1
.LBB0_388:
	s_or_b64 exec, exec, s[30:31]
	s_bcnt1_i32_b64 s26, s[28:29]
	s_add_i32 s28, s72, s26
	s_and_saveexec_b64 s[26:27], s[24:25]
	s_cbranch_execz .LBB0_390
	v_mbcnt_lo_u32_b32 v66, s22, 0
	v_mbcnt_hi_u32_b32 v66, s23, v66
	v_add_u32_e32 v66, s28, v66
	v_ashrrev_i32_e32 v67, 31, v66
	v_lshl_add_u64 v[66:67], v[66:67], 2, s[0:1]
	global_store_dword v[66:67], v166, off sc1
.LBB0_390:
	s_or_b64 exec, exec, s[26:27]
	s_bcnt1_i32_b64 s22, s[22:23]
	s_add_i32 s24, s28, s22
	s_and_saveexec_b64 s[22:23], s[18:19]
	s_cbranch_execz .LBB0_392
	v_mbcnt_lo_u32_b32 v66, s20, 0
	v_mbcnt_hi_u32_b32 v66, s21, v66
	v_add_u32_e32 v66, s24, v66
	v_ashrrev_i32_e32 v67, 31, v66
	v_lshl_add_u64 v[66:67], v[66:67], 2, s[0:1]
	global_store_dword v[66:67], v167, off sc1
.LBB0_392:
	s_or_b64 exec, exec, s[22:23]
	s_bcnt1_i32_b64 s18, s[20:21]
	s_add_i32 s20, s24, s18
	s_and_saveexec_b64 s[18:19], s[66:67]
	s_cbranch_execz .LBB0_394
	v_mbcnt_lo_u32_b32 v66, s16, 0
	v_mbcnt_hi_u32_b32 v66, s17, v66
	v_add_u32_e32 v66, s20, v66
	v_ashrrev_i32_e32 v67, 31, v66
	v_lshl_add_u64 v[66:67], v[66:67], 2, s[0:1]
	global_store_dword v[66:67], v168, off sc1
.LBB0_394:
	s_or_b64 exec, exec, s[18:19]
	s_bcnt1_i32_b64 s16, s[16:17]
	s_add_i32 s18, s20, s16
	s_and_saveexec_b64 s[16:17], s[12:13]
	s_cbranch_execz .LBB0_396
	v_mbcnt_lo_u32_b32 v66, s14, 0
	v_mbcnt_hi_u32_b32 v66, s15, v66
	v_add_u32_e32 v66, s18, v66
	v_ashrrev_i32_e32 v67, 31, v66
	v_lshl_add_u64 v[66:67], v[66:67], 2, s[0:1]
	global_store_dword v[66:67], v169, off sc1
.LBB0_396:
	s_or_b64 exec, exec, s[16:17]
	s_bcnt1_i32_b64 s12, s[14:15]
	s_add_i32 s14, s18, s12
	s_and_saveexec_b64 s[12:13], s[10:11]
	s_cbranch_execz .LBB0_398
	v_mbcnt_lo_u32_b32 v66, s8, 0
	v_mbcnt_hi_u32_b32 v66, s9, v66
	v_add_u32_e32 v66, s14, v66
	v_ashrrev_i32_e32 v67, 31, v66
	v_lshl_add_u64 v[66:67], v[66:67], 2, s[0:1]
	global_store_dword v[66:67], v170, off sc1
.LBB0_398:
	s_or_b64 exec, exec, s[12:13]
	s_bcnt1_i32_b64 s8, s[8:9]
	s_add_i32 s10, s14, s8
	s_and_saveexec_b64 s[8:9], s[6:7]
	s_cbranch_execz .LBB0_400
	v_mbcnt_lo_u32_b32 v66, s4, 0
	v_mbcnt_hi_u32_b32 v66, s5, v66
	v_add_u32_e32 v66, s10, v66
	v_ashrrev_i32_e32 v67, 31, v66
	v_lshl_add_u64 v[66:67], v[66:67], 2, s[0:1]
	global_store_dword v[66:67], v171, off sc1

; __device__ __forceinline__ int mbcnt(unsigned long long m) { return __builtin_amdgcn_mbcnt_hi((unsigned)(m >> 32), __builtin_amdgcn_mbcnt_lo((unsigned)m, 0u)); }
; #define PIN8(m) asm volatile("" : "+s"(m[0]), "+s"(m[1]), "+s"(m[2]), "+s"(m[3]), "+s"(m[4]), "+s"(m[5]), "+s"(m[6]), "+s"(m[7]))
; __device__ __forceinline__ void select_query(const float* sc, int* sel, int ce, int lane) {
;     ...
;     int pos = 0;
; #pragma unroll
;     for (int g = 0; g < 8; ++g) if (8 * g < nreg) {
;         unsigned long long m[8];
; #pragma unroll
;         for (int j = 0; j < 8; ++j) m[j] = __ballot(key[8 * g + j] > thr);
;         PIN8(m);
; #pragma unroll
;         for (int j = 0; j < 8; ++j) { if (key[8 * g + j] > thr) sel[pos + mbcnt(m[j])] = lane + 64 * (8 * g + j); pos += __builtin_popcountll(m[j]); }
;         asm volatile("" : "+s"(pos));
;     }
.LBB0_402:
	v_cmp_gt_u32_e64 s[34:35], v50, v65
	v_cmp_gt_u32_e64 s[26:27], v53, v65
	v_cmp_gt_u32_e64 s[18:19], v6, v65
	v_cmp_gt_u32_e64 s[22:23], v7, v65
	v_cmp_gt_u32_e64 s[66:67], v8, v65
	v_cmp_gt_u32_e64 s[14:15], v9, v65
	v_cmp_gt_u32_e64 s[6:7], v10, v65
	v_cmp_gt_u32_e64 s[10:11], v11, v65
	s_mov_b64 s[8:9], s[10:11]
	s_mov_b64 s[28:29], s[26:27]
	s_mov_b64 s[20:21], s[18:19]
	s_mov_b64 s[12:13], s[66:67]
	s_mov_b64 s[30:31], s[34:35]
	s_mov_b64 s[4:5], s[6:7]
	s_mov_b64 s[24:25], s[22:23]
	s_mov_b64 s[16:17], s[14:15]
	s_and_saveexec_b64 vcc, s[34:35]
	s_cbranch_execz .LBB0_404
	v_mbcnt_lo_u32_b32 v66, s30, 0
	v_mbcnt_hi_u32_b32 v66, s31, v66
	v_add_u32_e32 v66, s78, v66
	v_ashrrev_i32_e32 v67, 31, v66
	v_lshl_add_u64 v[66:67], v[66:67], 2, s[0:1]
	global_store_dword v[66:67], v180, off sc1
.LBB0_404:
	s_or_b64 exec, exec, vcc
	s_bcnt1_i32_b64 s30, s[30:31]
	s_add_i32 s72, s78, s30
	s_and_saveexec_b64 s[30:31], s[26:27]
	s_cbranch_execz .LBB0_406
	v_mbcnt_lo_u32_b32 v66, s28, 0
	v_mbcnt_hi_u32_b32 v66, s29, v66
	v_add_u32_e32 v66, s72, v66
	v_ashrrev_i32_e32 v67, 31, v66
	v_lshl_add_u64 v[66:67], v[66:67], 2, s[0:1]
	global_store_dword v[66:67], v181, off sc1
.LBB0_406:
	s_or_b64 exec, exec, s[30:31]
	s_bcnt1_i32_b64 s26, s[28:29]
	s_add_i32 s28, s72, s26
	s_and_saveexec_b64 s[26:27], s[22:23]
	s_cbranch_execz .LBB0_408
	v_mbcnt_lo_u32_b32 v66, s24, 0
	v_mbcnt_hi_u32_b32 v66, s25, v66
	v_add_u32_e32 v66, s28, v66
	v_ashrrev_i32_e32 v67, 31, v66
	v_lshl_add_u64 v[66:67], v[66:67], 2, s[0:1]
	global_store_dword v[66:67], v190, off sc1
.LBB0_408:
	s_or_b64 exec, exec, s[26:27]
	s_bcnt1_i32_b64 s22, s[24:25]
	s_add_i32 s24, s28, s22
	s_and_saveexec_b64 s[22:23], s[18:19]
	s_cbranch_execz .LBB0_410
	v_mbcnt_lo_u32_b32 v66, s20, 0
	v_mbcnt_hi_u32_b32 v66, s21, v66
	v_add_u32_e32 v66, s24, v66
	v_ashrrev_i32_e32 v67, 31, v66
	v_lshl_add_u64 v[66:67], v[66:67], 2, s[0:1]
	global_store_dword v[66:67], v191, off sc1
.LBB0_410:
	s_or_b64 exec, exec, s[22:23]
	s_bcnt1_i32_b64 s18, s[20:21]
	s_add_i32 s20, s24, s18
	s_and_saveexec_b64 s[18:19], s[14:15]
	s_cbranch_execz .LBB0_412
	v_mbcnt_lo_u32_b32 v66, s16, 0
	v_mbcnt_hi_u32_b32 v66, s17, v66
	v_add_u32_e32 v66, s20, v66
	v_ashrrev_i32_e32 v67, 31, v66
	v_lshl_add_u64 v[66:67], v[66:67], 2, s[0:1]
	global_store_dword v[66:67], v192, off sc1
.LBB0_412:
	s_or_b64 exec, exec, s[18:19]
	s_bcnt1_i32_b64 s14, s[16:17]
	s_add_i32 s16, s20, s14
	s_and_saveexec_b64 s[14:15], s[66:67]
	s_cbranch_execz .LBB0_414
	v_mbcnt_lo_u32_b32 v66, s12, 0
	v_mbcnt_hi_u32_b32 v66, s13, v66
	v_add_u32_e32 v66, s16, v66
	v_ashrrev_i32_e32 v67, 31, v66
	v_lshl_add_u64 v[66:67], v[66:67], 2, s[0:1]
	global_store_dword v[66:67], v193, off sc1
.LBB0_414:
	s_or_b64 exec, exec, s[14:15]
	s_bcnt1_i32_b64 s12, s[12:13]
	s_add_i32 s14, s16, s12
	s_and_saveexec_b64 s[12:13], s[10:11]
	s_cbranch_execz .LBB0_416
	v_mbcnt_lo_u32_b32 v66, s8, 0
	v_mbcnt_hi_u32_b32 v66, s9, v66
	v_add_u32_e32 v66, s14, v66
	v_ashrrev_i32_e32 v67, 31, v66
	v_lshl_add_u64 v[66:67], v[66:67], 2, s[0:1]
	global_store_dword v[66:67], v194, off sc1
.LBB0_416:
	s_or_b64 exec, exec, s[12:13]
	s_bcnt1_i32_b64 s8, s[8:9]
	s_add_i32 s10, s14, s8
	s_and_saveexec_b64 s[8:9], s[6:7]
	s_cbranch_execz .LBB0_418
	v_mbcnt_lo_u32_b32 v66, s4, 0
	v_mbcnt_hi_u32_b32 v66, s5, v66
	v_add_u32_e32 v66, s10, v66
	v_ashrrev_i32_e32 v67, 31, v66
	v_lshl_add_u64 v[66:67], v[66:67], 2, s[0:1]
	global_store_dword v[66:67], v195, off sc1

; __device__ __forceinline__ int mbcnt(unsigned long long m) { return __builtin_amdgcn_mbcnt_hi((unsigned)(m >> 32), __builtin_amdgcn_mbcnt_lo((unsigned)m, 0u)); }
; #define PIN8(m) asm volatile("" : "+s"(m[0]), "+s"(m[1]), "+s"(m[2]), "+s"(m[3]), "+s"(m[4]), "+s"(m[5]), "+s"(m[6]), "+s"(m[7]))
; __device__ __forceinline__ void select_query(const float* sc, int* sel, int ce, int lane) {
;     ...
;     int need = 256 - pos;
;     if (need > 0)
; #pragma unroll
;     for (int g = 0; g < 8; ++g) if (8 * g < nreg) {
;         unsigned long long m[8];
; #pragma unroll
;         for (int j = 0; j < 8; ++j) m[j] = __ballot(key[8 * g + j] == prefix);
;         PIN8(m);
; #pragma unroll
;         for (int j = 0; j < 8; ++j) { const int rank = mbcnt(m[j]);
;             if (key[8 * g + j] == prefix && rank < need) sel[pos + rank] = lane + 64 * (8 * g + j);
;             const int c = __builtin_popcountll(m[j]); const int take = c < need ? c : need; pos += take; need -= take; }
;         asm volatile("" : "+s"(pos), "+s"(need));
;     }
.LBB0_420:
	v_cmp_eq_u32_e64 s[34:35], v61, v48
	v_cmp_eq_u32_e64 s[26:27], v31, v48
	v_cmp_eq_u32_e64 s[24:25], v30, v48
	v_cmp_eq_u32_e64 s[20:21], v33, v48
	v_cmp_eq_u32_e64 s[16:17], v32, v48
	v_cmp_eq_u32_e64 s[12:13], v64, v48
	v_cmp_eq_u32_e64 s[8:9], v47, v48
	v_cmp_eq_u32_e64 s[4:5], v46, v48
	s_mov_b64 s[10:11], s[12:13]
	s_mov_b64 s[30:31], s[34:35]
	s_mov_b64 s[66:67], s[4:5]
	s_mov_b64 s[22:23], s[24:25]
	s_mov_b64 s[14:15], s[16:17]
	s_mov_b64 s[6:7], s[8:9]
	s_mov_b64 s[28:29], s[26:27]
	s_mov_b64 s[18:19], s[20:21]
	s_sub_i32 s72, 0x100, s78
	v_mbcnt_lo_u32_b32 v30, s30, 0
	v_mbcnt_hi_u32_b32 v30, s31, v30
	v_cmp_gt_i32_e32 vcc, s72, v30
	s_and_b64 s[34:35], s[34:35], vcc
	s_and_saveexec_b64 vcc, s[34:35]
	s_cbranch_execz .LBB0_422
	v_add_u32_e32 v30, s78, v30
	v_ashrrev_i32_e32 v31, 31, v30
	v_lshl_add_u64 v[30:31], v[30:31], 2, s[0:1]
	global_store_dword v[30:31], v96, off sc1
.LBB0_422:
	s_or_b64 exec, exec, vcc
	s_bcnt1_i32_b64 s30, s[30:31]
	s_min_u32 s31, s72, s30
	v_mbcnt_lo_u32_b32 v30, s28, 0
	s_add_i32 s30, s31, s78
	s_sub_i32 s31, s72, s31
	v_mbcnt_hi_u32_b32 v30, s29, v30
	v_cmp_gt_i32_e32 vcc, s31, v30
	s_and_b64 s[34:35], s[26:27], vcc
	s_and_saveexec_b64 s[26:27], s[34:35]
	s_cbranch_execz .LBB0_424
	v_add_u32_e32 v30, s30, v30
	v_ashrrev_i32_e32 v31, 31, v30
	v_lshl_add_u64 v[30:31], v[30:31], 2, s[0:1]
	global_store_dword v[30:31], v100, off sc1
.LBB0_424:
	s_or_b64 exec, exec, s[26:27]
	s_bcnt1_i32_b64 s26, s[28:29]
	s_min_i32 s27, s31, s26
	v_mbcnt_lo_u32_b32 v30, s22, 0
	s_add_i32 s26, s27, s30
	s_sub_i32 s27, s31, s27
	v_mbcnt_hi_u32_b32 v30, s23, v30
	v_cmp_gt_i32_e32 vcc, s27, v30
	s_and_b64 s[28:29], s[24:25], vcc
	s_and_saveexec_b64 s[24:25], s[28:29]
	s_cbranch_execz .LBB0_426
	v_add_u32_e32 v30, s26, v30
	v_ashrrev_i32_e32 v31, 31, v30
	v_lshl_add_u64 v[30:31], v[30:31], 2, s[0:1]
	global_store_dword v[30:31], v102, off sc1
.LBB0_426:
	s_or_b64 exec, exec, s[24:25]
	s_bcnt1_i32_b64 s22, s[22:23]
	s_min_i32 s23, s27, s22
	v_mbcnt_lo_u32_b32 v30, s18, 0
	s_add_i32 s22, s23, s26
	s_sub_i32 s23, s27, s23
	v_mbcnt_hi_u32_b32 v30, s19, v30
	v_cmp_gt_i32_e32 vcc, s23, v30
	s_and_b64 s[24:25], s[20:21], vcc
	s_and_saveexec_b64 s[20:21], s[24:25]
	s_cbranch_execz .LBB0_428
	v_add_u32_e32 v30, s22, v30
	v_ashrrev_i32_e32 v31, 31, v30
	v_lshl_add_u64 v[30:31], v[30:31], 2, s[0:1]
	global_store_dword v[30:31], v104, off sc1
.LBB0_428:
	s_or_b64 exec, exec, s[20:21]
	s_bcnt1_i32_b64 s18, s[18:19]
	s_min_i32 s19, s23, s18
	v_mbcnt_lo_u32_b32 v30, s14, 0
	s_add_i32 s18, s19, s22
	s_sub_i32 s19, s23, s19
	v_mbcnt_hi_u32_b32 v30, s15, v30
	v_cmp_gt_i32_e32 vcc, s19, v30
	s_and_b64 s[20:21], s[16:17], vcc
	s_and_saveexec_b64 s[16:17], s[20:21]
	s_cbranch_execz .LBB0_430
	v_add_u32_e32 v30, s18, v30
	v_ashrrev_i32_e32 v31, 31, v30
	v_lshl_add_u64 v[30:31], v[30:31], 2, s[0:1]
	global_store_dword v[30:31], v109, off sc1
.LBB0_430:
	s_or_b64 exec, exec, s[16:17]
	s_bcnt1_i32_b64 s14, s[14:15]
	s_min_i32 s15, s19, s14
	v_mbcnt_lo_u32_b32 v30, s10, 0
	s_add_i32 s14, s15, s18
	s_sub_i32 s15, s19, s15
	v_mbcnt_hi_u32_b32 v30, s11, v30
	v_cmp_gt_i32_e32 vcc, s15, v30
	s_and_b64 s[16:17], s[12:13], vcc
	s_and_saveexec_b64 s[12:13], s[16:17]
	s_cbranch_execz .LBB0_432
	v_add_u32_e32 v30, s14, v30
	v_ashrrev_i32_e32 v31, 31, v30
	v_lshl_add_u64 v[30:31], v[30:31], 2, s[0:1]
	global_store_dword v[30:31], v111, off sc1
.LBB0_432:
	s_or_b64 exec, exec, s[12:13]
	s_bcnt1_i32_b64 s10, s[10:11]
	s_min_i32 s11, s15, s10
	v_mbcnt_lo_u32_b32 v30, s6, 0
	s_add_i32 s10, s11, s14
	s_sub_i32 s11, s15, s11
	v_mbcnt_hi_u32_b32 v30, s7, v30
	v_cmp_gt_i32_e32 vcc, s11, v30
	s_and_b64 s[12:13], s[8:9], vcc
	s_and_saveexec_b64 s[8:9], s[12:13]
	s_cbranch_execz .LBB0_434
	v_add_u32_e32 v30, s10, v30
	v_ashrrev_i32_e32 v31, 31, v30
	v_lshl_add_u64 v[30:31], v[30:31], 2, s[0:1]
	global_store_dword v[30:31], v138, off sc1
.LBB0_434:
	s_or_b64 exec, exec, s[8:9]
	s_bcnt1_i32_b64 s6, s[6:7]
	s_min_i32 s7, s11, s6
	v_mbcnt_lo_u32_b32 v30, s66, 0
	s_add_i32 s6, s7, s10
	s_sub_i32 s7, s11, s7
	v_mbcnt_hi_u32_b32 v30, s67, v30
	v_cmp_gt_i32_e32 vcc, s7, v30
	s_and_b64 s[8:9], s[4:5], vcc
	s_and_saveexec_b64 s[4:5], s[8:9]
	s_cbranch_execz .LBB0_436
	v_add_u32_e32 v30, s6, v30
	v_ashrrev_i32_e32 v31, 31, v30
	v_lshl_add_u64 v[30:31], v[30:31], 2, s[0:1]
	global_store_dword v[30:31], v139, off sc1
; __device__ __forceinline__ int mbcnt(unsigned long long m) { return __builtin_amdgcn_mbcnt_hi((unsigned)(m >> 32), __builtin_amdgcn_mbcnt_lo((unsigned)m, 0u)); }
; #define PIN8(m) asm volatile("" : "+s"(m[0]), "+s"(m[1]), "+s"(m[2]), "+s"(m[3]), "+s"(m[4]), "+s"(m[5]), "+s"(m[6]), "+s"(m[7]))
; __device__ __forceinline__ void select_query(const float* sc, int* sel, int ce, int lane) {
;     ...
;     int need = 256 - pos;
;     if (need > 0)
; #pragma unroll
;     for (int g = 0; g < 8; ++g) if (8 * g < nreg) {
;         unsigned long long m[8];
; #pragma unroll
;         for (int j = 0; j < 8; ++j) m[j] = __ballot(key[8 * g + j] == prefix);
;         PIN8(m);
; #pragma unroll
;         for (int j = 0; j < 8; ++j) { const int rank = mbcnt(m[j]);
;             if (key[8 * g + j] == prefix && rank < need) sel[pos + rank] = lane + 64 * (8 * g + j);
;             const int c = __builtin_popcountll(m[j]); const int take = c < need ? c : need; pos += take; need -= take; }
;         asm volatile("" : "+s"(pos), "+s"(need));
;     }
.LBB0_436:
	s_or_b64 exec, exec, s[4:5]
	s_bcnt1_i32_b64 s4, s[66:67]
	s_min_i32 s4, s7, s4
	s_add_i32 s72, s4, s6
	s_sub_i32 s78, s7, s4
	s_and_b64 vcc, exec, s[64:65]
	s_cbranch_vccnz .LBB0_491
	v_cmp_eq_u32_e64 s[30:31], v59, v48
	v_cmp_eq_u32_e64 s[26:27], v63, v48
	v_cmp_eq_u32_e64 s[20:21], v41, v48
	v_cmp_eq_u32_e64 s[18:19], v40, v48
	v_cmp_eq_u32_e64 s[14:15], v43, v48
	v_cmp_eq_u32_e64 s[12:13], v42, v48
	v_cmp_eq_u32_e64 s[6:7], v45, v48
	v_cmp_eq_u32_e64 s[4:5], v44, v48
	s_mov_b64 s[24:25], s[26:27]
	s_mov_b64 s[66:67], s[18:19]
	s_mov_b64 s[10:11], s[12:13]
	s_mov_b64 s[28:29], s[30:31]
	s_mov_b64 s[64:65], s[4:5]
	s_mov_b64 s[22:23], s[20:21]
	s_mov_b64 s[16:17], s[14:15]
	s_mov_b64 s[8:9], s[6:7]
	s_nop 0
	v_mbcnt_lo_u32_b32 v30, s28, 0
	v_mbcnt_hi_u32_b32 v30, s29, v30
	v_cmp_gt_i32_e32 vcc, s78, v30
	s_and_b64 s[34:35], s[30:31], vcc
	s_and_saveexec_b64 s[30:31], s[34:35]
	s_cbranch_execz .LBB0_439
	v_add_u32_e32 v30, s72, v30
	v_ashrrev_i32_e32 v31, 31, v30
	v_lshl_add_u64 v[30:31], v[30:31], 2, s[0:1]
	global_store_dword v[30:31], v140, off sc1
.LBB0_439:
	s_or_b64 exec, exec, s[30:31]
	s_bcnt1_i32_b64 s28, s[28:29]
	s_min_i32 s29, s78, s28
	v_mbcnt_lo_u32_b32 v30, s24, 0
	s_add_i32 s28, s29, s72
	s_sub_i32 s29, s78, s29
	v_mbcnt_hi_u32_b32 v30, s25, v30
	v_cmp_gt_i32_e32 vcc, s29, v30
	s_and_b64 s[30:31], s[26:27], vcc
	s_and_saveexec_b64 s[26:27], s[30:31]
	s_cbranch_execz .LBB0_441
	v_add_u32_e32 v30, s28, v30
	v_ashrrev_i32_e32 v31, 31, v30
	v_lshl_add_u64 v[30:31], v[30:31], 2, s[0:1]
	global_store_dword v[30:31], v141, off sc1
.LBB0_441:
	s_or_b64 exec, exec, s[26:27]
	s_bcnt1_i32_b64 s24, s[24:25]
	s_min_i32 s25, s29, s24
	v_mbcnt_lo_u32_b32 v30, s22, 0
	s_add_i32 s24, s25, s28
	s_sub_i32 s25, s29, s25
	v_mbcnt_hi_u32_b32 v30, s23, v30
	v_cmp_gt_i32_e32 vcc, s25, v30
	s_and_b64 s[26:27], s[20:21], vcc
	s_and_saveexec_b64 s[20:21], s[26:27]
	s_cbranch_execz .LBB0_443
	v_add_u32_e32 v30, s24, v30
	v_ashrrev_i32_e32 v31, 31, v30
	v_lshl_add_u64 v[30:31], v[30:31], 2, s[0:1]
	global_store_dword v[30:31], v142, off sc1
.LBB0_443:
	s_or_b64 exec, exec, s[20:21]
	s_bcnt1_i32_b64 s20, s[22:23]
	s_min_i32 s21, s25, s20
	v_mbcnt_lo_u32_b32 v30, s66, 0
	s_add_i32 s20, s21, s24
	s_sub_i32 s21, s25, s21
	v_mbcnt_hi_u32_b32 v30, s67, v30
	v_cmp_gt_i32_e32 vcc, s21, v30
	s_and_b64 s[22:23], s[18:19], vcc
	s_and_saveexec_b64 s[18:19], s[22:23]
	s_cbranch_execz .LBB0_445
	v_add_u32_e32 v30, s20, v30
	v_ashrrev_i32_e32 v31, 31, v30
	v_lshl_add_u64 v[30:31], v[30:31], 2, s[0:1]
	global_store_dword v[30:31], v143, off sc1
.LBB0_445:
	s_or_b64 exec, exec, s[18:19]
	s_bcnt1_i32_b64 s18, s[66:67]
	s_min_i32 s19, s21, s18
	v_mbcnt_lo_u32_b32 v30, s16, 0
	s_add_i32 s18, s19, s20
	s_sub_i32 s19, s21, s19
	v_mbcnt_hi_u32_b32 v30, s17, v30
	v_cmp_gt_i32_e32 vcc, s19, v30
	s_and_b64 s[20:21], s[14:15], vcc
	s_and_saveexec_b64 s[14:15], s[20:21]
	s_cbranch_execz .LBB0_447
	v_add_u32_e32 v30, s18, v30
	v_ashrrev_i32_e32 v31, 31, v30
	v_lshl_add_u64 v[30:31], v[30:31], 2, s[0:1]
	global_store_dword v[30:31], v144, off sc1
.LBB0_447:
	s_or_b64 exec, exec, s[14:15]
	s_bcnt1_i32_b64 s14, s[16:17]
	s_min_i32 s15, s19, s14
	v_mbcnt_lo_u32_b32 v30, s10, 0
	s_add_i32 s14, s15, s18
	s_sub_i32 s15, s19, s15
	v_mbcnt_hi_u32_b32 v30, s11, v30
	v_cmp_gt_i32_e32 vcc, s15, v30
	s_and_b64 s[16:17], s[12:13], vcc
	s_and_saveexec_b64 s[12:13], s[16:17]
	s_cbranch_execz .LBB0_449
	v_add_u32_e32 v30, s14, v30
	v_ashrrev_i32_e32 v31, 31, v30
	v_lshl_add_u64 v[30:31], v[30:31], 2, s[0:1]
	global_store_dword v[30:31], v145, off sc1
.LBB0_449:
	s_or_b64 exec, exec, s[12:13]
	s_bcnt1_i32_b64 s10, s[10:11]
	s_min_i32 s11, s15, s10
	v_mbcnt_lo_u32_b32 v30, s8, 0
	s_add_i32 s10, s11, s14
	s_sub_i32 s11, s15, s11
	v_mbcnt_hi_u32_b32 v30, s9, v30
	v_cmp_gt_i32_e32 vcc, s11, v30
	s_and_b64 s[12:13], s[6:7], vcc
	s_and_saveexec_b64 s[6:7], s[12:13]
	s_cbranch_execz .LBB0_451
	v_add_u32_e32 v30, s10, v30
	v_ashrrev_i32_e32 v31, 31, v30
	v_lshl_add_u64 v[30:31], v[30:31], 2, s[0:1]
	global_store_dword v[30:31], v146, off sc1
.LBB0_451:
	s_or_b64 exec, exec, s[6:7]
	s_bcnt1_i32_b64 s6, s[8:9]
	s_min_i32 s7, s11, s6
	v_mbcnt_lo_u32_b32 v30, s64, 0
	s_add_i32 s6, s7, s10
	s_sub_i32 s7, s11, s7
	v_mbcnt_hi_u32_b32 v30, s65, v30
	v_cmp_gt_i32_e32 vcc, s7, v30
	s_and_b64 s[8:9], s[4:5], vcc
	s_and_saveexec_b64 s[4:5], s[8:9]
	s_cbranch_execz .LBB0_453
	v_add_u32_e32 v30, s6, v30
	v_ashrrev_i32_e32 v31, 31, v30
	v_lshl_add_u64 v[30:31], v[30:31], 2, s[0:1]
	global_store_dword v[30:31], v147, off sc1

; __device__ __forceinline__ int mbcnt(unsigned long long m) { return __builtin_amdgcn_mbcnt_hi((unsigned)(m >> 32), __builtin_amdgcn_mbcnt_lo((unsigned)m, 0u)); }
; #define PIN8(m) asm volatile("" : "+s"(m[0]), "+s"(m[1]), "+s"(m[2]), "+s"(m[3]), "+s"(m[4]), "+s"(m[5]), "+s"(m[6]), "+s"(m[7]))
; __device__ __forceinline__ void select_query(const float* sc, int* sel, int ce, int lane) {
;     ...
;     int need = 256 - pos;
;     if (need > 0)
; #pragma unroll
;     for (int g = 0; g < 8; ++g) if (8 * g < nreg) {
;         unsigned long long m[8];
; #pragma unroll
;         for (int j = 0; j < 8; ++j) m[j] = __ballot(key[8 * g + j] == prefix);
;         PIN8(m);
; #pragma unroll
;         for (int j = 0; j < 8; ++j) { const int rank = mbcnt(m[j]);
;             if (key[8 * g + j] == prefix && rank < need) sel[pos + rank] = lane + 64 * (8 * g + j);
;             const int c = __builtin_popcountll(m[j]); const int take = c < need ? c : need; pos += take; need -= take; }
;         asm volatile("" : "+s"(pos), "+s"(need));
;     }
.LBB0_455:
	v_cmp_eq_u32_e64 s[30:31], v56, v48
	v_cmp_eq_u32_e64 s[24:25], v60, v48
	v_cmp_eq_u32_e64 s[22:23], v25, v48
	v_cmp_eq_u32_e64 s[16:17], v24, v48
	v_cmp_eq_u32_e64 s[14:15], v27, v48
	v_cmp_eq_u32_e64 s[8:9], v26, v48
	v_cmp_eq_u32_e64 s[6:7], v29, v48
	v_cmp_eq_u32_e64 s[4:5], v28, v48
	s_mov_b64 s[20:21], s[22:23]
	s_mov_b64 s[12:13], s[14:15]
	s_mov_b64 s[62:63], s[6:7]
	s_mov_b64 s[26:27], s[24:25]
	s_mov_b64 s[18:19], s[16:17]
	s_mov_b64 s[10:11], s[8:9]
	s_mov_b64 s[28:29], s[30:31]
	s_mov_b64 s[60:61], s[4:5]
	s_nop 0
	v_mbcnt_lo_u32_b32 v24, s28, 0
	v_mbcnt_hi_u32_b32 v24, s29, v24
	v_cmp_gt_i32_e32 vcc, s78, v24
	s_and_b64 s[34:35], s[30:31], vcc
	s_and_saveexec_b64 s[30:31], s[34:35]
	s_cbranch_execz .LBB0_457
	v_add_u32_e32 v24, s72, v24
	v_ashrrev_i32_e32 v25, 31, v24
	v_lshl_add_u64 v[24:25], v[24:25], 2, s[0:1]
	global_store_dword v[24:25], v156, off sc1
.LBB0_457:
	s_or_b64 exec, exec, s[30:31]
	s_bcnt1_i32_b64 s28, s[28:29]
	s_min_i32 s29, s78, s28
	v_mbcnt_lo_u32_b32 v24, s26, 0
	s_add_i32 s28, s29, s72
	s_sub_i32 s29, s78, s29
	v_mbcnt_hi_u32_b32 v24, s27, v24
	v_cmp_gt_i32_e32 vcc, s29, v24
	s_and_b64 s[30:31], s[24:25], vcc
	s_and_saveexec_b64 s[24:25], s[30:31]
	s_cbranch_execz .LBB0_459
	v_add_u32_e32 v24, s28, v24
	v_ashrrev_i32_e32 v25, 31, v24
	v_lshl_add_u64 v[24:25], v[24:25], 2, s[0:1]
	global_store_dword v[24:25], v157, off sc1
.LBB0_459:
	s_or_b64 exec, exec, s[24:25]
	s_bcnt1_i32_b64 s24, s[26:27]
	s_min_i32 s25, s29, s24
	v_mbcnt_lo_u32_b32 v24, s20, 0
	s_add_i32 s24, s25, s28
	s_sub_i32 s25, s29, s25
	v_mbcnt_hi_u32_b32 v24, s21, v24
	v_cmp_gt_i32_e32 vcc, s25, v24
	s_and_b64 s[26:27], s[22:23], vcc
	s_and_saveexec_b64 s[22:23], s[26:27]
	s_cbranch_execz .LBB0_461
	v_add_u32_e32 v24, s24, v24
	v_ashrrev_i32_e32 v25, 31, v24
	v_lshl_add_u64 v[24:25], v[24:25], 2, s[0:1]
	global_store_dword v[24:25], v158, off sc1
.LBB0_461:
	s_or_b64 exec, exec, s[22:23]
	s_bcnt1_i32_b64 s20, s[20:21]
	s_min_i32 s21, s25, s20
	v_mbcnt_lo_u32_b32 v24, s18, 0
	s_add_i32 s20, s21, s24
	s_sub_i32 s21, s25, s21
	v_mbcnt_hi_u32_b32 v24, s19, v24
	v_cmp_gt_i32_e32 vcc, s21, v24
	s_and_b64 s[22:23], s[16:17], vcc
	s_and_saveexec_b64 s[16:17], s[22:23]
	s_cbranch_execz .LBB0_463
	v_add_u32_e32 v24, s20, v24
	v_ashrrev_i32_e32 v25, 31, v24
	v_lshl_add_u64 v[24:25], v[24:25], 2, s[0:1]
	global_store_dword v[24:25], v159, off sc1
.LBB0_463:
	s_or_b64 exec, exec, s[16:17]
	s_bcnt1_i32_b64 s16, s[18:19]
	s_min_i32 s17, s21, s16
	v_mbcnt_lo_u32_b32 v24, s12, 0
	s_add_i32 s16, s17, s20
	s_sub_i32 s17, s21, s17
	v_mbcnt_hi_u32_b32 v24, s13, v24
	v_cmp_gt_i32_e32 vcc, s17, v24
	s_and_b64 s[18:19], s[14:15], vcc
	s_and_saveexec_b64 s[14:15], s[18:19]
	s_cbranch_execz .LBB0_465
	v_add_u32_e32 v24, s16, v24
	v_ashrrev_i32_e32 v25, 31, v24
	v_lshl_add_u64 v[24:25], v[24:25], 2, s[0:1]
	global_store_dword v[24:25], v160, off sc1
.LBB0_465:
	s_or_b64 exec, exec, s[14:15]
	s_bcnt1_i32_b64 s12, s[12:13]
	s_min_i32 s13, s17, s12
	v_mbcnt_lo_u32_b32 v24, s10, 0
	s_add_i32 s12, s13, s16
	s_sub_i32 s13, s17, s13
	v_mbcnt_hi_u32_b32 v24, s11, v24
	v_cmp_gt_i32_e32 vcc, s13, v24
	s_and_b64 s[14:15], s[8:9], vcc
	s_and_saveexec_b64 s[8:9], s[14:15]
	s_cbranch_execz .LBB0_467
	v_add_u32_e32 v24, s12, v24
	v_ashrrev_i32_e32 v25, 31, v24
	v_lshl_add_u64 v[24:25], v[24:25], 2, s[0:1]
	global_store_dword v[24:25], v161, off sc1
.LBB0_467:
	s_or_b64 exec, exec, s[8:9]
	s_bcnt1_i32_b64 s8, s[10:11]
	s_min_i32 s9, s13, s8
	v_mbcnt_lo_u32_b32 v24, s62, 0
	s_add_i32 s8, s9, s12
	s_sub_i32 s9, s13, s9
	v_mbcnt_hi_u32_b32 v24, s63, v24
	v_cmp_gt_i32_e32 vcc, s9, v24
	s_and_b64 s[10:11], s[6:7], vcc
	s_and_saveexec_b64 s[6:7], s[10:11]
	s_cbranch_execz .LBB0_469
	v_add_u32_e32 v24, s8, v24
	v_ashrrev_i32_e32 v25, 31, v24
	v_lshl_add_u64 v[24:25], v[24:25], 2, s[0:1]
	global_store_dword v[24:25], v162, off sc1
.LBB0_469:
	s_or_b64 exec, exec, s[6:7]
	s_bcnt1_i32_b64 s6, s[62:63]
	s_min_i32 s7, s9, s6
	v_mbcnt_lo_u32_b32 v24, s60, 0
	s_add_i32 s6, s7, s8
	s_sub_i32 s7, s9, s7
	v_mbcnt_hi_u32_b32 v24, s61, v24
	v_cmp_gt_i32_e32 vcc, s7, v24
	s_and_b64 s[8:9], s[4:5], vcc
	s_and_saveexec_b64 s[4:5], s[8:9]
	s_cbranch_execz .LBB0_471
	v_add_u32_e32 v24, s6, v24
	v_ashrrev_i32_e32 v25, 31, v24
	v_lshl_add_u64 v[24:25], v[24:25], 2, s[0:1]
	global_store_dword v[24:25], v163, off sc1

; __device__ __forceinline__ int mbcnt(unsigned long long m) { return __builtin_amdgcn_mbcnt_hi((unsigned)(m >> 32), __builtin_amdgcn_mbcnt_lo((unsigned)m, 0u)); }
; #define PIN8(m) asm volatile("" : "+s"(m[0]), "+s"(m[1]), "+s"(m[2]), "+s"(m[3]), "+s"(m[4]), "+s"(m[5]), "+s"(m[6]), "+s"(m[7]))
; __device__ __forceinline__ void select_query(const float* sc, int* sel, int ce, int lane) {
;     ...
;     for (int g = 0; g < 8; ++g) if (8 * g < nreg) {
;         unsigned long long m[8];
; #pragma unroll
;         for (int j = 0; j < 8; ++j) m[j] = __ballot(key[8 * g + j] == prefix);
;         PIN8(m);
; #pragma unroll
;         for (int j = 0; j < 8; ++j) { const int rank = mbcnt(m[j]);
;             if (key[8 * g + j] == prefix && rank < need) sel[pos + rank] = lane + 64 * (8 * g + j);
;             const int c = __builtin_popcountll(m[j]); const int take = c < need ? c : need; pos += take; need -= take; }
;         asm volatile("" : "+s"(pos), "+s"(need));
;     }
.LBB0_473:
	v_cmp_eq_u32_e64 s[30:31], v52, v48
	v_cmp_eq_u32_e64 s[24:25], v55, v48
	v_cmp_eq_u32_e64 s[20:21], v13, v48
	v_cmp_eq_u32_e64 s[18:19], v12, v48
	v_cmp_eq_u32_e64 s[14:15], v15, v48
	v_cmp_eq_u32_e64 s[12:13], v14, v48
	v_cmp_eq_u32_e64 s[6:7], v17, v48
	v_cmp_eq_u32_e64 s[4:5], v16, v48
	s_mov_b64 s[58:59], s[18:19]
	s_mov_b64 s[10:11], s[12:13]
	s_mov_b64 s[28:29], s[30:31]
	s_mov_b64 s[56:57], s[4:5]
	s_mov_b64 s[22:23], s[20:21]
	s_mov_b64 s[16:17], s[14:15]
	s_mov_b64 s[8:9], s[6:7]
	s_mov_b64 s[26:27], s[24:25]
	s_nop 0
	v_mbcnt_lo_u32_b32 v12, s28, 0
	v_mbcnt_hi_u32_b32 v12, s29, v12
	v_cmp_gt_i32_e32 vcc, s78, v12
	s_and_b64 s[34:35], s[30:31], vcc
	s_and_saveexec_b64 s[30:31], s[34:35]
	s_cbranch_execz .LBB0_475
	v_add_u32_e32 v12, s72, v12
	v_ashrrev_i32_e32 v13, 31, v12
	v_lshl_add_u64 v[12:13], v[12:13], 2, s[0:1]
	global_store_dword v[12:13], v172, off sc1
.LBB0_475:
	s_or_b64 exec, exec, s[30:31]
	s_bcnt1_i32_b64 s28, s[28:29]
	s_min_i32 s29, s78, s28
	v_mbcnt_lo_u32_b32 v12, s26, 0
	s_add_i32 s28, s29, s72
	s_sub_i32 s29, s78, s29
	v_mbcnt_hi_u32_b32 v12, s27, v12
	v_cmp_gt_i32_e32 vcc, s29, v12
	s_and_b64 s[30:31], s[24:25], vcc
	s_and_saveexec_b64 s[24:25], s[30:31]
	s_cbranch_execz .LBB0_477
	v_add_u32_e32 v12, s28, v12
	v_ashrrev_i32_e32 v13, 31, v12
	v_lshl_add_u64 v[12:13], v[12:13], 2, s[0:1]
	global_store_dword v[12:13], v173, off sc1
.LBB0_477:
	s_or_b64 exec, exec, s[24:25]
	s_bcnt1_i32_b64 s24, s[26:27]
	s_min_i32 s25, s29, s24
	v_mbcnt_lo_u32_b32 v12, s22, 0
	s_add_i32 s24, s25, s28
	s_sub_i32 s25, s29, s25
	v_mbcnt_hi_u32_b32 v12, s23, v12
	v_cmp_gt_i32_e32 vcc, s25, v12
	s_and_b64 s[26:27], s[20:21], vcc
	s_and_saveexec_b64 s[20:21], s[26:27]
	s_cbranch_execz .LBB0_479
	v_add_u32_e32 v12, s24, v12
	v_ashrrev_i32_e32 v13, 31, v12
	v_lshl_add_u64 v[12:13], v[12:13], 2, s[0:1]
	global_store_dword v[12:13], v174, off sc1
.LBB0_479:
	s_or_b64 exec, exec, s[20:21]
	s_bcnt1_i32_b64 s20, s[22:23]
	s_min_i32 s21, s25, s20
	v_mbcnt_lo_u32_b32 v12, s58, 0
	s_add_i32 s20, s21, s24
	s_sub_i32 s21, s25, s21
	v_mbcnt_hi_u32_b32 v12, s59, v12
	v_cmp_gt_i32_e32 vcc, s21, v12
	s_and_b64 s[22:23], s[18:19], vcc
	s_and_saveexec_b64 s[18:19], s[22:23]
	s_cbranch_execz .LBB0_481
	v_add_u32_e32 v12, s20, v12
	v_ashrrev_i32_e32 v13, 31, v12
	v_lshl_add_u64 v[12:13], v[12:13], 2, s[0:1]
	global_store_dword v[12:13], v175, off sc1
.LBB0_481:
	s_or_b64 exec, exec, s[18:19]
	s_bcnt1_i32_b64 s18, s[58:59]
	s_min_i32 s19, s21, s18
	v_mbcnt_lo_u32_b32 v12, s16, 0
	s_add_i32 s18, s19, s20
	s_sub_i32 s19, s21, s19
	v_mbcnt_hi_u32_b32 v12, s17, v12
	v_cmp_gt_i32_e32 vcc, s19, v12
	s_and_b64 s[20:21], s[14:15], vcc
	s_and_saveexec_b64 s[14:15], s[20:21]
	s_cbranch_execz .LBB0_483
	v_add_u32_e32 v12, s18, v12
	v_ashrrev_i32_e32 v13, 31, v12
	v_lshl_add_u64 v[12:13], v[12:13], 2, s[0:1]
	global_store_dword v[12:13], v176, off sc1
.LBB0_483:
	s_or_b64 exec, exec, s[14:15]
	s_bcnt1_i32_b64 s14, s[16:17]
	s_min_i32 s15, s19, s14
	v_mbcnt_lo_u32_b32 v12, s10, 0
	s_add_i32 s14, s15, s18
	s_sub_i32 s15, s19, s15
	v_mbcnt_hi_u32_b32 v12, s11, v12
	v_cmp_gt_i32_e32 vcc, s15, v12
	s_and_b64 s[16:17], s[12:13], vcc
	s_and_saveexec_b64 s[12:13], s[16:17]
	s_cbranch_execz .LBB0_485
	v_add_u32_e32 v12, s14, v12
	v_ashrrev_i32_e32 v13, 31, v12
	v_lshl_add_u64 v[12:13], v[12:13], 2, s[0:1]
	global_store_dword v[12:13], v177, off sc1
.LBB0_485:
	s_or_b64 exec, exec, s[12:13]
	s_bcnt1_i32_b64 s10, s[10:11]
	s_min_i32 s11, s15, s10
	v_mbcnt_lo_u32_b32 v12, s8, 0
	s_add_i32 s10, s11, s14
	s_sub_i32 s11, s15, s11
	v_mbcnt_hi_u32_b32 v12, s9, v12
	v_cmp_gt_i32_e32 vcc, s11, v12
	s_and_b64 s[12:13], s[6:7], vcc
	s_and_saveexec_b64 s[6:7], s[12:13]
	s_cbranch_execz .LBB0_487
	v_add_u32_e32 v12, s10, v12
	v_ashrrev_i32_e32 v13, 31, v12
	v_lshl_add_u64 v[12:13], v[12:13], 2, s[0:1]
	global_store_dword v[12:13], v178, off sc1
.LBB0_487:
	s_or_b64 exec, exec, s[6:7]
	s_bcnt1_i32_b64 s6, s[8:9]
	s_min_i32 s7, s11, s6
	v_mbcnt_lo_u32_b32 v12, s56, 0
	s_add_i32 s6, s7, s10
	s_sub_i32 s7, s11, s7
	v_mbcnt_hi_u32_b32 v12, s57, v12
	v_cmp_gt_i32_e32 vcc, s7, v12
	s_and_b64 s[8:9], s[4:5], vcc
	s_and_saveexec_b64 s[4:5], s[8:9]
	s_cbranch_execz .LBB0_489
	v_add_u32_e32 v12, s6, v12
	v_ashrrev_i32_e32 v13, 31, v12
	v_lshl_add_u64 v[12:13], v[12:13], 2, s[0:1]
	global_store_dword v[12:13], v179, off sc1

; __device__ __forceinline__ int mbcnt(unsigned long long m) { return __builtin_amdgcn_mbcnt_hi((unsigned)(m >> 32), __builtin_amdgcn_mbcnt_lo((unsigned)m, 0u)); }
; #define PIN8(m) asm volatile("" : "+s"(m[0]), "+s"(m[1]), "+s"(m[2]), "+s"(m[3]), "+s"(m[4]), "+s"(m[5]), "+s"(m[6]), "+s"(m[7]))
; __device__ __forceinline__ void select_query(const float* sc, int* sel, int ce, int lane) {
;     ...
;     for (int g = 0; g < 8; ++g) if (8 * g < nreg) {
;         unsigned long long m[8];
; #pragma unroll
;         for (int j = 0; j < 8; ++j) m[j] = __ballot(key[8 * g + j] == prefix);
;         PIN8(m);
; #pragma unroll
;         for (int j = 0; j < 8; ++j) { const int rank = mbcnt(m[j]);
;             if (key[8 * g + j] == prefix && rank < need) sel[pos + rank] = lane + 64 * (8 * g + j);
;             const int c = __builtin_popcountll(m[j]); const int take = c < need ? c : need; pos += take; need -= take; }
;         asm volatile("" : "+s"(pos), "+s"(need));
;     }
.LBB0_492:
	v_cmp_eq_u32_e64 s[34:35], v58, v48
	v_cmp_eq_u32_e64 s[26:27], v62, v48
	v_cmp_eq_u32_e64 s[22:23], v35, v48
	v_cmp_eq_u32_e64 s[18:19], v34, v48
	v_cmp_eq_u32_e64 s[14:15], v37, v48
	v_cmp_eq_u32_e64 s[12:13], v36, v48
	v_cmp_eq_u32_e64 s[8:9], v39, v48
	v_cmp_eq_u32_e64 s[4:5], v38, v48
	s_mov_b64 s[10:11], s[12:13]
	s_mov_b64 s[30:31], s[34:35]
	s_mov_b64 s[62:63], s[4:5]
	s_mov_b64 s[24:25], s[22:23]
	s_mov_b64 s[16:17], s[14:15]
	s_mov_b64 s[6:7], s[8:9]
	s_mov_b64 s[28:29], s[26:27]
	s_mov_b64 s[20:21], s[18:19]
	s_nop 0
	v_mbcnt_lo_u32_b32 v30, s30, 0
	v_mbcnt_hi_u32_b32 v30, s31, v30
	v_cmp_gt_i32_e32 vcc, s78, v30
	s_and_b64 s[34:35], s[34:35], vcc
	s_and_saveexec_b64 s[64:65], s[34:35]
	s_cbranch_execz .LBB0_494
	v_add_u32_e32 v30, s72, v30
	v_ashrrev_i32_e32 v31, 31, v30
	v_lshl_add_u64 v[30:31], v[30:31], 2, s[0:1]
	global_store_dword v[30:31], v148, off sc1
.LBB0_494:
	s_or_b64 exec, exec, s[64:65]
	s_bcnt1_i32_b64 s30, s[30:31]
	s_min_i32 s31, s78, s30
	v_mbcnt_lo_u32_b32 v30, s28, 0
	s_add_i32 s30, s31, s72
	s_sub_i32 s31, s78, s31
	v_mbcnt_hi_u32_b32 v30, s29, v30
	v_cmp_gt_i32_e32 vcc, s31, v30
	s_and_b64 s[34:35], s[26:27], vcc
	s_and_saveexec_b64 s[26:27], s[34:35]
	s_cbranch_execz .LBB0_496
	v_add_u32_e32 v30, s30, v30
	v_ashrrev_i32_e32 v31, 31, v30
	v_lshl_add_u64 v[30:31], v[30:31], 2, s[0:1]
	global_store_dword v[30:31], v149, off sc1
.LBB0_496:
	s_or_b64 exec, exec, s[26:27]
	s_bcnt1_i32_b64 s26, s[28:29]
	s_min_i32 s27, s31, s26
	v_mbcnt_lo_u32_b32 v30, s24, 0
	s_add_i32 s26, s27, s30
	s_sub_i32 s27, s31, s27
	v_mbcnt_hi_u32_b32 v30, s25, v30
	v_cmp_gt_i32_e32 vcc, s27, v30
	s_and_b64 s[28:29], s[22:23], vcc
	s_and_saveexec_b64 s[22:23], s[28:29]
	s_cbranch_execz .LBB0_498
	v_add_u32_e32 v30, s26, v30
	v_ashrrev_i32_e32 v31, 31, v30
	v_lshl_add_u64 v[30:31], v[30:31], 2, s[0:1]
	global_store_dword v[30:31], v150, off sc1
.LBB0_498:
	s_or_b64 exec, exec, s[22:23]
	s_bcnt1_i32_b64 s22, s[24:25]
	s_min_i32 s23, s27, s22
	v_mbcnt_lo_u32_b32 v30, s20, 0
	s_add_i32 s22, s23, s26
	s_sub_i32 s23, s27, s23
	v_mbcnt_hi_u32_b32 v30, s21, v30
	v_cmp_gt_i32_e32 vcc, s23, v30
	s_and_b64 s[24:25], s[18:19], vcc
	s_and_saveexec_b64 s[18:19], s[24:25]
	s_cbranch_execz .LBB0_500
	v_add_u32_e32 v30, s22, v30
	v_ashrrev_i32_e32 v31, 31, v30
	v_lshl_add_u64 v[30:31], v[30:31], 2, s[0:1]
	global_store_dword v[30:31], v151, off sc1
.LBB0_500:
	s_or_b64 exec, exec, s[18:19]
	s_bcnt1_i32_b64 s18, s[20:21]
	s_min_i32 s19, s23, s18
	v_mbcnt_lo_u32_b32 v30, s16, 0
	s_add_i32 s18, s19, s22
	s_sub_i32 s19, s23, s19
	v_mbcnt_hi_u32_b32 v30, s17, v30
	v_cmp_gt_i32_e32 vcc, s19, v30
	s_and_b64 s[20:21], s[14:15], vcc
	s_and_saveexec_b64 s[14:15], s[20:21]
	s_cbranch_execz .LBB0_502
	v_add_u32_e32 v30, s18, v30
	v_ashrrev_i32_e32 v31, 31, v30
	v_lshl_add_u64 v[30:31], v[30:31], 2, s[0:1]
	global_store_dword v[30:31], v152, off sc1
.LBB0_502:
	s_or_b64 exec, exec, s[14:15]
	s_bcnt1_i32_b64 s14, s[16:17]
	s_min_i32 s15, s19, s14
	v_mbcnt_lo_u32_b32 v30, s10, 0
	s_add_i32 s14, s15, s18
	s_sub_i32 s15, s19, s15
	v_mbcnt_hi_u32_b32 v30, s11, v30
	v_cmp_gt_i32_e32 vcc, s15, v30
	s_and_b64 s[16:17], s[12:13], vcc
	s_and_saveexec_b64 s[12:13], s[16:17]
	s_cbranch_execz .LBB0_504
	v_add_u32_e32 v30, s14, v30
	v_ashrrev_i32_e32 v31, 31, v30
	v_lshl_add_u64 v[30:31], v[30:31], 2, s[0:1]
	global_store_dword v[30:31], v153, off sc1
.LBB0_504:
	s_or_b64 exec, exec, s[12:13]
	s_bcnt1_i32_b64 s10, s[10:11]
	s_min_i32 s11, s15, s10
	v_mbcnt_lo_u32_b32 v30, s6, 0
	s_add_i32 s10, s11, s14
	s_sub_i32 s11, s15, s11
	v_mbcnt_hi_u32_b32 v30, s7, v30
	v_cmp_gt_i32_e32 vcc, s11, v30
	s_and_b64 s[12:13], s[8:9], vcc
	s_and_saveexec_b64 s[8:9], s[12:13]
	s_cbranch_execz .LBB0_506
	v_add_u32_e32 v30, s10, v30
	v_ashrrev_i32_e32 v31, 31, v30
	v_lshl_add_u64 v[30:31], v[30:31], 2, s[0:1]
	global_store_dword v[30:31], v154, off sc1
.LBB0_506:
	s_or_b64 exec, exec, s[8:9]
	s_bcnt1_i32_b64 s6, s[6:7]
	s_min_i32 s7, s11, s6
	v_mbcnt_lo_u32_b32 v30, s62, 0
	s_add_i32 s6, s7, s10
	s_sub_i32 s7, s11, s7
	v_mbcnt_hi_u32_b32 v30, s63, v30
	v_cmp_gt_i32_e32 vcc, s7, v30
	s_and_b64 s[8:9], s[4:5], vcc
	s_and_saveexec_b64 s[4:5], s[8:9]
	s_cbranch_execz .LBB0_508
	v_add_u32_e32 v30, s6, v30
	v_ashrrev_i32_e32 v31, 31, v30
	v_lshl_add_u64 v[30:31], v[30:31], 2, s[0:1]
	global_store_dword v[30:31], v155, off sc1

; __device__ __forceinline__ int mbcnt(unsigned long long m) { return __builtin_amdgcn_mbcnt_hi((unsigned)(m >> 32), __builtin_amdgcn_mbcnt_lo((unsigned)m, 0u)); }
; #define PIN8(m) asm volatile("" : "+s"(m[0]), "+s"(m[1]), "+s"(m[2]), "+s"(m[3]), "+s"(m[4]), "+s"(m[5]), "+s"(m[6]), "+s"(m[7]))
; __device__ __forceinline__ void select_query(const float* sc, int* sel, int ce, int lane) {
;     ...
;     for (int g = 0; g < 8; ++g) if (8 * g < nreg) {
;         unsigned long long m[8];
; #pragma unroll
;         for (int j = 0; j < 8; ++j) m[j] = __ballot(key[8 * g + j] == prefix);
;         PIN8(m);
; #pragma unroll
;         for (int j = 0; j < 8; ++j) { const int rank = mbcnt(m[j]);
;             if (key[8 * g + j] == prefix && rank < need) sel[pos + rank] = lane + 64 * (8 * g + j);
;             const int c = __builtin_popcountll(m[j]); const int take = c < need ? c : need; pos += take; need -= take; }
;         asm volatile("" : "+s"(pos), "+s"(need));
;     }
.LBB0_510:
	v_cmp_eq_u32_e64 s[30:31], v54, v48
	v_cmp_eq_u32_e64 s[24:25], v57, v48
	v_cmp_eq_u32_e64 s[20:21], v19, v48
	v_cmp_eq_u32_e64 s[18:19], v18, v48
	v_cmp_eq_u32_e64 s[12:13], v21, v48
	v_cmp_eq_u32_e64 s[10:11], v20, v48
	v_cmp_eq_u32_e64 s[6:7], v23, v48
	v_cmp_eq_u32_e64 s[4:5], v22, v48
	s_mov_b64 s[60:61], s[6:7]
	s_mov_b64 s[26:27], s[24:25]
	s_mov_b64 s[16:17], s[18:19]
	s_mov_b64 s[8:9], s[10:11]
	s_mov_b64 s[28:29], s[30:31]
	s_mov_b64 s[58:59], s[4:5]
	s_mov_b64 s[22:23], s[20:21]
	s_mov_b64 s[14:15], s[12:13]
	s_nop 0
	v_mbcnt_lo_u32_b32 v18, s28, 0
	v_mbcnt_hi_u32_b32 v18, s29, v18
	v_cmp_gt_i32_e32 vcc, s78, v18
	s_and_b64 s[34:35], s[30:31], vcc
	s_and_saveexec_b64 s[30:31], s[34:35]
	s_cbranch_execz .LBB0_512
	v_add_u32_e32 v18, s72, v18
	v_ashrrev_i32_e32 v19, 31, v18
	v_lshl_add_u64 v[18:19], v[18:19], 2, s[0:1]
	global_store_dword v[18:19], v164, off sc1
.LBB0_512:
	s_or_b64 exec, exec, s[30:31]
	s_bcnt1_i32_b64 s28, s[28:29]
	s_min_i32 s29, s78, s28
	v_mbcnt_lo_u32_b32 v18, s26, 0
	s_add_i32 s28, s29, s72
	s_sub_i32 s29, s78, s29
	v_mbcnt_hi_u32_b32 v18, s27, v18
	v_cmp_gt_i32_e32 vcc, s29, v18
	s_and_b64 s[30:31], s[24:25], vcc
	s_and_saveexec_b64 s[24:25], s[30:31]
	s_cbranch_execz .LBB0_514
	v_add_u32_e32 v18, s28, v18
	v_ashrrev_i32_e32 v19, 31, v18
	v_lshl_add_u64 v[18:19], v[18:19], 2, s[0:1]
	global_store_dword v[18:19], v165, off sc1
.LBB0_514:
	s_or_b64 exec, exec, s[24:25]
	s_bcnt1_i32_b64 s24, s[26:27]
	s_min_i32 s25, s29, s24
	v_mbcnt_lo_u32_b32 v18, s22, 0
	s_add_i32 s24, s25, s28
	s_sub_i32 s25, s29, s25
	v_mbcnt_hi_u32_b32 v18, s23, v18
	v_cmp_gt_i32_e32 vcc, s25, v18
	s_and_b64 s[26:27], s[20:21], vcc
	s_and_saveexec_b64 s[20:21], s[26:27]
	s_cbranch_execz .LBB0_516
	v_add_u32_e32 v18, s24, v18
	v_ashrrev_i32_e32 v19, 31, v18
	v_lshl_add_u64 v[18:19], v[18:19], 2, s[0:1]
	global_store_dword v[18:19], v166, off sc1
.LBB0_516:
	s_or_b64 exec, exec, s[20:21]
	s_bcnt1_i32_b64 s20, s[22:23]
	s_min_i32 s21, s25, s20
	v_mbcnt_lo_u32_b32 v18, s16, 0
	s_add_i32 s20, s21, s24
	s_sub_i32 s21, s25, s21
	v_mbcnt_hi_u32_b32 v18, s17, v18
	v_cmp_gt_i32_e32 vcc, s21, v18
	s_and_b64 s[22:23], s[18:19], vcc
	s_and_saveexec_b64 s[18:19], s[22:23]
	s_cbranch_execz .LBB0_518
	v_add_u32_e32 v18, s20, v18
	v_ashrrev_i32_e32 v19, 31, v18
	v_lshl_add_u64 v[18:19], v[18:19], 2, s[0:1]
	global_store_dword v[18:19], v167, off sc1
.LBB0_518:
	s_or_b64 exec, exec, s[18:19]
	s_bcnt1_i32_b64 s16, s[16:17]
	s_min_i32 s17, s21, s16
	v_mbcnt_lo_u32_b32 v18, s14, 0
	s_add_i32 s16, s17, s20
	s_sub_i32 s17, s21, s17
	v_mbcnt_hi_u32_b32 v18, s15, v18
	v_cmp_gt_i32_e32 vcc, s17, v18
	s_and_b64 s[18:19], s[12:13], vcc
	s_and_saveexec_b64 s[12:13], s[18:19]
	s_cbranch_execz .LBB0_520
	v_add_u32_e32 v18, s16, v18
	v_ashrrev_i32_e32 v19, 31, v18
	v_lshl_add_u64 v[18:19], v[18:19], 2, s[0:1]
	global_store_dword v[18:19], v168, off sc1
.LBB0_520:
	s_or_b64 exec, exec, s[12:13]
	s_bcnt1_i32_b64 s12, s[14:15]
	s_min_i32 s13, s17, s12
	v_mbcnt_lo_u32_b32 v18, s8, 0
	s_add_i32 s12, s13, s16
	s_sub_i32 s13, s17, s13
	v_mbcnt_hi_u32_b32 v18, s9, v18
	v_cmp_gt_i32_e32 vcc, s13, v18
	s_and_b64 s[14:15], s[10:11], vcc
	s_and_saveexec_b64 s[10:11], s[14:15]
	s_cbranch_execz .LBB0_522
	v_add_u32_e32 v18, s12, v18
	v_ashrrev_i32_e32 v19, 31, v18
	v_lshl_add_u64 v[18:19], v[18:19], 2, s[0:1]
	global_store_dword v[18:19], v169, off sc1
.LBB0_522:
	s_or_b64 exec, exec, s[10:11]
	s_bcnt1_i32_b64 s8, s[8:9]
	s_min_i32 s9, s13, s8
	v_mbcnt_lo_u32_b32 v18, s60, 0
	s_add_i32 s8, s9, s12
	s_sub_i32 s9, s13, s9
	v_mbcnt_hi_u32_b32 v18, s61, v18
	v_cmp_gt_i32_e32 vcc, s9, v18
	s_and_b64 s[10:11], s[6:7], vcc
	s_and_saveexec_b64 s[6:7], s[10:11]
	s_cbranch_execz .LBB0_524
	v_add_u32_e32 v18, s8, v18
	v_ashrrev_i32_e32 v19, 31, v18
	v_lshl_add_u64 v[18:19], v[18:19], 2, s[0:1]
	global_store_dword v[18:19], v170, off sc1
.LBB0_524:
	s_or_b64 exec, exec, s[6:7]
	s_bcnt1_i32_b64 s6, s[60:61]
	s_min_i32 s7, s9, s6
	v_mbcnt_lo_u32_b32 v18, s58, 0
	s_add_i32 s6, s7, s8
	s_sub_i32 s7, s9, s7
	v_mbcnt_hi_u32_b32 v18, s59, v18
	v_cmp_gt_i32_e32 vcc, s7, v18
	s_and_b64 s[8:9], s[4:5], vcc
	s_and_saveexec_b64 s[4:5], s[8:9]
	s_cbranch_execz .LBB0_526
	v_add_u32_e32 v18, s6, v18
	v_ashrrev_i32_e32 v19, 31, v18
	v_lshl_add_u64 v[18:19], v[18:19], 2, s[0:1]
	global_store_dword v[18:19], v171, off sc1

; __device__ __forceinline__ int mbcnt(unsigned long long m) { return __builtin_amdgcn_mbcnt_hi((unsigned)(m >> 32), __builtin_amdgcn_mbcnt_lo((unsigned)m, 0u)); }
; #define PIN8(m) asm volatile("" : "+s"(m[0]), "+s"(m[1]), "+s"(m[2]), "+s"(m[3]), "+s"(m[4]), "+s"(m[5]), "+s"(m[6]), "+s"(m[7]))
; __device__ __forceinline__ void select_query(const float* sc, int* sel, int ce, int lane) {
;     ...
;     for (int g = 0; g < 8; ++g) if (8 * g < nreg) {
;         unsigned long long m[8];
; #pragma unroll
;         for (int j = 0; j < 8; ++j) m[j] = __ballot(key[8 * g + j] == prefix);
;         PIN8(m);
; #pragma unroll
;         for (int j = 0; j < 8; ++j) { const int rank = mbcnt(m[j]);
;             if (key[8 * g + j] == prefix && rank < need) sel[pos + rank] = lane + 64 * (8 * g + j);
;             const int c = __builtin_popcountll(m[j]); const int take = c < need ? c : need; pos += take; need -= take; }
;         asm volatile("" : "+s"(pos), "+s"(need));
;     }
.LBB0_528:
	v_cmp_eq_u32_e64 s[30:31], v50, v48
	v_cmp_eq_u32_e64 s[24:25], v53, v48
	v_cmp_eq_u32_e64 s[20:21], v7, v48
	v_cmp_eq_u32_e64 s[16:17], v6, v48
	v_cmp_eq_u32_e64 s[14:15], v9, v48
	v_cmp_eq_u32_e64 s[8:9], v8, v48
	v_cmp_eq_u32_e64 s[6:7], v11, v48
	v_cmp_eq_u32_e64 s[4:5], v10, v48
	s_mov_b64 s[28:29], s[30:31]
	s_mov_b64 s[54:55], s[4:5]
	s_mov_b64 s[22:23], s[20:21]
	s_mov_b64 s[12:13], s[14:15]
	s_mov_b64 s[56:57], s[6:7]
	s_mov_b64 s[26:27], s[24:25]
	s_mov_b64 s[18:19], s[16:17]
	s_mov_b64 s[10:11], s[8:9]
	s_nop 0
	v_mbcnt_lo_u32_b32 v6, s28, 0
	v_mbcnt_hi_u32_b32 v6, s29, v6
	v_cmp_gt_i32_e32 vcc, s78, v6
	s_and_b64 s[34:35], s[30:31], vcc
	s_and_saveexec_b64 s[30:31], s[34:35]
	s_cbranch_execz .LBB0_530
	v_add_u32_e32 v6, s72, v6
	v_ashrrev_i32_e32 v7, 31, v6
	v_lshl_add_u64 v[6:7], v[6:7], 2, s[0:1]
	global_store_dword v[6:7], v180, off sc1
.LBB0_530:
	s_or_b64 exec, exec, s[30:31]
	s_bcnt1_i32_b64 s28, s[28:29]
	s_min_i32 s29, s78, s28
	v_mbcnt_lo_u32_b32 v6, s26, 0
	s_add_i32 s28, s29, s72
	s_sub_i32 s29, s78, s29
	v_mbcnt_hi_u32_b32 v6, s27, v6
	v_cmp_gt_i32_e32 vcc, s29, v6
	s_and_b64 s[30:31], s[24:25], vcc
	s_and_saveexec_b64 s[24:25], s[30:31]
	s_cbranch_execz .LBB0_532
	v_add_u32_e32 v6, s28, v6
	v_ashrrev_i32_e32 v7, 31, v6
	v_lshl_add_u64 v[6:7], v[6:7], 2, s[0:1]
	global_store_dword v[6:7], v181, off sc1
.LBB0_532:
	s_or_b64 exec, exec, s[24:25]
	s_bcnt1_i32_b64 s24, s[26:27]
	s_min_i32 s25, s29, s24
	v_mbcnt_lo_u32_b32 v6, s22, 0
	s_add_i32 s24, s25, s28
	s_sub_i32 s25, s29, s25
	v_mbcnt_hi_u32_b32 v6, s23, v6
	v_cmp_gt_i32_e32 vcc, s25, v6
	s_and_b64 s[26:27], s[20:21], vcc
	s_and_saveexec_b64 s[20:21], s[26:27]
	s_cbranch_execz .LBB0_534
	v_add_u32_e32 v6, s24, v6
	v_ashrrev_i32_e32 v7, 31, v6
	v_lshl_add_u64 v[6:7], v[6:7], 2, s[0:1]
	global_store_dword v[6:7], v190, off sc1
.LBB0_534:
	s_or_b64 exec, exec, s[20:21]
	s_bcnt1_i32_b64 s20, s[22:23]
	s_min_i32 s21, s25, s20
	v_mbcnt_lo_u32_b32 v6, s18, 0
	s_add_i32 s20, s21, s24
	s_sub_i32 s21, s25, s21
	v_mbcnt_hi_u32_b32 v6, s19, v6
	v_cmp_gt_i32_e32 vcc, s21, v6
	s_and_b64 s[22:23], s[16:17], vcc
	s_and_saveexec_b64 s[16:17], s[22:23]
	s_cbranch_execz .LBB0_536
	v_add_u32_e32 v6, s20, v6
	v_ashrrev_i32_e32 v7, 31, v6
	v_lshl_add_u64 v[6:7], v[6:7], 2, s[0:1]
	global_store_dword v[6:7], v191, off sc1
.LBB0_536:
	s_or_b64 exec, exec, s[16:17]
	s_bcnt1_i32_b64 s16, s[18:19]
	s_min_i32 s17, s21, s16
	v_mbcnt_lo_u32_b32 v6, s12, 0
	s_add_i32 s16, s17, s20
	s_sub_i32 s17, s21, s17
	v_mbcnt_hi_u32_b32 v6, s13, v6
	v_cmp_gt_i32_e32 vcc, s17, v6
	s_and_b64 s[18:19], s[14:15], vcc
	s_and_saveexec_b64 s[14:15], s[18:19]
	s_cbranch_execz .LBB0_538
	v_add_u32_e32 v6, s16, v6
	v_ashrrev_i32_e32 v7, 31, v6
	v_lshl_add_u64 v[6:7], v[6:7], 2, s[0:1]
	global_store_dword v[6:7], v192, off sc1
.LBB0_538:
	s_or_b64 exec, exec, s[14:15]
	s_bcnt1_i32_b64 s12, s[12:13]
	s_min_i32 s13, s17, s12
	v_mbcnt_lo_u32_b32 v6, s10, 0
	s_add_i32 s12, s13, s16
	s_sub_i32 s13, s17, s13
	v_mbcnt_hi_u32_b32 v6, s11, v6
	v_cmp_gt_i32_e32 vcc, s13, v6
	s_and_b64 s[14:15], s[8:9], vcc
	s_and_saveexec_b64 s[8:9], s[14:15]
	s_cbranch_execz .LBB0_540
	v_add_u32_e32 v6, s12, v6
	v_ashrrev_i32_e32 v7, 31, v6
	v_lshl_add_u64 v[6:7], v[6:7], 2, s[0:1]
	global_store_dword v[6:7], v193, off sc1
.LBB0_540:
	s_or_b64 exec, exec, s[8:9]
	s_bcnt1_i32_b64 s8, s[10:11]
	s_min_i32 s9, s13, s8
	v_mbcnt_lo_u32_b32 v6, s56, 0
	s_add_i32 s8, s9, s12
	s_sub_i32 s9, s13, s9
	v_mbcnt_hi_u32_b32 v6, s57, v6
	v_cmp_gt_i32_e32 vcc, s9, v6
	s_and_b64 s[10:11], s[6:7], vcc
	s_and_saveexec_b64 s[6:7], s[10:11]
	s_cbranch_execz .LBB0_542
	v_add_u32_e32 v6, s8, v6
	v_ashrrev_i32_e32 v7, 31, v6
	v_lshl_add_u64 v[6:7], v[6:7], 2, s[0:1]
	global_store_dword v[6:7], v194, off sc1
.LBB0_542:
	s_or_b64 exec, exec, s[6:7]
	s_bcnt1_i32_b64 s6, s[56:57]
	s_min_i32 s7, s9, s6
	v_mbcnt_lo_u32_b32 v6, s54, 0
	s_add_i32 s6, s7, s8
	s_sub_i32 s7, s9, s7
	v_mbcnt_hi_u32_b32 v6, s55, v6
	v_cmp_gt_i32_e32 vcc, s7, v6
	s_and_b64 s[8:9], s[4:5], vcc
	s_and_saveexec_b64 s[4:5], s[8:9]
	s_cbranch_execz .LBB0_544
	v_add_u32_e32 v6, s6, v6
	v_ashrrev_i32_e32 v7, 31, v6
	v_lshl_add_u64 v[6:7], v[6:7], 2, s[0:1]
	global_store_dword v[6:7], v195, off sc1

; __device__ __forceinline__ int mbcnt(unsigned long long m) { return __builtin_amdgcn_mbcnt_hi((unsigned)(m >> 32), __builtin_amdgcn_mbcnt_lo((unsigned)m, 0u)); }
; #define PIN8(m) asm volatile("" : "+s"(m[0]), "+s"(m[1]), "+s"(m[2]), "+s"(m[3]), "+s"(m[4]), "+s"(m[5]), "+s"(m[6]), "+s"(m[7]))
; __device__ __forceinline__ void select_query(const float* sc, int* sel, int ce, int lane) {
;     ...
;     for (int g = 0; g < 8; ++g) if (8 * g < nreg) {
;         unsigned long long m[8];
; #pragma unroll
;         for (int j = 0; j < 8; ++j) m[j] = __ballot(key[8 * g + j] == prefix);
;         PIN8(m);
; #pragma unroll
;         for (int j = 0; j < 8; ++j) { const int rank = mbcnt(m[j]);
;             if (key[8 * g + j] == prefix && rank < need) sel[pos + rank] = lane + 64 * (8 * g + j);
;             const int c = __builtin_popcountll(m[j]); const int take = c < need ? c : need; pos += take; need -= take; }
;         asm volatile("" : "+s"(pos), "+s"(need));
;     }
.LBB0_545:
	v_cmp_eq_u32_e64 s[30:31], v49, v48
	v_cmp_eq_u32_e64 s[24:25], v51, v48
	v_cmp_eq_u32_e64 s[20:21], v5, v48
	v_cmp_eq_u32_e64 s[16:17], v4, v48
	v_cmp_eq_u32_e64 s[14:15], v3, v48
	v_cmp_eq_u32_e64 s[10:11], v2, v48
	v_cmp_eq_u32_e64 s[6:7], v1, v48
	v_cmp_eq_u32_e64 s[52:53], v0, v48
	s_mov_b64 s[12:13], s[14:15]
	s_mov_b64 s[54:55], s[6:7]
	s_mov_b64 s[26:27], s[24:25]
	s_mov_b64 s[18:19], s[16:17]
	s_mov_b64 s[8:9], s[10:11]
	s_mov_b64 s[28:29], s[30:31]
	s_mov_b64 s[4:5], s[52:53]
	s_mov_b64 s[22:23], s[20:21]
	s_nop 0
	v_mbcnt_lo_u32_b32 v0, s28, 0
	v_mbcnt_hi_u32_b32 v0, s29, v0
	v_cmp_gt_i32_e32 vcc, s78, v0
	s_and_b64 s[34:35], s[30:31], vcc
	s_and_saveexec_b64 s[30:31], s[34:35]
	s_cbranch_execz .LBB0_547
	v_add_u32_e32 v0, s72, v0
	v_ashrrev_i32_e32 v1, 31, v0
	v_lshl_add_u64 v[0:1], v[0:1], 2, s[0:1]
	global_store_dword v[0:1], v196, off sc1
.LBB0_547:
	s_or_b64 exec, exec, s[30:31]
	s_bcnt1_i32_b64 s28, s[28:29]
	s_min_i32 s29, s78, s28
	v_mbcnt_lo_u32_b32 v0, s26, 0
	s_add_i32 s28, s29, s72
	s_sub_i32 s29, s78, s29
	v_mbcnt_hi_u32_b32 v0, s27, v0
	v_cmp_gt_i32_e32 vcc, s29, v0
	s_and_b64 s[30:31], s[24:25], vcc
	s_and_saveexec_b64 s[24:25], s[30:31]
	s_cbranch_execz .LBB0_549
	v_add_u32_e32 v0, s28, v0
	v_ashrrev_i32_e32 v1, 31, v0
	v_lshl_add_u64 v[0:1], v[0:1], 2, s[0:1]
	global_store_dword v[0:1], v197, off sc1
.LBB0_549:
	s_or_b64 exec, exec, s[24:25]
	s_bcnt1_i32_b64 s24, s[26:27]
	s_min_i32 s25, s29, s24
	v_mbcnt_lo_u32_b32 v0, s22, 0
	s_add_i32 s24, s25, s28
	s_sub_i32 s25, s29, s25
	v_mbcnt_hi_u32_b32 v0, s23, v0
	v_cmp_gt_i32_e32 vcc, s25, v0
	s_and_b64 s[26:27], s[20:21], vcc
	s_and_saveexec_b64 s[20:21], s[26:27]
	s_cbranch_execz .LBB0_551
	v_add_u32_e32 v0, s24, v0
	v_ashrrev_i32_e32 v1, 31, v0
	v_lshl_add_u64 v[0:1], v[0:1], 2, s[0:1]
	global_store_dword v[0:1], v198, off sc1
.LBB0_551:
	s_or_b64 exec, exec, s[20:21]
	s_bcnt1_i32_b64 s20, s[22:23]
	s_min_i32 s21, s25, s20
	v_mbcnt_lo_u32_b32 v0, s18, 0
	s_add_i32 s20, s21, s24
	s_sub_i32 s21, s25, s21
	v_mbcnt_hi_u32_b32 v0, s19, v0
	v_cmp_gt_i32_e32 vcc, s21, v0
	s_and_b64 s[22:23], s[16:17], vcc
	s_and_saveexec_b64 s[16:17], s[22:23]
	s_cbranch_execz .LBB0_553
	v_add_u32_e32 v0, s20, v0
	v_ashrrev_i32_e32 v1, 31, v0
	v_lshl_add_u64 v[0:1], v[0:1], 2, s[0:1]
	global_store_dword v[0:1], v199, off sc1
.LBB0_553:
	s_or_b64 exec, exec, s[16:17]
	s_bcnt1_i32_b64 s16, s[18:19]
	s_min_i32 s17, s21, s16
	v_mbcnt_lo_u32_b32 v0, s12, 0
	s_add_i32 s16, s17, s20
	s_sub_i32 s17, s21, s17
	v_mbcnt_hi_u32_b32 v0, s13, v0
	v_cmp_gt_i32_e32 vcc, s17, v0
	s_and_b64 s[18:19], s[14:15], vcc
	s_and_saveexec_b64 s[14:15], s[18:19]
	s_cbranch_execz .LBB0_555
	v_add_u32_e32 v0, s16, v0
	v_ashrrev_i32_e32 v1, 31, v0
	v_lshl_add_u64 v[0:1], v[0:1], 2, s[0:1]
	global_store_dword v[0:1], v200, off sc1
.LBB0_555:
	s_or_b64 exec, exec, s[14:15]
	s_bcnt1_i32_b64 s12, s[12:13]
	s_min_i32 s13, s17, s12
	v_mbcnt_lo_u32_b32 v0, s8, 0
	s_add_i32 s12, s13, s16
	s_sub_i32 s13, s17, s13
	v_mbcnt_hi_u32_b32 v0, s9, v0
	v_cmp_gt_i32_e32 vcc, s13, v0
	s_and_b64 s[14:15], s[10:11], vcc
	s_and_saveexec_b64 s[10:11], s[14:15]
	s_cbranch_execz .LBB0_557
	v_add_u32_e32 v0, s12, v0
	v_ashrrev_i32_e32 v1, 31, v0
	v_lshl_add_u64 v[0:1], v[0:1], 2, s[0:1]
	global_store_dword v[0:1], v201, off sc1
.LBB0_557:
	s_or_b64 exec, exec, s[10:11]
	s_bcnt1_i32_b64 s8, s[8:9]
	s_min_i32 s9, s13, s8
	v_mbcnt_lo_u32_b32 v0, s54, 0
	s_add_i32 s8, s9, s12
	s_sub_i32 s9, s13, s9
	v_mbcnt_hi_u32_b32 v0, s55, v0
	v_cmp_gt_i32_e32 vcc, s9, v0
	s_and_b64 s[10:11], s[6:7], vcc
	s_and_saveexec_b64 s[6:7], s[10:11]
	s_cbranch_execz .LBB0_559
	v_add_u32_e32 v0, s8, v0
	v_ashrrev_i32_e32 v1, 31, v0
	v_lshl_add_u64 v[0:1], v[0:1], 2, s[0:1]
	global_store_dword v[0:1], v202, off sc1
.LBB0_559:
	s_or_b64 exec, exec, s[6:7]
	s_bcnt1_i32_b64 s6, s[54:55]
	s_min_i32 s6, s9, s6
	v_mbcnt_lo_u32_b32 v0, s4, 0
	s_sub_i32 s9, s9, s6
	v_mbcnt_hi_u32_b32 v0, s5, v0
	v_cmp_gt_i32_e32 vcc, s9, v0
	s_add_i32 s8, s6, s8
	s_and_b64 s[10:11], s[52:53], vcc
	s_and_saveexec_b64 s[6:7], s[10:11]
	s_cbranch_execz .LBB0_245
	v_add_u32_e32 v0, s8, v0
	v_ashrrev_i32_e32 v1, 31, v0
	v_lshl_add_u64 v[0:1], v[0:1], 2, s[0:1]
	global_store_dword v[0:1], v203, off sc1
	s_branch .LBB0_245
; __device__ __forceinline__ void idx_unit(bf16* QB, float* SC, int* SEL, const float* qg, const float* kg, int b, int tp, LAS unsigned char* wl, int lane, bool do_norm) {
;     ...
;     const int lg = lane >> 4, li = lane & 15;
; #pragma unroll 1
;     for (int a = 0; a < 4; ++a)
; #pragma unroll 1
;         for (int p = 0; p < 5; ++p) {
;             const int col = (p < 4) ? (CQ + (4 * p + lg) * 128) : (CK + lg * 128);
;             bf16* ptr = QB + (row + a) * NBP + col + 8 * li;
;             const u32x4 w = *(const u32x4*)ptr;
;             float v[8] = {bflo(w.x), bfhi(w.x), bflo(w.y), bfhi(w.y), bflo(w.z), bfhi(w.z), bflo(w.w), bfhi(w.w)};
;             float s = 0.f;
; #pragma unroll
;             for (int e = 0; e < 8; ++e) s += v[e] * v[e];
;             s += __shfl_xor(s, 1); s += __shfl_xor(s, 2); s += __shfl_xor(s, 4); s += __shfl_xor(s, 8);
;             const float rstd = (1.0f / sqrtf(s * (1.f / 128.f) + RMS_EPS)) * ((p < 4) ? C2 : 1.f);
;             const float* gp = ((p < 4) ? qg : kg) + 8 * li;
;             const f32x4 g0 = *(const f32x4*)gp, g1 = *(const f32x4*)(gp + 4);
.LBB0_561:
	v_readlane_b32 s66, v253, 47
	v_readlane_b32 s84, v253, 49
	v_readlane_b32 s58, v253, 44
	v_readlane_b32 s67, v253, 48
	v_readlane_b32 s85, v253, 50
	v_readlane_b32 s88, v253, 59
	s_mov_b32 s3, 0
	v_readlane_b32 s59, v253, 45
	v_readlane_b32 s64, v253, 46
	v_readlane_b32 s67, v253, 55
	v_readlane_b32 s85, v253, 56
	v_readlane_b32 s86, v253, 57
	v_readlane_b32 s87, v253, 58
	v_readlane_b32 s89, v253, 60
	s_movk_i32 s92, 0x3000
	s_movk_i32 s93, 0x5a
	s_mov_b32 s94, 0xff800000
	v_readlane_b32 s49, v254, 6
	v_readlane_b32 s11, v250, 33
	s_add_u32 s0, s80, s76
	s_addc_u32 s1, s81, s77
	global_load_dwordx4 v[222:225], v105, s[0:1] offset:16
	global_load_dwordx4 v[218:221], v105, s[0:1]
	s_add_u32 s0, s82, s76
	s_addc_u32 s1, s83, s77
	global_load_dwordx4 v[230:233], v105, s[0:1] offset:16
	global_load_dwordx4 v[226:229], v105, s[0:1]
	s_add_u32 s0, s2, 0
	s_addc_u32 s1, s79, 0
	s_mul_i32 s4, s1, 0x2200
	v_mad_u64_u32 v[0:1], s[0:1], s0, v212, v[118:119]
	v_add_u32_e32 v1, s4, v1
	v_mov_b32_e32 v2, v216
	v_ashrrev_i32_e32 v3, 31, v2
	v_lshl_add_u64 v[14:15], v[2:3], 1, v[0:1]
	global_load_dwordx4 v[16:19], v[14:15], off
	v_add_u32_e32 v2, 0x200, v216
	v_ashrrev_i32_e32 v3, 31, v2
	v_lshl_add_u64 v[14:15], v[2:3], 1, v[0:1]
	global_load_dwordx4 v[20:23], v[14:15], off
	v_add_u32_e32 v2, 0x400, v216
	v_ashrrev_i32_e32 v3, 31, v2
	v_lshl_add_u64 v[14:15], v[2:3], 1, v[0:1]
	global_load_dwordx4 v[24:27], v[14:15], off
	v_add_u32_e32 v2, 0x600, v216
	v_ashrrev_i32_e32 v3, 31, v2
	v_lshl_add_u64 v[14:15], v[2:3], 1, v[0:1]
	global_load_dwordx4 v[28:31], v[14:15], off
	v_add_u32_e32 v2, 0x800, v216
	v_ashrrev_i32_e32 v3, 31, v2
	v_lshl_add_u64 v[14:15], v[2:3], 1, v[0:1]
	global_load_dwordx4 v[32:35], v[14:15], off
	s_add_u32 s0, s2, 1
	s_addc_u32 s1, s79, 0
	s_mul_i32 s4, s1, 0x2200
	v_mad_u64_u32 v[0:1], s[0:1], s0, v212, v[118:119]
	v_add_u32_e32 v1, s4, v1
	v_mov_b32_e32 v2, v216
	v_ashrrev_i32_e32 v3, 31, v2
	v_lshl_add_u64 v[14:15], v[2:3], 1, v[0:1]
	global_load_dwordx4 v[36:39], v[14:15], off
	v_add_u32_e32 v2, 0x200, v216
	v_ashrrev_i32_e32 v3, 31, v2
	v_lshl_add_u64 v[14:15], v[2:3], 1, v[0:1]
	global_load_dwordx4 v[40:43], v[14:15], off
	v_add_u32_e32 v2, 0x400, v216
	v_ashrrev_i32_e32 v3, 31, v2
	v_lshl_add_u64 v[14:15], v[2:3], 1, v[0:1]
	global_load_dwordx4 v[44:47], v[14:15], off
	v_add_u32_e32 v2, 0x600, v216
	v_ashrrev_i32_e32 v3, 31, v2
	v_lshl_add_u64 v[14:15], v[2:3], 1, v[0:1]
	global_load_dwordx4 v[48:51], v[14:15], off
	v_add_u32_e32 v2, 0x800, v216
	v_ashrrev_i32_e32 v3, 31, v2
	v_lshl_add_u64 v[14:15], v[2:3], 1, v[0:1]
	global_load_dwordx4 v[52:55], v[14:15], off
	s_add_u32 s0, s2, 2
	s_addc_u32 s1, s79, 0
	s_mul_i32 s4, s1, 0x2200
	v_mad_u64_u32 v[0:1], s[0:1], s0, v212, v[118:119]
	v_add_u32_e32 v1, s4, v1
	v_mov_b32_e32 v2, v216
	v_ashrrev_i32_e32 v3, 31, v2
	v_lshl_add_u64 v[14:15], v[2:3], 1, v[0:1]
	global_load_dwordx4 v[56:59], v[14:15], off
	v_add_u32_e32 v2, 0x200, v216
	v_ashrrev_i32_e32 v3, 31, v2
	v_lshl_add_u64 v[14:15], v[2:3], 1, v[0:1]
	global_load_dwordx4 v[60:63], v[14:15], off
	v_add_u32_e32 v2, 0x400, v216
	v_ashrrev_i32_e32 v3, 31, v2
	v_lshl_add_u64 v[14:15], v[2:3], 1, v[0:1]
	global_load_dwordx4 v[64:67], v[14:15], off
	v_add_u32_e32 v2, 0x600, v216
	v_ashrrev_i32_e32 v3, 31, v2
	v_lshl_add_u64 v[14:15], v[2:3], 1, v[0:1]
	global_load_dwordx4 v[68:71], v[14:15], off
	v_add_u32_e32 v2, 0x800, v216
	v_ashrrev_i32_e32 v3, 31, v2
	v_lshl_add_u64 v[14:15], v[2:3], 1, v[0:1]
	global_load_dwordx4 v[72:75], v[14:15], off
	s_add_u32 s0, s2, 3
	s_addc_u32 s1, s79, 0
	s_mul_i32 s4, s1, 0x2200
	v_mad_u64_u32 v[0:1], s[0:1], s0, v212, v[118:119]
	v_add_u32_e32 v1, s4, v1
	v_mov_b32_e32 v2, v216
	v_ashrrev_i32_e32 v3, 31, v2
	v_lshl_add_u64 v[14:15], v[2:3], 1, v[0:1]
	global_load_dwordx4 v[76:79], v[14:15], off
	v_add_u32_e32 v2, 0x200, v216
	v_ashrrev_i32_e32 v3, 31, v2
	v_lshl_add_u64 v[14:15], v[2:3], 1, v[0:1]
	global_load_dwordx4 v[80:83], v[14:15], off
	v_add_u32_e32 v2, 0x400, v216
	v_ashrrev_i32_e32 v3, 31, v2
	v_lshl_add_u64 v[14:15], v[2:3], 1, v[0:1]
	global_load_dwordx4 v[84:87], v[14:15], off
	v_add_u32_e32 v2, 0x600, v216
	v_ashrrev_i32_e32 v3, 31, v2
	v_lshl_add_u64 v[14:15], v[2:3], 1, v[0:1]
	global_load_dwordx4 v[88:91], v[14:15], off
	v_add_u32_e32 v2, 0x800, v216
	v_ashrrev_i32_e32 v3, 31, v2
	v_lshl_add_u64 v[14:15], v[2:3], 1, v[0:1]
	global_load_dwordx4 v[92:95], v[14:15], off
	s_add_u32 s0, s2, 0
	s_addc_u32 s1, s79, 0
	s_mul_i32 s4, s1, 0x2200
	v_mad_u64_u32 v[0:1], s[0:1], s0, v212, v[118:119]
	v_add_u32_e32 v1, s4, v1
	s_waitcnt vmcnt(19)
	v_mov_b32_e32 v217, v211
	v_lshlrev_b32_e32 v234, 16, v16
	v_and_b32_e32 v16, 0xffff0000, v16
	v_mul_f32_e32 v238, v16, v16
	v_lshlrev_b32_e32 v235, 16, v17
	v_fmac_f32_e32 v238, v234, v234
	v_and_b32_e32 v17, 0xffff0000, v17
	v_fmac_f32_e32 v238, v235, v235
	v_lshlrev_b32_e32 v236, 16, v18
	v_fmac_f32_e32 v238, v17, v17
	v_and_b32_e32 v18, 0xffff0000, v18
	v_fmac_f32_e32 v238, v236, v236
	v_lshlrev_b32_e32 v237, 16, v19
	v_fmac_f32_e32 v238, v18, v18
	v_and_b32_e32 v19, 0xffff0000, v19
	v_fmac_f32_e32 v238, v237, v237
	v_fmac_f32_e32 v238, v19, v19
	ds_bpermute_b32 v239, v204, v238
	s_waitcnt lgkmcnt(0)
	v_add_f32_e32 v238, v238, v239
	ds_bpermute_b32 v239, v205, v238
	s_waitcnt lgkmcnt(0)
	v_add_f32_e32 v238, v238, v239
	ds_bpermute_b32 v239, v214, v238
	s_waitcnt lgkmcnt(0)
	v_add_f32_e32 v238, v238, v239
	ds_bpermute_b32 v239, v215, v238
	s_waitcnt lgkmcnt(0)
; __device__ __forceinline__ unsigned pk2(float lo, float hi) { return pg8::cvt_pk_bf16(lo, hi); }
; __device__ __forceinline__ void idx_unit(bf16* QB, float* SC, int* SEL, const float* qg, const float* kg, int b, int tp, LAS unsigned char* wl, int lane, bool do_norm) {
;     ...
;     for (int a = 0; a < 4; ++a)
; #pragma unroll 1
;         for (int p = 0; p < 5; ++p) {
;             const int col = (p < 4) ? (CQ + (4 * p + lg) * 128) : (CK + lg * 128);
;             bf16* ptr = QB + (row + a) * NBP + col + 8 * li;
;             const u32x4 w = *(const u32x4*)ptr;
;             float v[8] = {bflo(w.x), bfhi(w.x), bflo(w.y), bfhi(w.y), bflo(w.z), bfhi(w.z), bflo(w.w), bfhi(w.w)};
;             float s = 0.f;
; #pragma unroll
;             for (int e = 0; e < 8; ++e) s += v[e] * v[e];
;             s += __shfl_xor(s, 1); s += __shfl_xor(s, 2); s += __shfl_xor(s, 4); s += __shfl_xor(s, 8);
;             const float rstd = (1.0f / sqrtf(s * (1.f / 128.f) + RMS_EPS)) * ((p < 4) ? C2 : 1.f);
;             const float* gp = ((p < 4) ? qg : kg) + 8 * li;
;             const f32x4 g0 = *(const f32x4*)gp, g1 = *(const f32x4*)(gp + 4);
;             u32x4 o; o.x = pk2(v[0] * rstd * g0.x, v[1] * rstd * g0.y); o.y = pk2(v[2] * rstd * g0.z, v[3] * rstd * g0.w);
;             o.z = pk2(v[4] * rstd * g1.x, v[5] * rstd * g1.y); o.w = pk2(v[6] * rstd * g1.z, v[7] * rstd * g1.w);
;             *(u32x4*)ptr = o;
;         }
	v_add_f32_e32 v238, v238, v239
	v_fmamk_f32 v238, v238, 0x3c000000, v208
	v_mul_f32_e32 v239, 0x4f800000, v238
	v_cmp_gt_f32_e32 vcc, s33, v238
	s_nop 1
	v_cndmask_b32_e32 v238, v238, v239, vcc
	v_sqrt_f32_e32 v239, v238
	s_nop 0
	v_add_u32_e32 v240, -1, v239
	v_add_u32_e32 v241, 1, v239
	v_fma_f32 v242, -v240, v239, v238
	v_fma_f32 v243, -v241, v239, v238
	v_cmp_ge_f32_e64 s[0:1], 0, v242
	s_nop 1
	v_cndmask_b32_e64 v239, v239, v240, s[0:1]
	v_cmp_lt_f32_e64 s[0:1], 0, v243
	s_nop 1
	v_cndmask_b32_e64 v239, v239, v241, s[0:1]
	v_mul_f32_e32 v240, 0x37800000, v239
	v_cndmask_b32_e32 v239, v239, v240, vcc
	v_cmp_class_f32_e32 vcc, v238, v209
	s_nop 1
	v_cndmask_b32_e32 v238, v239, v238, vcc
	v_div_scale_f32 v239, s[0:1], v238, v238, 1.0
	v_rcp_f32_e32 v241, v239
	v_div_scale_f32 v240, vcc, 1.0, v238, 1.0
	v_fma_f32 v242, -v239, v241, 1.0
	v_fmac_f32_e32 v241, v242, v241
	v_mul_f32_e32 v242, v240, v241
	v_fma_f32 v243, -v239, v242, v240
	v_fmac_f32_e32 v242, v243, v241
	v_fma_f32 v239, -v239, v242, v240
	v_div_fmas_f32 v239, v239, v241, v242
	v_div_fixup_f32 v238, v239, v238, 1.0
	v_mul_f32_e32 v217, v217, v238
	v_mul_f32_e32 v16, v217, v16
	v_mul_f32_e32 v17, v217, v17
	v_mul_f32_e32 v18, v217, v18
	v_mul_f32_e32 v19, v217, v19
	v_mul_f32_e32 v234, v217, v234
	v_mul_f32_e32 v235, v217, v235
	v_mul_f32_e32 v236, v217, v236
	v_mul_f32_e32 v237, v217, v237
	v_mul_f32_e32 v16, v219, v16
	v_mul_f32_e32 v17, v221, v17
	v_mul_f32_e32 v18, v223, v18
	v_mul_f32_e32 v19, v225, v19
	v_mul_f32_e32 v244, v218, v234
	v_mul_f32_e32 v245, v220, v235
	v_mul_f32_e32 v246, v222, v236
	v_mul_f32_e32 v247, v224, v237
	v_cvt_pk_bf16_f32 v16, v244, v16
	v_cvt_pk_bf16_f32 v17, v245, v17
	v_cvt_pk_bf16_f32 v18, v246, v18
	v_cvt_pk_bf16_f32 v19, v247, v19
	v_mov_b32_e32 v2, v216
	v_ashrrev_i32_e32 v3, 31, v2
	v_lshl_add_u64 v[14:15], v[2:3], 1, v[0:1]
	global_store_dwordx4 v[14:15], v[16:19], off sc1
	s_waitcnt vmcnt(19)
	v_mov_b32_e32 v217, v211
	v_lshlrev_b32_e32 v234, 16, v20
	v_and_b32_e32 v20, 0xffff0000, v20
	v_mul_f32_e32 v238, v20, v20
	v_lshlrev_b32_e32 v235, 16, v21
	v_fmac_f32_e32 v238, v234, v234
	v_and_b32_e32 v21, 0xffff0000, v21
	v_fmac_f32_e32 v238, v235, v235
	v_lshlrev_b32_e32 v236, 16, v22
	v_fmac_f32_e32 v238, v21, v21
	v_and_b32_e32 v22, 0xffff0000, v22
	v_fmac_f32_e32 v238, v236, v236
	v_lshlrev_b32_e32 v237, 16, v23
	v_fmac_f32_e32 v238, v22, v22
	v_and_b32_e32 v23, 0xffff0000, v23
	v_fmac_f32_e32 v238, v237, v237
	v_fmac_f32_e32 v238, v23, v23
	ds_bpermute_b32 v239, v204, v238
	s_waitcnt lgkmcnt(0)
	v_add_f32_e32 v238, v238, v239
	ds_bpermute_b32 v239, v205, v238
	s_waitcnt lgkmcnt(0)
	v_add_f32_e32 v238, v238, v239
	ds_bpermute_b32 v239, v214, v238
	s_waitcnt lgkmcnt(0)
	v_add_f32_e32 v238, v238, v239
	ds_bpermute_b32 v239, v215, v238
	s_waitcnt lgkmcnt(0)
	v_add_f32_e32 v238, v238, v239
	v_fmamk_f32 v238, v238, 0x3c000000, v208
	v_mul_f32_e32 v239, 0x4f800000, v238
	v_cmp_gt_f32_e32 vcc, s33, v238
	s_nop 1
	v_cndmask_b32_e32 v238, v238, v239, vcc
	v_sqrt_f32_e32 v239, v238
	s_nop 0
	v_add_u32_e32 v240, -1, v239
	v_add_u32_e32 v241, 1, v239
	v_fma_f32 v242, -v240, v239, v238
	v_fma_f32 v243, -v241, v239, v238
	v_cmp_ge_f32_e64 s[0:1], 0, v242
	s_nop 1
	v_cndmask_b32_e64 v239, v239, v240, s[0:1]
	v_cmp_lt_f32_e64 s[0:1], 0, v243
	s_nop 1
	v_cndmask_b32_e64 v239, v239, v241, s[0:1]
	v_mul_f32_e32 v240, 0x37800000, v239
	v_cndmask_b32_e32 v239, v239, v240, vcc
	v_cmp_class_f32_e32 vcc, v238, v209
	s_nop 1
	v_cndmask_b32_e32 v238, v239, v238, vcc
	v_div_scale_f32 v239, s[0:1], v238, v238, 1.0
	v_rcp_f32_e32 v241, v239
	v_div_scale_f32 v240, vcc, 1.0, v238, 1.0
	v_fma_f32 v242, -v239, v241, 1.0
	v_fmac_f32_e32 v241, v242, v241
	v_mul_f32_e32 v242, v240, v241
	v_fma_f32 v243, -v239, v242, v240
	v_fmac_f32_e32 v242, v243, v241
	v_fma_f32 v239, -v239, v242, v240
	v_div_fmas_f32 v239, v239, v241, v242
	v_div_fixup_f32 v238, v239, v238, 1.0
	v_mul_f32_e32 v217, v217, v238
	v_mul_f32_e32 v20, v217, v20
	v_mul_f32_e32 v21, v217, v21
	v_mul_f32_e32 v22, v217, v22
	v_mul_f32_e32 v23, v217, v23
	v_mul_f32_e32 v234, v217, v234
	v_mul_f32_e32 v235, v217, v235
	v_mul_f32_e32 v236, v217, v236
	v_mul_f32_e32 v237, v217, v237
	v_mul_f32_e32 v20, v219, v20
	v_mul_f32_e32 v21, v221, v21
	v_mul_f32_e32 v22, v223, v22
	v_mul_f32_e32 v23, v225, v23
	v_mul_f32_e32 v244, v218, v234
	v_mul_f32_e32 v245, v220, v235
	v_mul_f32_e32 v246, v222, v236
	v_mul_f32_e32 v247, v224, v237
	v_cvt_pk_bf16_f32 v20, v244, v20
	v_cvt_pk_bf16_f32 v21, v245, v21
	v_cvt_pk_bf16_f32 v22, v246, v22
	v_cvt_pk_bf16_f32 v23, v247, v23
	v_add_u32_e32 v2, 0x200, v216
	v_ashrrev_i32_e32 v3, 31, v2
	v_lshl_add_u64 v[14:15], v[2:3], 1, v[0:1]
	global_store_dwordx4 v[14:15], v[20:23], off sc1
	s_waitcnt vmcnt(19)
	v_mov_b32_e32 v217, v211
	v_lshlrev_b32_e32 v234, 16, v24
	v_and_b32_e32 v24, 0xffff0000, v24
	v_mul_f32_e32 v238, v24, v24
	v_lshlrev_b32_e32 v235, 16, v25
	v_fmac_f32_e32 v238, v234, v234
	v_and_b32_e32 v25, 0xffff0000, v25
	v_fmac_f32_e32 v238, v235, v235
	v_lshlrev_b32_e32 v236, 16, v26
	v_fmac_f32_e32 v238, v25, v25
	v_and_b32_e32 v26, 0xffff0000, v26
	v_fmac_f32_e32 v238, v236, v236
	v_lshlrev_b32_e32 v237, 16, v27
	v_fmac_f32_e32 v238, v26, v26
	v_and_b32_e32 v27, 0xffff0000, v27
	v_fmac_f32_e32 v238, v237, v237
	v_fmac_f32_e32 v238, v27, v27
	ds_bpermute_b32 v239, v204, v238
	s_waitcnt lgkmcnt(0)
	v_add_f32_e32 v238, v238, v239
	ds_bpermute_b32 v239, v205, v238
	s_waitcnt lgkmcnt(0)
	v_add_f32_e32 v238, v238, v239
	ds_bpermute_b32 v239, v214, v238
	s_waitcnt lgkmcnt(0)
	v_add_f32_e32 v238, v238, v239
	ds_bpermute_b32 v239, v215, v238
	s_waitcnt lgkmcnt(0)
; __device__ __forceinline__ unsigned pk2(float lo, float hi) { return pg8::cvt_pk_bf16(lo, hi); }
; __device__ __forceinline__ void idx_unit(bf16* QB, float* SC, int* SEL, const float* qg, const float* kg, int b, int tp, LAS unsigned char* wl, int lane, bool do_norm) {
;     ...
;     for (int a = 0; a < 4; ++a)
; #pragma unroll 1
;         for (int p = 0; p < 5; ++p) {
;             const int col = (p < 4) ? (CQ + (4 * p + lg) * 128) : (CK + lg * 128);
;             bf16* ptr = QB + (row + a) * NBP + col + 8 * li;
;             const u32x4 w = *(const u32x4*)ptr;
;             float v[8] = {bflo(w.x), bfhi(w.x), bflo(w.y), bfhi(w.y), bflo(w.z), bfhi(w.z), bflo(w.w), bfhi(w.w)};
;             float s = 0.f;
; #pragma unroll
;             for (int e = 0; e < 8; ++e) s += v[e] * v[e];
;             s += __shfl_xor(s, 1); s += __shfl_xor(s, 2); s += __shfl_xor(s, 4); s += __shfl_xor(s, 8);
;             const float rstd = (1.0f / sqrtf(s * (1.f / 128.f) + RMS_EPS)) * ((p < 4) ? C2 : 1.f);
;             const float* gp = ((p < 4) ? qg : kg) + 8 * li;
;             const f32x4 g0 = *(const f32x4*)gp, g1 = *(const f32x4*)(gp + 4);
;             u32x4 o; o.x = pk2(v[0] * rstd * g0.x, v[1] * rstd * g0.y); o.y = pk2(v[2] * rstd * g0.z, v[3] * rstd * g0.w);
;             o.z = pk2(v[4] * rstd * g1.x, v[5] * rstd * g1.y); o.w = pk2(v[6] * rstd * g1.z, v[7] * rstd * g1.w);
;             *(u32x4*)ptr = o;
;         }
	v_add_f32_e32 v238, v238, v239
	v_fmamk_f32 v238, v238, 0x3c000000, v208
	v_mul_f32_e32 v239, 0x4f800000, v238
	v_cmp_gt_f32_e32 vcc, s33, v238
	s_nop 1
	v_cndmask_b32_e32 v238, v238, v239, vcc
	v_sqrt_f32_e32 v239, v238
	s_nop 0
	v_add_u32_e32 v240, -1, v239
	v_add_u32_e32 v241, 1, v239
	v_fma_f32 v242, -v240, v239, v238
	v_fma_f32 v243, -v241, v239, v238
	v_cmp_ge_f32_e64 s[0:1], 0, v242
	s_nop 1
	v_cndmask_b32_e64 v239, v239, v240, s[0:1]
	v_cmp_lt_f32_e64 s[0:1], 0, v243
	s_nop 1
	v_cndmask_b32_e64 v239, v239, v241, s[0:1]
	v_mul_f32_e32 v240, 0x37800000, v239
	v_cndmask_b32_e32 v239, v239, v240, vcc
	v_cmp_class_f32_e32 vcc, v238, v209
	s_nop 1
	v_cndmask_b32_e32 v238, v239, v238, vcc
	v_div_scale_f32 v239, s[0:1], v238, v238, 1.0
	v_rcp_f32_e32 v241, v239
	v_div_scale_f32 v240, vcc, 1.0, v238, 1.0
	v_fma_f32 v242, -v239, v241, 1.0
	v_fmac_f32_e32 v241, v242, v241
	v_mul_f32_e32 v242, v240, v241
	v_fma_f32 v243, -v239, v242, v240
	v_fmac_f32_e32 v242, v243, v241
	v_fma_f32 v239, -v239, v242, v240
	v_div_fmas_f32 v239, v239, v241, v242
	v_div_fixup_f32 v238, v239, v238, 1.0
	v_mul_f32_e32 v217, v217, v238
	v_mul_f32_e32 v24, v217, v24
	v_mul_f32_e32 v25, v217, v25
	v_mul_f32_e32 v26, v217, v26
	v_mul_f32_e32 v27, v217, v27
	v_mul_f32_e32 v234, v217, v234
	v_mul_f32_e32 v235, v217, v235
	v_mul_f32_e32 v236, v217, v236
	v_mul_f32_e32 v237, v217, v237
	v_mul_f32_e32 v24, v219, v24
	v_mul_f32_e32 v25, v221, v25
	v_mul_f32_e32 v26, v223, v26
	v_mul_f32_e32 v27, v225, v27
	v_mul_f32_e32 v244, v218, v234
	v_mul_f32_e32 v245, v220, v235
	v_mul_f32_e32 v246, v222, v236
	v_mul_f32_e32 v247, v224, v237
	v_cvt_pk_bf16_f32 v24, v244, v24
	v_cvt_pk_bf16_f32 v25, v245, v25
	v_cvt_pk_bf16_f32 v26, v246, v26
	v_cvt_pk_bf16_f32 v27, v247, v27
	v_add_u32_e32 v2, 0x400, v216
	v_ashrrev_i32_e32 v3, 31, v2
	v_lshl_add_u64 v[14:15], v[2:3], 1, v[0:1]
	global_store_dwordx4 v[14:15], v[24:27], off sc1
	s_waitcnt vmcnt(19)
	v_mov_b32_e32 v217, v211
	v_lshlrev_b32_e32 v234, 16, v28
	v_and_b32_e32 v28, 0xffff0000, v28
	v_mul_f32_e32 v238, v28, v28
	v_lshlrev_b32_e32 v235, 16, v29
	v_fmac_f32_e32 v238, v234, v234
	v_and_b32_e32 v29, 0xffff0000, v29
	v_fmac_f32_e32 v238, v235, v235
	v_lshlrev_b32_e32 v236, 16, v30
	v_fmac_f32_e32 v238, v29, v29
	v_and_b32_e32 v30, 0xffff0000, v30
	v_fmac_f32_e32 v238, v236, v236
	v_lshlrev_b32_e32 v237, 16, v31
	v_fmac_f32_e32 v238, v30, v30
	v_and_b32_e32 v31, 0xffff0000, v31
	v_fmac_f32_e32 v238, v237, v237
	v_fmac_f32_e32 v238, v31, v31
	ds_bpermute_b32 v239, v204, v238
	s_waitcnt lgkmcnt(0)
	v_add_f32_e32 v238, v238, v239
	ds_bpermute_b32 v239, v205, v238
	s_waitcnt lgkmcnt(0)
	v_add_f32_e32 v238, v238, v239
	ds_bpermute_b32 v239, v214, v238
	s_waitcnt lgkmcnt(0)
	v_add_f32_e32 v238, v238, v239
	ds_bpermute_b32 v239, v215, v238
	s_waitcnt lgkmcnt(0)
	v_add_f32_e32 v238, v238, v239
	v_fmamk_f32 v238, v238, 0x3c000000, v208
	v_mul_f32_e32 v239, 0x4f800000, v238
	v_cmp_gt_f32_e32 vcc, s33, v238
	s_nop 1
	v_cndmask_b32_e32 v238, v238, v239, vcc
	v_sqrt_f32_e32 v239, v238
	s_nop 0
	v_add_u32_e32 v240, -1, v239
	v_add_u32_e32 v241, 1, v239
	v_fma_f32 v242, -v240, v239, v238
	v_fma_f32 v243, -v241, v239, v238
	v_cmp_ge_f32_e64 s[0:1], 0, v242
	s_nop 1
	v_cndmask_b32_e64 v239, v239, v240, s[0:1]
	v_cmp_lt_f32_e64 s[0:1], 0, v243
	s_nop 1
	v_cndmask_b32_e64 v239, v239, v241, s[0:1]
	v_mul_f32_e32 v240, 0x37800000, v239
	v_cndmask_b32_e32 v239, v239, v240, vcc
	v_cmp_class_f32_e32 vcc, v238, v209
	s_nop 1
	v_cndmask_b32_e32 v238, v239, v238, vcc
	v_div_scale_f32 v239, s[0:1], v238, v238, 1.0
	v_rcp_f32_e32 v241, v239
	v_div_scale_f32 v240, vcc, 1.0, v238, 1.0
	v_fma_f32 v242, -v239, v241, 1.0
	v_fmac_f32_e32 v241, v242, v241
	v_mul_f32_e32 v242, v240, v241
	v_fma_f32 v243, -v239, v242, v240
	v_fmac_f32_e32 v242, v243, v241
	v_fma_f32 v239, -v239, v242, v240
	v_div_fmas_f32 v239, v239, v241, v242
	v_div_fixup_f32 v238, v239, v238, 1.0
	v_mul_f32_e32 v217, v217, v238
	v_mul_f32_e32 v28, v217, v28
	v_mul_f32_e32 v29, v217, v29
	v_mul_f32_e32 v30, v217, v30
	v_mul_f32_e32 v31, v217, v31
	v_mul_f32_e32 v234, v217, v234
	v_mul_f32_e32 v235, v217, v235
	v_mul_f32_e32 v236, v217, v236
	v_mul_f32_e32 v237, v217, v237
	v_mul_f32_e32 v28, v219, v28
	v_mul_f32_e32 v29, v221, v29
	v_mul_f32_e32 v30, v223, v30
	v_mul_f32_e32 v31, v225, v31
	v_mul_f32_e32 v244, v218, v234
	v_mul_f32_e32 v245, v220, v235
	v_mul_f32_e32 v246, v222, v236
	v_mul_f32_e32 v247, v224, v237
	v_cvt_pk_bf16_f32 v28, v244, v28
	v_cvt_pk_bf16_f32 v29, v245, v29
	v_cvt_pk_bf16_f32 v30, v246, v30
	v_cvt_pk_bf16_f32 v31, v247, v31
	v_add_u32_e32 v2, 0x600, v216
	v_ashrrev_i32_e32 v3, 31, v2
	v_lshl_add_u64 v[14:15], v[2:3], 1, v[0:1]
	global_store_dwordx4 v[14:15], v[28:31], off sc1
	s_waitcnt vmcnt(19)
	v_mov_b32_e32 v217, 1.0
	v_lshlrev_b32_e32 v234, 16, v32
	v_and_b32_e32 v32, 0xffff0000, v32
	v_mul_f32_e32 v238, v32, v32
	v_lshlrev_b32_e32 v235, 16, v33
	v_fmac_f32_e32 v238, v234, v234
	v_and_b32_e32 v33, 0xffff0000, v33
	v_fmac_f32_e32 v238, v235, v235
	v_lshlrev_b32_e32 v236, 16, v34
	v_fmac_f32_e32 v238, v33, v33
	v_and_b32_e32 v34, 0xffff0000, v34
	v_fmac_f32_e32 v238, v236, v236
	v_lshlrev_b32_e32 v237, 16, v35
	v_fmac_f32_e32 v238, v34, v34
	v_and_b32_e32 v35, 0xffff0000, v35
	v_fmac_f32_e32 v238, v237, v237
	v_fmac_f32_e32 v238, v35, v35
	ds_bpermute_b32 v239, v204, v238
	s_waitcnt lgkmcnt(0)
	v_add_f32_e32 v238, v238, v239
	ds_bpermute_b32 v239, v205, v238
	s_waitcnt lgkmcnt(0)
	v_add_f32_e32 v238, v238, v239
	ds_bpermute_b32 v239, v214, v238
	s_waitcnt lgkmcnt(0)
	v_add_f32_e32 v238, v238, v239
	ds_bpermute_b32 v239, v215, v238
	s_waitcnt lgkmcnt(0)
; __device__ __forceinline__ unsigned pk2(float lo, float hi) { return pg8::cvt_pk_bf16(lo, hi); }
; __device__ __forceinline__ void idx_unit(bf16* QB, float* SC, int* SEL, const float* qg, const float* kg, int b, int tp, LAS unsigned char* wl, int lane, bool do_norm) {
;     ...
;     for (int a = 0; a < 4; ++a)
; #pragma unroll 1
;         for (int p = 0; p < 5; ++p) {
;             const int col = (p < 4) ? (CQ + (4 * p + lg) * 128) : (CK + lg * 128);
;             bf16* ptr = QB + (row + a) * NBP + col + 8 * li;
;             const u32x4 w = *(const u32x4*)ptr;
;             float v[8] = {bflo(w.x), bfhi(w.x), bflo(w.y), bfhi(w.y), bflo(w.z), bfhi(w.z), bflo(w.w), bfhi(w.w)};
;             float s = 0.f;
; #pragma unroll
;             for (int e = 0; e < 8; ++e) s += v[e] * v[e];
;             s += __shfl_xor(s, 1); s += __shfl_xor(s, 2); s += __shfl_xor(s, 4); s += __shfl_xor(s, 8);
;             const float rstd = (1.0f / sqrtf(s * (1.f / 128.f) + RMS_EPS)) * ((p < 4) ? C2 : 1.f);
;             const float* gp = ((p < 4) ? qg : kg) + 8 * li;
;             const f32x4 g0 = *(const f32x4*)gp, g1 = *(const f32x4*)(gp + 4);
;             u32x4 o; o.x = pk2(v[0] * rstd * g0.x, v[1] * rstd * g0.y); o.y = pk2(v[2] * rstd * g0.z, v[3] * rstd * g0.w);
;             o.z = pk2(v[4] * rstd * g1.x, v[5] * rstd * g1.y); o.w = pk2(v[6] * rstd * g1.z, v[7] * rstd * g1.w);
;             *(u32x4*)ptr = o;
;         }
	v_add_f32_e32 v238, v238, v239
	v_fmamk_f32 v238, v238, 0x3c000000, v208
	v_mul_f32_e32 v239, 0x4f800000, v238
	v_cmp_gt_f32_e32 vcc, s33, v238
	s_nop 1
	v_cndmask_b32_e32 v238, v238, v239, vcc
	v_sqrt_f32_e32 v239, v238
	s_nop 0
	v_add_u32_e32 v240, -1, v239
	v_add_u32_e32 v241, 1, v239
	v_fma_f32 v242, -v240, v239, v238
	v_fma_f32 v243, -v241, v239, v238
	v_cmp_ge_f32_e64 s[0:1], 0, v242
	s_nop 1
	v_cndmask_b32_e64 v239, v239, v240, s[0:1]
	v_cmp_lt_f32_e64 s[0:1], 0, v243
	s_nop 1
	v_cndmask_b32_e64 v239, v239, v241, s[0:1]
	v_mul_f32_e32 v240, 0x37800000, v239
	v_cndmask_b32_e32 v239, v239, v240, vcc
	v_cmp_class_f32_e32 vcc, v238, v209
	s_nop 1
	v_cndmask_b32_e32 v238, v239, v238, vcc
	v_div_scale_f32 v239, s[0:1], v238, v238, 1.0
	v_rcp_f32_e32 v241, v239
	v_div_scale_f32 v240, vcc, 1.0, v238, 1.0
	v_fma_f32 v242, -v239, v241, 1.0
	v_fmac_f32_e32 v241, v242, v241
	v_mul_f32_e32 v242, v240, v241
	v_fma_f32 v243, -v239, v242, v240
	v_fmac_f32_e32 v242, v243, v241
	v_fma_f32 v239, -v239, v242, v240
	v_div_fmas_f32 v239, v239, v241, v242
	v_div_fixup_f32 v238, v239, v238, 1.0
	v_mul_f32_e32 v217, v217, v238
	v_mul_f32_e32 v32, v217, v32
	v_mul_f32_e32 v33, v217, v33
	v_mul_f32_e32 v34, v217, v34
	v_mul_f32_e32 v35, v217, v35
	v_mul_f32_e32 v234, v217, v234
	v_mul_f32_e32 v235, v217, v235
	v_mul_f32_e32 v236, v217, v236
	v_mul_f32_e32 v237, v217, v237
	v_mul_f32_e32 v32, v227, v32
	v_mul_f32_e32 v33, v229, v33
	v_mul_f32_e32 v34, v231, v34
	v_mul_f32_e32 v35, v233, v35
	v_mul_f32_e32 v244, v226, v234
	v_mul_f32_e32 v245, v228, v235
	v_mul_f32_e32 v246, v230, v236
	v_mul_f32_e32 v247, v232, v237
	v_cvt_pk_bf16_f32 v32, v244, v32
	v_cvt_pk_bf16_f32 v33, v245, v33
	v_cvt_pk_bf16_f32 v34, v246, v34
	v_cvt_pk_bf16_f32 v35, v247, v35
	v_add_u32_e32 v2, 0x800, v216
	v_ashrrev_i32_e32 v3, 31, v2
	v_lshl_add_u64 v[14:15], v[2:3], 1, v[0:1]
	global_store_dwordx4 v[14:15], v[32:35], off sc1
	s_add_u32 s0, s2, 1
	s_addc_u32 s1, s79, 0
	s_mul_i32 s4, s1, 0x2200
	v_mad_u64_u32 v[0:1], s[0:1], s0, v212, v[118:119]
	v_add_u32_e32 v1, s4, v1
	s_waitcnt vmcnt(19)
	v_mov_b32_e32 v217, v211
	v_lshlrev_b32_e32 v234, 16, v36
	v_and_b32_e32 v36, 0xffff0000, v36
	v_mul_f32_e32 v238, v36, v36
	v_lshlrev_b32_e32 v235, 16, v37
	v_fmac_f32_e32 v238, v234, v234
	v_and_b32_e32 v37, 0xffff0000, v37
	v_fmac_f32_e32 v238, v235, v235
	v_lshlrev_b32_e32 v236, 16, v38
	v_fmac_f32_e32 v238, v37, v37
	v_and_b32_e32 v38, 0xffff0000, v38
	v_fmac_f32_e32 v238, v236, v236
	v_lshlrev_b32_e32 v237, 16, v39
	v_fmac_f32_e32 v238, v38, v38
	v_and_b32_e32 v39, 0xffff0000, v39
	v_fmac_f32_e32 v238, v237, v237
	v_fmac_f32_e32 v238, v39, v39
	ds_bpermute_b32 v239, v204, v238
	s_waitcnt lgkmcnt(0)
	v_add_f32_e32 v238, v238, v239
	ds_bpermute_b32 v239, v205, v238
	s_waitcnt lgkmcnt(0)
	v_add_f32_e32 v238, v238, v239
	ds_bpermute_b32 v239, v214, v238
	s_waitcnt lgkmcnt(0)
	v_add_f32_e32 v238, v238, v239
	ds_bpermute_b32 v239, v215, v238
	s_waitcnt lgkmcnt(0)
	v_add_f32_e32 v238, v238, v239
	v_fmamk_f32 v238, v238, 0x3c000000, v208
	v_mul_f32_e32 v239, 0x4f800000, v238
	v_cmp_gt_f32_e32 vcc, s33, v238
	s_nop 1
	v_cndmask_b32_e32 v238, v238, v239, vcc
	v_sqrt_f32_e32 v239, v238
	s_nop 0
	v_add_u32_e32 v240, -1, v239
	v_add_u32_e32 v241, 1, v239
	v_fma_f32 v242, -v240, v239, v238
	v_fma_f32 v243, -v241, v239, v238
	v_cmp_ge_f32_e64 s[0:1], 0, v242
	s_nop 1
	v_cndmask_b32_e64 v239, v239, v240, s[0:1]
	v_cmp_lt_f32_e64 s[0:1], 0, v243
	s_nop 1
	v_cndmask_b32_e64 v239, v239, v241, s[0:1]
	v_mul_f32_e32 v240, 0x37800000, v239
	v_cndmask_b32_e32 v239, v239, v240, vcc
	v_cmp_class_f32_e32 vcc, v238, v209
	s_nop 1
	v_cndmask_b32_e32 v238, v239, v238, vcc
	v_div_scale_f32 v239, s[0:1], v238, v238, 1.0
	v_rcp_f32_e32 v241, v239
	v_div_scale_f32 v240, vcc, 1.0, v238, 1.0
	v_fma_f32 v242, -v239, v241, 1.0
	v_fmac_f32_e32 v241, v242, v241
	v_mul_f32_e32 v242, v240, v241
	v_fma_f32 v243, -v239, v242, v240
	v_fmac_f32_e32 v242, v243, v241
	v_fma_f32 v239, -v239, v242, v240
	v_div_fmas_f32 v239, v239, v241, v242
	v_div_fixup_f32 v238, v239, v238, 1.0
	v_mul_f32_e32 v217, v217, v238
	v_mul_f32_e32 v36, v217, v36
	v_mul_f32_e32 v37, v217, v37
	v_mul_f32_e32 v38, v217, v38
	v_mul_f32_e32 v39, v217, v39
	v_mul_f32_e32 v234, v217, v234
	v_mul_f32_e32 v235, v217, v235
	v_mul_f32_e32 v236, v217, v236
	v_mul_f32_e32 v237, v217, v237
	v_mul_f32_e32 v36, v219, v36
	v_mul_f32_e32 v37, v221, v37
	v_mul_f32_e32 v38, v223, v38
	v_mul_f32_e32 v39, v225, v39
	v_mul_f32_e32 v244, v218, v234
	v_mul_f32_e32 v245, v220, v235
	v_mul_f32_e32 v246, v222, v236
	v_mul_f32_e32 v247, v224, v237
	v_cvt_pk_bf16_f32 v36, v244, v36
	v_cvt_pk_bf16_f32 v37, v245, v37
	v_cvt_pk_bf16_f32 v38, v246, v38
	v_cvt_pk_bf16_f32 v39, v247, v39
	v_mov_b32_e32 v2, v216
	v_ashrrev_i32_e32 v3, 31, v2
	v_lshl_add_u64 v[14:15], v[2:3], 1, v[0:1]
	global_store_dwordx4 v[14:15], v[36:39], off sc1
	s_waitcnt vmcnt(19)
	v_mov_b32_e32 v217, v211
	v_lshlrev_b32_e32 v234, 16, v40
	v_and_b32_e32 v40, 0xffff0000, v40
	v_mul_f32_e32 v238, v40, v40
	v_lshlrev_b32_e32 v235, 16, v41
	v_fmac_f32_e32 v238, v234, v234
	v_and_b32_e32 v41, 0xffff0000, v41
	v_fmac_f32_e32 v238, v235, v235
	v_lshlrev_b32_e32 v236, 16, v42
	v_fmac_f32_e32 v238, v41, v41
	v_and_b32_e32 v42, 0xffff0000, v42
	v_fmac_f32_e32 v238, v236, v236
	v_lshlrev_b32_e32 v237, 16, v43
	v_fmac_f32_e32 v238, v42, v42
	v_and_b32_e32 v43, 0xffff0000, v43
	v_fmac_f32_e32 v238, v237, v237
	v_fmac_f32_e32 v238, v43, v43
	ds_bpermute_b32 v239, v204, v238
	s_waitcnt lgkmcnt(0)
	v_add_f32_e32 v238, v238, v239
	ds_bpermute_b32 v239, v205, v238
	s_waitcnt lgkmcnt(0)
	v_add_f32_e32 v238, v238, v239
	ds_bpermute_b32 v239, v214, v238
	s_waitcnt lgkmcnt(0)
; __device__ __forceinline__ unsigned pk2(float lo, float hi) { return pg8::cvt_pk_bf16(lo, hi); }
; __device__ __forceinline__ void idx_unit(bf16* QB, float* SC, int* SEL, const float* qg, const float* kg, int b, int tp, LAS unsigned char* wl, int lane, bool do_norm) {
;     ...
;     for (int a = 0; a < 4; ++a)
; #pragma unroll 1
;         for (int p = 0; p < 5; ++p) {
;             const int col = (p < 4) ? (CQ + (4 * p + lg) * 128) : (CK + lg * 128);
;             bf16* ptr = QB + (row + a) * NBP + col + 8 * li;
;             const u32x4 w = *(const u32x4*)ptr;
;             float v[8] = {bflo(w.x), bfhi(w.x), bflo(w.y), bfhi(w.y), bflo(w.z), bfhi(w.z), bflo(w.w), bfhi(w.w)};
;             float s = 0.f;
; #pragma unroll
;             for (int e = 0; e < 8; ++e) s += v[e] * v[e];
;             s += __shfl_xor(s, 1); s += __shfl_xor(s, 2); s += __shfl_xor(s, 4); s += __shfl_xor(s, 8);
;             const float rstd = (1.0f / sqrtf(s * (1.f / 128.f) + RMS_EPS)) * ((p < 4) ? C2 : 1.f);
;             const float* gp = ((p < 4) ? qg : kg) + 8 * li;
;             const f32x4 g0 = *(const f32x4*)gp, g1 = *(const f32x4*)(gp + 4);
;             u32x4 o; o.x = pk2(v[0] * rstd * g0.x, v[1] * rstd * g0.y); o.y = pk2(v[2] * rstd * g0.z, v[3] * rstd * g0.w);
;             o.z = pk2(v[4] * rstd * g1.x, v[5] * rstd * g1.y); o.w = pk2(v[6] * rstd * g1.z, v[7] * rstd * g1.w);
;             *(u32x4*)ptr = o;
;         }
	v_add_f32_e32 v238, v238, v239
	ds_bpermute_b32 v239, v215, v238
	s_waitcnt lgkmcnt(0)
	v_add_f32_e32 v238, v238, v239
	v_fmamk_f32 v238, v238, 0x3c000000, v208
	v_mul_f32_e32 v239, 0x4f800000, v238
	v_cmp_gt_f32_e32 vcc, s33, v238
	s_nop 1
	v_cndmask_b32_e32 v238, v238, v239, vcc
	v_sqrt_f32_e32 v239, v238
	s_nop 0
	v_add_u32_e32 v240, -1, v239
	v_add_u32_e32 v241, 1, v239
	v_fma_f32 v242, -v240, v239, v238
	v_fma_f32 v243, -v241, v239, v238
	v_cmp_ge_f32_e64 s[0:1], 0, v242
	s_nop 1
	v_cndmask_b32_e64 v239, v239, v240, s[0:1]
	v_cmp_lt_f32_e64 s[0:1], 0, v243
	s_nop 1
	v_cndmask_b32_e64 v239, v239, v241, s[0:1]
	v_mul_f32_e32 v240, 0x37800000, v239
	v_cndmask_b32_e32 v239, v239, v240, vcc
	v_cmp_class_f32_e32 vcc, v238, v209
	s_nop 1
	v_cndmask_b32_e32 v238, v239, v238, vcc
	v_div_scale_f32 v239, s[0:1], v238, v238, 1.0
	v_rcp_f32_e32 v241, v239
	v_div_scale_f32 v240, vcc, 1.0, v238, 1.0
	v_fma_f32 v242, -v239, v241, 1.0
	v_fmac_f32_e32 v241, v242, v241
	v_mul_f32_e32 v242, v240, v241
	v_fma_f32 v243, -v239, v242, v240
	v_fmac_f32_e32 v242, v243, v241
	v_fma_f32 v239, -v239, v242, v240
	v_div_fmas_f32 v239, v239, v241, v242
	v_div_fixup_f32 v238, v239, v238, 1.0
	v_mul_f32_e32 v217, v217, v238
	v_mul_f32_e32 v40, v217, v40
	v_mul_f32_e32 v41, v217, v41
	v_mul_f32_e32 v42, v217, v42
	v_mul_f32_e32 v43, v217, v43
	v_mul_f32_e32 v234, v217, v234
	v_mul_f32_e32 v235, v217, v235
	v_mul_f32_e32 v236, v217, v236
	v_mul_f32_e32 v237, v217, v237
	v_mul_f32_e32 v40, v219, v40
	v_mul_f32_e32 v41, v221, v41
	v_mul_f32_e32 v42, v223, v42
	v_mul_f32_e32 v43, v225, v43
	v_mul_f32_e32 v244, v218, v234
	v_mul_f32_e32 v245, v220, v235
	v_mul_f32_e32 v246, v222, v236
	v_mul_f32_e32 v247, v224, v237
	v_cvt_pk_bf16_f32 v40, v244, v40
	v_cvt_pk_bf16_f32 v41, v245, v41
	v_cvt_pk_bf16_f32 v42, v246, v42
	v_cvt_pk_bf16_f32 v43, v247, v43
	v_add_u32_e32 v2, 0x200, v216
	v_ashrrev_i32_e32 v3, 31, v2
	v_lshl_add_u64 v[14:15], v[2:3], 1, v[0:1]
	global_store_dwordx4 v[14:15], v[40:43], off sc1
	s_waitcnt vmcnt(19)
	v_mov_b32_e32 v217, v211
	v_lshlrev_b32_e32 v234, 16, v44
	v_and_b32_e32 v44, 0xffff0000, v44
	v_mul_f32_e32 v238, v44, v44
	v_lshlrev_b32_e32 v235, 16, v45
	v_fmac_f32_e32 v238, v234, v234
	v_and_b32_e32 v45, 0xffff0000, v45
	v_fmac_f32_e32 v238, v235, v235
	v_lshlrev_b32_e32 v236, 16, v46
	v_fmac_f32_e32 v238, v45, v45
	v_and_b32_e32 v46, 0xffff0000, v46
	v_fmac_f32_e32 v238, v236, v236
	v_lshlrev_b32_e32 v237, 16, v47
	v_fmac_f32_e32 v238, v46, v46
	v_and_b32_e32 v47, 0xffff0000, v47
	v_fmac_f32_e32 v238, v237, v237
	v_fmac_f32_e32 v238, v47, v47
	ds_bpermute_b32 v239, v204, v238
	s_waitcnt lgkmcnt(0)
	v_add_f32_e32 v238, v238, v239
	ds_bpermute_b32 v239, v205, v238
	s_waitcnt lgkmcnt(0)
	v_add_f32_e32 v238, v238, v239
	ds_bpermute_b32 v239, v214, v238
	s_waitcnt lgkmcnt(0)
	v_add_f32_e32 v238, v238, v239
	ds_bpermute_b32 v239, v215, v238
	s_waitcnt lgkmcnt(0)
	v_add_f32_e32 v238, v238, v239
	v_fmamk_f32 v238, v238, 0x3c000000, v208
	v_mul_f32_e32 v239, 0x4f800000, v238
	v_cmp_gt_f32_e32 vcc, s33, v238
	s_nop 1
	v_cndmask_b32_e32 v238, v238, v239, vcc
	v_sqrt_f32_e32 v239, v238
	s_nop 0
	v_add_u32_e32 v240, -1, v239
	v_add_u32_e32 v241, 1, v239
	v_fma_f32 v242, -v240, v239, v238
	v_fma_f32 v243, -v241, v239, v238
	v_cmp_ge_f32_e64 s[0:1], 0, v242
	s_nop 1
	v_cndmask_b32_e64 v239, v239, v240, s[0:1]
	v_cmp_lt_f32_e64 s[0:1], 0, v243
	s_nop 1
	v_cndmask_b32_e64 v239, v239, v241, s[0:1]
	v_mul_f32_e32 v240, 0x37800000, v239
	v_cndmask_b32_e32 v239, v239, v240, vcc
	v_cmp_class_f32_e32 vcc, v238, v209
	s_nop 1
	v_cndmask_b32_e32 v238, v239, v238, vcc
	v_div_scale_f32 v239, s[0:1], v238, v238, 1.0
	v_rcp_f32_e32 v241, v239
	v_div_scale_f32 v240, vcc, 1.0, v238, 1.0
	v_fma_f32 v242, -v239, v241, 1.0
	v_fmac_f32_e32 v241, v242, v241
	v_mul_f32_e32 v242, v240, v241
	v_fma_f32 v243, -v239, v242, v240
	v_fmac_f32_e32 v242, v243, v241
	v_fma_f32 v239, -v239, v242, v240
	v_div_fmas_f32 v239, v239, v241, v242
	v_div_fixup_f32 v238, v239, v238, 1.0
	v_mul_f32_e32 v217, v217, v238
	v_mul_f32_e32 v44, v217, v44
	v_mul_f32_e32 v45, v217, v45
	v_mul_f32_e32 v46, v217, v46
	v_mul_f32_e32 v47, v217, v47
	v_mul_f32_e32 v234, v217, v234
	v_mul_f32_e32 v235, v217, v235
	v_mul_f32_e32 v236, v217, v236
	v_mul_f32_e32 v237, v217, v237
	v_mul_f32_e32 v44, v219, v44
	v_mul_f32_e32 v45, v221, v45
	v_mul_f32_e32 v46, v223, v46
	v_mul_f32_e32 v47, v225, v47
	v_mul_f32_e32 v244, v218, v234
	v_mul_f32_e32 v245, v220, v235
	v_mul_f32_e32 v246, v222, v236
	v_mul_f32_e32 v247, v224, v237
	v_cvt_pk_bf16_f32 v44, v244, v44
	v_cvt_pk_bf16_f32 v45, v245, v45
	v_cvt_pk_bf16_f32 v46, v246, v46
	v_cvt_pk_bf16_f32 v47, v247, v47
	v_add_u32_e32 v2, 0x400, v216
	v_ashrrev_i32_e32 v3, 31, v2
	v_lshl_add_u64 v[14:15], v[2:3], 1, v[0:1]
	global_store_dwordx4 v[14:15], v[44:47], off sc1
	s_waitcnt vmcnt(19)
	v_mov_b32_e32 v217, v211
	v_lshlrev_b32_e32 v234, 16, v48
	v_and_b32_e32 v48, 0xffff0000, v48
	v_mul_f32_e32 v238, v48, v48
	v_lshlrev_b32_e32 v235, 16, v49
	v_fmac_f32_e32 v238, v234, v234
	v_and_b32_e32 v49, 0xffff0000, v49
	v_fmac_f32_e32 v238, v235, v235
	v_lshlrev_b32_e32 v236, 16, v50
	v_fmac_f32_e32 v238, v49, v49
	v_and_b32_e32 v50, 0xffff0000, v50
	v_fmac_f32_e32 v238, v236, v236
	v_lshlrev_b32_e32 v237, 16, v51
	v_fmac_f32_e32 v238, v50, v50
	v_and_b32_e32 v51, 0xffff0000, v51
	v_fmac_f32_e32 v238, v237, v237
	v_fmac_f32_e32 v238, v51, v51
	ds_bpermute_b32 v239, v204, v238
	s_waitcnt lgkmcnt(0)
	v_add_f32_e32 v238, v238, v239
	ds_bpermute_b32 v239, v205, v238
	s_waitcnt lgkmcnt(0)
	v_add_f32_e32 v238, v238, v239
	ds_bpermute_b32 v239, v214, v238
	s_waitcnt lgkmcnt(0)
; __device__ __forceinline__ unsigned pk2(float lo, float hi) { return pg8::cvt_pk_bf16(lo, hi); }
; __device__ __forceinline__ void idx_unit(bf16* QB, float* SC, int* SEL, const float* qg, const float* kg, int b, int tp, LAS unsigned char* wl, int lane, bool do_norm) {
;     ...
;     for (int a = 0; a < 4; ++a)
; #pragma unroll 1
;         for (int p = 0; p < 5; ++p) {
;             const int col = (p < 4) ? (CQ + (4 * p + lg) * 128) : (CK + lg * 128);
;             bf16* ptr = QB + (row + a) * NBP + col + 8 * li;
;             const u32x4 w = *(const u32x4*)ptr;
;             float v[8] = {bflo(w.x), bfhi(w.x), bflo(w.y), bfhi(w.y), bflo(w.z), bfhi(w.z), bflo(w.w), bfhi(w.w)};
;             float s = 0.f;
; #pragma unroll
;             for (int e = 0; e < 8; ++e) s += v[e] * v[e];
;             s += __shfl_xor(s, 1); s += __shfl_xor(s, 2); s += __shfl_xor(s, 4); s += __shfl_xor(s, 8);
;             const float rstd = (1.0f / sqrtf(s * (1.f / 128.f) + RMS_EPS)) * ((p < 4) ? C2 : 1.f);
;             const float* gp = ((p < 4) ? qg : kg) + 8 * li;
;             const f32x4 g0 = *(const f32x4*)gp, g1 = *(const f32x4*)(gp + 4);
;             u32x4 o; o.x = pk2(v[0] * rstd * g0.x, v[1] * rstd * g0.y); o.y = pk2(v[2] * rstd * g0.z, v[3] * rstd * g0.w);
;             o.z = pk2(v[4] * rstd * g1.x, v[5] * rstd * g1.y); o.w = pk2(v[6] * rstd * g1.z, v[7] * rstd * g1.w);
;             *(u32x4*)ptr = o;
;         }
	v_add_f32_e32 v238, v238, v239
	ds_bpermute_b32 v239, v215, v238
	s_waitcnt lgkmcnt(0)
	v_add_f32_e32 v238, v238, v239
	v_fmamk_f32 v238, v238, 0x3c000000, v208
	v_mul_f32_e32 v239, 0x4f800000, v238
	v_cmp_gt_f32_e32 vcc, s33, v238
	s_nop 1
	v_cndmask_b32_e32 v238, v238, v239, vcc
	v_sqrt_f32_e32 v239, v238
	s_nop 0
	v_add_u32_e32 v240, -1, v239
	v_add_u32_e32 v241, 1, v239
	v_fma_f32 v242, -v240, v239, v238
	v_fma_f32 v243, -v241, v239, v238
	v_cmp_ge_f32_e64 s[0:1], 0, v242
	s_nop 1
	v_cndmask_b32_e64 v239, v239, v240, s[0:1]
	v_cmp_lt_f32_e64 s[0:1], 0, v243
	s_nop 1
	v_cndmask_b32_e64 v239, v239, v241, s[0:1]
	v_mul_f32_e32 v240, 0x37800000, v239
	v_cndmask_b32_e32 v239, v239, v240, vcc
	v_cmp_class_f32_e32 vcc, v238, v209
	s_nop 1
	v_cndmask_b32_e32 v238, v239, v238, vcc
	v_div_scale_f32 v239, s[0:1], v238, v238, 1.0
	v_rcp_f32_e32 v241, v239
	v_div_scale_f32 v240, vcc, 1.0, v238, 1.0
	v_fma_f32 v242, -v239, v241, 1.0
	v_fmac_f32_e32 v241, v242, v241
	v_mul_f32_e32 v242, v240, v241
	v_fma_f32 v243, -v239, v242, v240
	v_fmac_f32_e32 v242, v243, v241
	v_fma_f32 v239, -v239, v242, v240
	v_div_fmas_f32 v239, v239, v241, v242
	v_div_fixup_f32 v238, v239, v238, 1.0
	v_mul_f32_e32 v217, v217, v238
	v_mul_f32_e32 v48, v217, v48
	v_mul_f32_e32 v49, v217, v49
	v_mul_f32_e32 v50, v217, v50
	v_mul_f32_e32 v51, v217, v51
	v_mul_f32_e32 v234, v217, v234
	v_mul_f32_e32 v235, v217, v235
	v_mul_f32_e32 v236, v217, v236
	v_mul_f32_e32 v237, v217, v237
	v_mul_f32_e32 v48, v219, v48
	v_mul_f32_e32 v49, v221, v49
	v_mul_f32_e32 v50, v223, v50
	v_mul_f32_e32 v51, v225, v51
	v_mul_f32_e32 v244, v218, v234
	v_mul_f32_e32 v245, v220, v235
	v_mul_f32_e32 v246, v222, v236
	v_mul_f32_e32 v247, v224, v237
	v_cvt_pk_bf16_f32 v48, v244, v48
	v_cvt_pk_bf16_f32 v49, v245, v49
	v_cvt_pk_bf16_f32 v50, v246, v50
	v_cvt_pk_bf16_f32 v51, v247, v51
	v_add_u32_e32 v2, 0x600, v216
	v_ashrrev_i32_e32 v3, 31, v2
	v_lshl_add_u64 v[14:15], v[2:3], 1, v[0:1]
	global_store_dwordx4 v[14:15], v[48:51], off sc1
	s_waitcnt vmcnt(19)
	v_mov_b32_e32 v217, 1.0
	v_lshlrev_b32_e32 v234, 16, v52
	v_and_b32_e32 v52, 0xffff0000, v52
	v_mul_f32_e32 v238, v52, v52
	v_lshlrev_b32_e32 v235, 16, v53
	v_fmac_f32_e32 v238, v234, v234
	v_and_b32_e32 v53, 0xffff0000, v53
	v_fmac_f32_e32 v238, v235, v235
	v_lshlrev_b32_e32 v236, 16, v54
	v_fmac_f32_e32 v238, v53, v53
	v_and_b32_e32 v54, 0xffff0000, v54
	v_fmac_f32_e32 v238, v236, v236
	v_lshlrev_b32_e32 v237, 16, v55
	v_fmac_f32_e32 v238, v54, v54
	v_and_b32_e32 v55, 0xffff0000, v55
	v_fmac_f32_e32 v238, v237, v237
	v_fmac_f32_e32 v238, v55, v55
	ds_bpermute_b32 v239, v204, v238
	s_waitcnt lgkmcnt(0)
	v_add_f32_e32 v238, v238, v239
	ds_bpermute_b32 v239, v205, v238
	s_waitcnt lgkmcnt(0)
	v_add_f32_e32 v238, v238, v239
	ds_bpermute_b32 v239, v214, v238
	s_waitcnt lgkmcnt(0)
	v_add_f32_e32 v238, v238, v239
	ds_bpermute_b32 v239, v215, v238
	s_waitcnt lgkmcnt(0)
	v_add_f32_e32 v238, v238, v239
	v_fmamk_f32 v238, v238, 0x3c000000, v208
	v_mul_f32_e32 v239, 0x4f800000, v238
	v_cmp_gt_f32_e32 vcc, s33, v238
	s_nop 1
	v_cndmask_b32_e32 v238, v238, v239, vcc
	v_sqrt_f32_e32 v239, v238
	s_nop 0
	v_add_u32_e32 v240, -1, v239
	v_add_u32_e32 v241, 1, v239
	v_fma_f32 v242, -v240, v239, v238
	v_fma_f32 v243, -v241, v239, v238
	v_cmp_ge_f32_e64 s[0:1], 0, v242
	s_nop 1
	v_cndmask_b32_e64 v239, v239, v240, s[0:1]
	v_cmp_lt_f32_e64 s[0:1], 0, v243
	s_nop 1
	v_cndmask_b32_e64 v239, v239, v241, s[0:1]
	v_mul_f32_e32 v240, 0x37800000, v239
	v_cndmask_b32_e32 v239, v239, v240, vcc
	v_cmp_class_f32_e32 vcc, v238, v209
	s_nop 1
	v_cndmask_b32_e32 v238, v239, v238, vcc
	v_div_scale_f32 v239, s[0:1], v238, v238, 1.0
	v_rcp_f32_e32 v241, v239
	v_div_scale_f32 v240, vcc, 1.0, v238, 1.0
	v_fma_f32 v242, -v239, v241, 1.0
	v_fmac_f32_e32 v241, v242, v241
	v_mul_f32_e32 v242, v240, v241
	v_fma_f32 v243, -v239, v242, v240
	v_fmac_f32_e32 v242, v243, v241
	v_fma_f32 v239, -v239, v242, v240
	v_div_fmas_f32 v239, v239, v241, v242
	v_div_fixup_f32 v238, v239, v238, 1.0
	v_mul_f32_e32 v217, v217, v238
	v_mul_f32_e32 v52, v217, v52
	v_mul_f32_e32 v53, v217, v53
	v_mul_f32_e32 v54, v217, v54
	v_mul_f32_e32 v55, v217, v55
	v_mul_f32_e32 v234, v217, v234
	v_mul_f32_e32 v235, v217, v235
	v_mul_f32_e32 v236, v217, v236
	v_mul_f32_e32 v237, v217, v237
	v_mul_f32_e32 v52, v227, v52
	v_mul_f32_e32 v53, v229, v53
	v_mul_f32_e32 v54, v231, v54
	v_mul_f32_e32 v55, v233, v55
	v_mul_f32_e32 v244, v226, v234
	v_mul_f32_e32 v245, v228, v235
	v_mul_f32_e32 v246, v230, v236
	v_mul_f32_e32 v247, v232, v237
	v_cvt_pk_bf16_f32 v52, v244, v52
	v_cvt_pk_bf16_f32 v53, v245, v53
	v_cvt_pk_bf16_f32 v54, v246, v54
	v_cvt_pk_bf16_f32 v55, v247, v55
	v_add_u32_e32 v2, 0x800, v216
	v_ashrrev_i32_e32 v3, 31, v2
	v_lshl_add_u64 v[14:15], v[2:3], 1, v[0:1]
	global_store_dwordx4 v[14:15], v[52:55], off sc1
	s_add_u32 s0, s2, 2
	s_addc_u32 s1, s79, 0
	s_mul_i32 s4, s1, 0x2200
	v_mad_u64_u32 v[0:1], s[0:1], s0, v212, v[118:119]
	v_add_u32_e32 v1, s4, v1
	s_waitcnt vmcnt(19)
	v_mov_b32_e32 v217, v211
	v_lshlrev_b32_e32 v234, 16, v56
	v_and_b32_e32 v56, 0xffff0000, v56
	v_mul_f32_e32 v238, v56, v56
	v_lshlrev_b32_e32 v235, 16, v57
	v_fmac_f32_e32 v238, v234, v234
	v_and_b32_e32 v57, 0xffff0000, v57
	v_fmac_f32_e32 v238, v235, v235
	v_lshlrev_b32_e32 v236, 16, v58
	v_fmac_f32_e32 v238, v57, v57
	v_and_b32_e32 v58, 0xffff0000, v58
	v_fmac_f32_e32 v238, v236, v236
	v_lshlrev_b32_e32 v237, 16, v59
	v_fmac_f32_e32 v238, v58, v58
	v_and_b32_e32 v59, 0xffff0000, v59
	v_fmac_f32_e32 v238, v237, v237
	v_fmac_f32_e32 v238, v59, v59
	ds_bpermute_b32 v239, v204, v238
	s_waitcnt lgkmcnt(0)
; __device__ __forceinline__ unsigned pk2(float lo, float hi) { return pg8::cvt_pk_bf16(lo, hi); }
; __device__ __forceinline__ void idx_unit(bf16* QB, float* SC, int* SEL, const float* qg, const float* kg, int b, int tp, LAS unsigned char* wl, int lane, bool do_norm) {
;     ...
;     for (int a = 0; a < 4; ++a)
; #pragma unroll 1
;         for (int p = 0; p < 5; ++p) {
;             const int col = (p < 4) ? (CQ + (4 * p + lg) * 128) : (CK + lg * 128);
;             bf16* ptr = QB + (row + a) * NBP + col + 8 * li;
;             const u32x4 w = *(const u32x4*)ptr;
;             float v[8] = {bflo(w.x), bfhi(w.x), bflo(w.y), bfhi(w.y), bflo(w.z), bfhi(w.z), bflo(w.w), bfhi(w.w)};
;             float s = 0.f;
; #pragma unroll
;             for (int e = 0; e < 8; ++e) s += v[e] * v[e];
;             s += __shfl_xor(s, 1); s += __shfl_xor(s, 2); s += __shfl_xor(s, 4); s += __shfl_xor(s, 8);
;             const float rstd = (1.0f / sqrtf(s * (1.f / 128.f) + RMS_EPS)) * ((p < 4) ? C2 : 1.f);
;             const float* gp = ((p < 4) ? qg : kg) + 8 * li;
;             const f32x4 g0 = *(const f32x4*)gp, g1 = *(const f32x4*)(gp + 4);
;             u32x4 o; o.x = pk2(v[0] * rstd * g0.x, v[1] * rstd * g0.y); o.y = pk2(v[2] * rstd * g0.z, v[3] * rstd * g0.w);
;             o.z = pk2(v[4] * rstd * g1.x, v[5] * rstd * g1.y); o.w = pk2(v[6] * rstd * g1.z, v[7] * rstd * g1.w);
;             *(u32x4*)ptr = o;
;         }
	v_add_f32_e32 v238, v238, v239
	ds_bpermute_b32 v239, v205, v238
	s_waitcnt lgkmcnt(0)
	v_add_f32_e32 v238, v238, v239
	ds_bpermute_b32 v239, v214, v238
	s_waitcnt lgkmcnt(0)
	v_add_f32_e32 v238, v238, v239
	ds_bpermute_b32 v239, v215, v238
	s_waitcnt lgkmcnt(0)
	v_add_f32_e32 v238, v238, v239
	v_fmamk_f32 v238, v238, 0x3c000000, v208
	v_mul_f32_e32 v239, 0x4f800000, v238
	v_cmp_gt_f32_e32 vcc, s33, v238
	s_nop 1
	v_cndmask_b32_e32 v238, v238, v239, vcc
	v_sqrt_f32_e32 v239, v238
	s_nop 0
	v_add_u32_e32 v240, -1, v239
	v_add_u32_e32 v241, 1, v239
	v_fma_f32 v242, -v240, v239, v238
	v_fma_f32 v243, -v241, v239, v238
	v_cmp_ge_f32_e64 s[0:1], 0, v242
	s_nop 1
	v_cndmask_b32_e64 v239, v239, v240, s[0:1]
	v_cmp_lt_f32_e64 s[0:1], 0, v243
	s_nop 1
	v_cndmask_b32_e64 v239, v239, v241, s[0:1]
	v_mul_f32_e32 v240, 0x37800000, v239
	v_cndmask_b32_e32 v239, v239, v240, vcc
	v_cmp_class_f32_e32 vcc, v238, v209
	s_nop 1
	v_cndmask_b32_e32 v238, v239, v238, vcc
	v_div_scale_f32 v239, s[0:1], v238, v238, 1.0
	v_rcp_f32_e32 v241, v239
	v_div_scale_f32 v240, vcc, 1.0, v238, 1.0
	v_fma_f32 v242, -v239, v241, 1.0
	v_fmac_f32_e32 v241, v242, v241
	v_mul_f32_e32 v242, v240, v241
	v_fma_f32 v243, -v239, v242, v240
	v_fmac_f32_e32 v242, v243, v241
	v_fma_f32 v239, -v239, v242, v240
	v_div_fmas_f32 v239, v239, v241, v242
	v_div_fixup_f32 v238, v239, v238, 1.0
	v_mul_f32_e32 v217, v217, v238
	v_mul_f32_e32 v56, v217, v56
	v_mul_f32_e32 v57, v217, v57
	v_mul_f32_e32 v58, v217, v58
	v_mul_f32_e32 v59, v217, v59
	v_mul_f32_e32 v234, v217, v234
	v_mul_f32_e32 v235, v217, v235
	v_mul_f32_e32 v236, v217, v236
	v_mul_f32_e32 v237, v217, v237
	v_mul_f32_e32 v56, v219, v56
	v_mul_f32_e32 v57, v221, v57
	v_mul_f32_e32 v58, v223, v58
	v_mul_f32_e32 v59, v225, v59
	v_mul_f32_e32 v244, v218, v234
	v_mul_f32_e32 v245, v220, v235
	v_mul_f32_e32 v246, v222, v236
	v_mul_f32_e32 v247, v224, v237
	v_cvt_pk_bf16_f32 v56, v244, v56
	v_cvt_pk_bf16_f32 v57, v245, v57
	v_cvt_pk_bf16_f32 v58, v246, v58
	v_cvt_pk_bf16_f32 v59, v247, v59
	v_mov_b32_e32 v2, v216
	v_ashrrev_i32_e32 v3, 31, v2
	v_lshl_add_u64 v[14:15], v[2:3], 1, v[0:1]
	global_store_dwordx4 v[14:15], v[56:59], off sc1
	s_waitcnt vmcnt(19)
	v_mov_b32_e32 v217, v211
	v_lshlrev_b32_e32 v234, 16, v60
	v_and_b32_e32 v60, 0xffff0000, v60
	v_mul_f32_e32 v238, v60, v60
	v_lshlrev_b32_e32 v235, 16, v61
	v_fmac_f32_e32 v238, v234, v234
	v_and_b32_e32 v61, 0xffff0000, v61
	v_fmac_f32_e32 v238, v235, v235
	v_lshlrev_b32_e32 v236, 16, v62
	v_fmac_f32_e32 v238, v61, v61
	v_and_b32_e32 v62, 0xffff0000, v62
	v_fmac_f32_e32 v238, v236, v236
	v_lshlrev_b32_e32 v237, 16, v63
	v_fmac_f32_e32 v238, v62, v62
	v_and_b32_e32 v63, 0xffff0000, v63
	v_fmac_f32_e32 v238, v237, v237
	v_fmac_f32_e32 v238, v63, v63
	ds_bpermute_b32 v239, v204, v238
	s_waitcnt lgkmcnt(0)
	v_add_f32_e32 v238, v238, v239
	ds_bpermute_b32 v239, v205, v238
	s_waitcnt lgkmcnt(0)
	v_add_f32_e32 v238, v238, v239
	ds_bpermute_b32 v239, v214, v238
	s_waitcnt lgkmcnt(0)
	v_add_f32_e32 v238, v238, v239
	ds_bpermute_b32 v239, v215, v238
	s_waitcnt lgkmcnt(0)
	v_add_f32_e32 v238, v238, v239
	v_fmamk_f32 v238, v238, 0x3c000000, v208
	v_mul_f32_e32 v239, 0x4f800000, v238
	v_cmp_gt_f32_e32 vcc, s33, v238
	s_nop 1
	v_cndmask_b32_e32 v238, v238, v239, vcc
	v_sqrt_f32_e32 v239, v238
	s_nop 0
	v_add_u32_e32 v240, -1, v239
	v_add_u32_e32 v241, 1, v239
	v_fma_f32 v242, -v240, v239, v238
	v_fma_f32 v243, -v241, v239, v238
	v_cmp_ge_f32_e64 s[0:1], 0, v242
	s_nop 1
	v_cndmask_b32_e64 v239, v239, v240, s[0:1]
	v_cmp_lt_f32_e64 s[0:1], 0, v243
	s_nop 1
	v_cndmask_b32_e64 v239, v239, v241, s[0:1]
	v_mul_f32_e32 v240, 0x37800000, v239
	v_cndmask_b32_e32 v239, v239, v240, vcc
	v_cmp_class_f32_e32 vcc, v238, v209
	s_nop 1
	v_cndmask_b32_e32 v238, v239, v238, vcc
	v_div_scale_f32 v239, s[0:1], v238, v238, 1.0
	v_rcp_f32_e32 v241, v239
	v_div_scale_f32 v240, vcc, 1.0, v238, 1.0
	v_fma_f32 v242, -v239, v241, 1.0
	v_fmac_f32_e32 v241, v242, v241
	v_mul_f32_e32 v242, v240, v241
	v_fma_f32 v243, -v239, v242, v240
	v_fmac_f32_e32 v242, v243, v241
	v_fma_f32 v239, -v239, v242, v240
	v_div_fmas_f32 v239, v239, v241, v242
	v_div_fixup_f32 v238, v239, v238, 1.0
	v_mul_f32_e32 v217, v217, v238
	v_mul_f32_e32 v60, v217, v60
	v_mul_f32_e32 v61, v217, v61
	v_mul_f32_e32 v62, v217, v62
	v_mul_f32_e32 v63, v217, v63
	v_mul_f32_e32 v234, v217, v234
	v_mul_f32_e32 v235, v217, v235
	v_mul_f32_e32 v236, v217, v236
	v_mul_f32_e32 v237, v217, v237
	v_mul_f32_e32 v60, v219, v60
	v_mul_f32_e32 v61, v221, v61
	v_mul_f32_e32 v62, v223, v62
	v_mul_f32_e32 v63, v225, v63
	v_mul_f32_e32 v244, v218, v234
	v_mul_f32_e32 v245, v220, v235
	v_mul_f32_e32 v246, v222, v236
	v_mul_f32_e32 v247, v224, v237
	v_cvt_pk_bf16_f32 v60, v244, v60
	v_cvt_pk_bf16_f32 v61, v245, v61
	v_cvt_pk_bf16_f32 v62, v246, v62
	v_cvt_pk_bf16_f32 v63, v247, v63
	v_add_u32_e32 v2, 0x200, v216
	v_ashrrev_i32_e32 v3, 31, v2
	v_lshl_add_u64 v[14:15], v[2:3], 1, v[0:1]
	global_store_dwordx4 v[14:15], v[60:63], off sc1
	s_waitcnt vmcnt(19)
	v_mov_b32_e32 v217, v211
	v_lshlrev_b32_e32 v234, 16, v64
	v_and_b32_e32 v64, 0xffff0000, v64
	v_mul_f32_e32 v238, v64, v64
	v_lshlrev_b32_e32 v235, 16, v65
	v_fmac_f32_e32 v238, v234, v234
	v_and_b32_e32 v65, 0xffff0000, v65
	v_fmac_f32_e32 v238, v235, v235
	v_lshlrev_b32_e32 v236, 16, v66
	v_fmac_f32_e32 v238, v65, v65
	v_and_b32_e32 v66, 0xffff0000, v66
	v_fmac_f32_e32 v238, v236, v236
	v_lshlrev_b32_e32 v237, 16, v67
	v_fmac_f32_e32 v238, v66, v66
	v_and_b32_e32 v67, 0xffff0000, v67
	v_fmac_f32_e32 v238, v237, v237
	v_fmac_f32_e32 v238, v67, v67
	ds_bpermute_b32 v239, v204, v238
	s_waitcnt lgkmcnt(0)
; __device__ __forceinline__ unsigned pk2(float lo, float hi) { return pg8::cvt_pk_bf16(lo, hi); }
; __device__ __forceinline__ void idx_unit(bf16* QB, float* SC, int* SEL, const float* qg, const float* kg, int b, int tp, LAS unsigned char* wl, int lane, bool do_norm) {
;     ...
;     for (int a = 0; a < 4; ++a)
; #pragma unroll 1
;         for (int p = 0; p < 5; ++p) {
;             const int col = (p < 4) ? (CQ + (4 * p + lg) * 128) : (CK + lg * 128);
;             bf16* ptr = QB + (row + a) * NBP + col + 8 * li;
;             const u32x4 w = *(const u32x4*)ptr;
;             float v[8] = {bflo(w.x), bfhi(w.x), bflo(w.y), bfhi(w.y), bflo(w.z), bfhi(w.z), bflo(w.w), bfhi(w.w)};
;             float s = 0.f;
; #pragma unroll
;             for (int e = 0; e < 8; ++e) s += v[e] * v[e];
;             s += __shfl_xor(s, 1); s += __shfl_xor(s, 2); s += __shfl_xor(s, 4); s += __shfl_xor(s, 8);
;             const float rstd = (1.0f / sqrtf(s * (1.f / 128.f) + RMS_EPS)) * ((p < 4) ? C2 : 1.f);
;             const float* gp = ((p < 4) ? qg : kg) + 8 * li;
;             const f32x4 g0 = *(const f32x4*)gp, g1 = *(const f32x4*)(gp + 4);
;             u32x4 o; o.x = pk2(v[0] * rstd * g0.x, v[1] * rstd * g0.y); o.y = pk2(v[2] * rstd * g0.z, v[3] * rstd * g0.w);
;             o.z = pk2(v[4] * rstd * g1.x, v[5] * rstd * g1.y); o.w = pk2(v[6] * rstd * g1.z, v[7] * rstd * g1.w);
;             *(u32x4*)ptr = o;
;         }
	v_add_f32_e32 v238, v238, v239
	ds_bpermute_b32 v239, v205, v238
	s_waitcnt lgkmcnt(0)
	v_add_f32_e32 v238, v238, v239
	ds_bpermute_b32 v239, v214, v238
	s_waitcnt lgkmcnt(0)
	v_add_f32_e32 v238, v238, v239
	ds_bpermute_b32 v239, v215, v238
	s_waitcnt lgkmcnt(0)
	v_add_f32_e32 v238, v238, v239
	v_fmamk_f32 v238, v238, 0x3c000000, v208
	v_mul_f32_e32 v239, 0x4f800000, v238
	v_cmp_gt_f32_e32 vcc, s33, v238
	s_nop 1
	v_cndmask_b32_e32 v238, v238, v239, vcc
	v_sqrt_f32_e32 v239, v238
	s_nop 0
	v_add_u32_e32 v240, -1, v239
	v_add_u32_e32 v241, 1, v239
	v_fma_f32 v242, -v240, v239, v238
	v_fma_f32 v243, -v241, v239, v238
	v_cmp_ge_f32_e64 s[0:1], 0, v242
	s_nop 1
	v_cndmask_b32_e64 v239, v239, v240, s[0:1]
	v_cmp_lt_f32_e64 s[0:1], 0, v243
	s_nop 1
	v_cndmask_b32_e64 v239, v239, v241, s[0:1]
	v_mul_f32_e32 v240, 0x37800000, v239
	v_cndmask_b32_e32 v239, v239, v240, vcc
	v_cmp_class_f32_e32 vcc, v238, v209
	s_nop 1
	v_cndmask_b32_e32 v238, v239, v238, vcc
	v_div_scale_f32 v239, s[0:1], v238, v238, 1.0
	v_rcp_f32_e32 v241, v239
	v_div_scale_f32 v240, vcc, 1.0, v238, 1.0
	v_fma_f32 v242, -v239, v241, 1.0
	v_fmac_f32_e32 v241, v242, v241
	v_mul_f32_e32 v242, v240, v241
	v_fma_f32 v243, -v239, v242, v240
	v_fmac_f32_e32 v242, v243, v241
	v_fma_f32 v239, -v239, v242, v240
	v_div_fmas_f32 v239, v239, v241, v242
	v_div_fixup_f32 v238, v239, v238, 1.0
	v_mul_f32_e32 v217, v217, v238
	v_mul_f32_e32 v64, v217, v64
	v_mul_f32_e32 v65, v217, v65
	v_mul_f32_e32 v66, v217, v66
	v_mul_f32_e32 v67, v217, v67
	v_mul_f32_e32 v234, v217, v234
	v_mul_f32_e32 v235, v217, v235
	v_mul_f32_e32 v236, v217, v236
	v_mul_f32_e32 v237, v217, v237
	v_mul_f32_e32 v64, v219, v64
	v_mul_f32_e32 v65, v221, v65
	v_mul_f32_e32 v66, v223, v66
	v_mul_f32_e32 v67, v225, v67
	v_mul_f32_e32 v244, v218, v234
	v_mul_f32_e32 v245, v220, v235
	v_mul_f32_e32 v246, v222, v236
	v_mul_f32_e32 v247, v224, v237
	v_cvt_pk_bf16_f32 v64, v244, v64
	v_cvt_pk_bf16_f32 v65, v245, v65
	v_cvt_pk_bf16_f32 v66, v246, v66
	v_cvt_pk_bf16_f32 v67, v247, v67
	v_add_u32_e32 v2, 0x400, v216
	v_ashrrev_i32_e32 v3, 31, v2
	v_lshl_add_u64 v[14:15], v[2:3], 1, v[0:1]
	global_store_dwordx4 v[14:15], v[64:67], off sc1
	s_waitcnt vmcnt(19)
	v_mov_b32_e32 v217, v211
	v_lshlrev_b32_e32 v234, 16, v68
	v_and_b32_e32 v68, 0xffff0000, v68
	v_mul_f32_e32 v238, v68, v68
	v_lshlrev_b32_e32 v235, 16, v69
	v_fmac_f32_e32 v238, v234, v234
	v_and_b32_e32 v69, 0xffff0000, v69
	v_fmac_f32_e32 v238, v235, v235
	v_lshlrev_b32_e32 v236, 16, v70
	v_fmac_f32_e32 v238, v69, v69
	v_and_b32_e32 v70, 0xffff0000, v70
	v_fmac_f32_e32 v238, v236, v236
	v_lshlrev_b32_e32 v237, 16, v71
	v_fmac_f32_e32 v238, v70, v70
	v_and_b32_e32 v71, 0xffff0000, v71
	v_fmac_f32_e32 v238, v237, v237
	v_fmac_f32_e32 v238, v71, v71
	ds_bpermute_b32 v239, v204, v238
	s_waitcnt lgkmcnt(0)
	v_add_f32_e32 v238, v238, v239
	ds_bpermute_b32 v239, v205, v238
	s_waitcnt lgkmcnt(0)
	v_add_f32_e32 v238, v238, v239
	ds_bpermute_b32 v239, v214, v238
	s_waitcnt lgkmcnt(0)
	v_add_f32_e32 v238, v238, v239
	ds_bpermute_b32 v239, v215, v238
	s_waitcnt lgkmcnt(0)
	v_add_f32_e32 v238, v238, v239
	v_fmamk_f32 v238, v238, 0x3c000000, v208
	v_mul_f32_e32 v239, 0x4f800000, v238
	v_cmp_gt_f32_e32 vcc, s33, v238
	s_nop 1
	v_cndmask_b32_e32 v238, v238, v239, vcc
	v_sqrt_f32_e32 v239, v238
	s_nop 0
	v_add_u32_e32 v240, -1, v239
	v_add_u32_e32 v241, 1, v239
	v_fma_f32 v242, -v240, v239, v238
	v_fma_f32 v243, -v241, v239, v238
	v_cmp_ge_f32_e64 s[0:1], 0, v242
	s_nop 1
	v_cndmask_b32_e64 v239, v239, v240, s[0:1]
	v_cmp_lt_f32_e64 s[0:1], 0, v243
	s_nop 1
	v_cndmask_b32_e64 v239, v239, v241, s[0:1]
	v_mul_f32_e32 v240, 0x37800000, v239
	v_cndmask_b32_e32 v239, v239, v240, vcc
	v_cmp_class_f32_e32 vcc, v238, v209
	s_nop 1
	v_cndmask_b32_e32 v238, v239, v238, vcc
	v_div_scale_f32 v239, s[0:1], v238, v238, 1.0
	v_rcp_f32_e32 v241, v239
	v_div_scale_f32 v240, vcc, 1.0, v238, 1.0
	v_fma_f32 v242, -v239, v241, 1.0
	v_fmac_f32_e32 v241, v242, v241
	v_mul_f32_e32 v242, v240, v241
	v_fma_f32 v243, -v239, v242, v240
	v_fmac_f32_e32 v242, v243, v241
	v_fma_f32 v239, -v239, v242, v240
	v_div_fmas_f32 v239, v239, v241, v242
	v_div_fixup_f32 v238, v239, v238, 1.0
	v_mul_f32_e32 v217, v217, v238
	v_mul_f32_e32 v68, v217, v68
	v_mul_f32_e32 v69, v217, v69
	v_mul_f32_e32 v70, v217, v70
	v_mul_f32_e32 v71, v217, v71
	v_mul_f32_e32 v234, v217, v234
	v_mul_f32_e32 v235, v217, v235
	v_mul_f32_e32 v236, v217, v236
	v_mul_f32_e32 v237, v217, v237
	v_mul_f32_e32 v68, v219, v68
	v_mul_f32_e32 v69, v221, v69
	v_mul_f32_e32 v70, v223, v70
	v_mul_f32_e32 v71, v225, v71
	v_mul_f32_e32 v244, v218, v234
	v_mul_f32_e32 v245, v220, v235
	v_mul_f32_e32 v246, v222, v236
	v_mul_f32_e32 v247, v224, v237
	v_cvt_pk_bf16_f32 v68, v244, v68
	v_cvt_pk_bf16_f32 v69, v245, v69
	v_cvt_pk_bf16_f32 v70, v246, v70
	v_cvt_pk_bf16_f32 v71, v247, v71
	v_add_u32_e32 v2, 0x600, v216
	v_ashrrev_i32_e32 v3, 31, v2
	v_lshl_add_u64 v[14:15], v[2:3], 1, v[0:1]
	global_store_dwordx4 v[14:15], v[68:71], off sc1
	s_waitcnt vmcnt(19)
	v_mov_b32_e32 v217, 1.0
	v_lshlrev_b32_e32 v234, 16, v72
	v_and_b32_e32 v72, 0xffff0000, v72
	v_mul_f32_e32 v238, v72, v72
	v_lshlrev_b32_e32 v235, 16, v73
	v_fmac_f32_e32 v238, v234, v234
	v_and_b32_e32 v73, 0xffff0000, v73
	v_fmac_f32_e32 v238, v235, v235
	v_lshlrev_b32_e32 v236, 16, v74
	v_fmac_f32_e32 v238, v73, v73
	v_and_b32_e32 v74, 0xffff0000, v74
	v_fmac_f32_e32 v238, v236, v236
	v_lshlrev_b32_e32 v237, 16, v75
	v_fmac_f32_e32 v238, v74, v74
	v_and_b32_e32 v75, 0xffff0000, v75
	v_fmac_f32_e32 v238, v237, v237
	v_fmac_f32_e32 v238, v75, v75
	ds_bpermute_b32 v239, v204, v238
	s_waitcnt lgkmcnt(0)
; __device__ __forceinline__ unsigned pk2(float lo, float hi) { return pg8::cvt_pk_bf16(lo, hi); }
; __device__ __forceinline__ void idx_unit(bf16* QB, float* SC, int* SEL, const float* qg, const float* kg, int b, int tp, LAS unsigned char* wl, int lane, bool do_norm) {
;     ...
;     for (int a = 0; a < 4; ++a)
; #pragma unroll 1
;         for (int p = 0; p < 5; ++p) {
;             const int col = (p < 4) ? (CQ + (4 * p + lg) * 128) : (CK + lg * 128);
;             bf16* ptr = QB + (row + a) * NBP + col + 8 * li;
;             const u32x4 w = *(const u32x4*)ptr;
;             float v[8] = {bflo(w.x), bfhi(w.x), bflo(w.y), bfhi(w.y), bflo(w.z), bfhi(w.z), bflo(w.w), bfhi(w.w)};
;             float s = 0.f;
; #pragma unroll
;             for (int e = 0; e < 8; ++e) s += v[e] * v[e];
;             s += __shfl_xor(s, 1); s += __shfl_xor(s, 2); s += __shfl_xor(s, 4); s += __shfl_xor(s, 8);
;             const float rstd = (1.0f / sqrtf(s * (1.f / 128.f) + RMS_EPS)) * ((p < 4) ? C2 : 1.f);
;             const float* gp = ((p < 4) ? qg : kg) + 8 * li;
;             const f32x4 g0 = *(const f32x4*)gp, g1 = *(const f32x4*)(gp + 4);
;             u32x4 o; o.x = pk2(v[0] * rstd * g0.x, v[1] * rstd * g0.y); o.y = pk2(v[2] * rstd * g0.z, v[3] * rstd * g0.w);
;             o.z = pk2(v[4] * rstd * g1.x, v[5] * rstd * g1.y); o.w = pk2(v[6] * rstd * g1.z, v[7] * rstd * g1.w);
;             *(u32x4*)ptr = o;
;         }
	v_add_f32_e32 v238, v238, v239
	ds_bpermute_b32 v239, v205, v238
	s_waitcnt lgkmcnt(0)
	v_add_f32_e32 v238, v238, v239
	ds_bpermute_b32 v239, v214, v238
	s_waitcnt lgkmcnt(0)
	v_add_f32_e32 v238, v238, v239
	ds_bpermute_b32 v239, v215, v238
	s_waitcnt lgkmcnt(0)
	v_add_f32_e32 v238, v238, v239
	v_fmamk_f32 v238, v238, 0x3c000000, v208
	v_mul_f32_e32 v239, 0x4f800000, v238
	v_cmp_gt_f32_e32 vcc, s33, v238
	s_nop 1
	v_cndmask_b32_e32 v238, v238, v239, vcc
	v_sqrt_f32_e32 v239, v238
	s_nop 0
	v_add_u32_e32 v240, -1, v239
	v_add_u32_e32 v241, 1, v239
	v_fma_f32 v242, -v240, v239, v238
	v_fma_f32 v243, -v241, v239, v238
	v_cmp_ge_f32_e64 s[0:1], 0, v242
	s_nop 1
	v_cndmask_b32_e64 v239, v239, v240, s[0:1]
	v_cmp_lt_f32_e64 s[0:1], 0, v243
	s_nop 1
	v_cndmask_b32_e64 v239, v239, v241, s[0:1]
	v_mul_f32_e32 v240, 0x37800000, v239
	v_cndmask_b32_e32 v239, v239, v240, vcc
	v_cmp_class_f32_e32 vcc, v238, v209
	s_nop 1
	v_cndmask_b32_e32 v238, v239, v238, vcc
	v_div_scale_f32 v239, s[0:1], v238, v238, 1.0
	v_rcp_f32_e32 v241, v239
	v_div_scale_f32 v240, vcc, 1.0, v238, 1.0
	v_fma_f32 v242, -v239, v241, 1.0
	v_fmac_f32_e32 v241, v242, v241
	v_mul_f32_e32 v242, v240, v241
	v_fma_f32 v243, -v239, v242, v240
	v_fmac_f32_e32 v242, v243, v241
	v_fma_f32 v239, -v239, v242, v240
	v_div_fmas_f32 v239, v239, v241, v242
	v_div_fixup_f32 v238, v239, v238, 1.0
	v_mul_f32_e32 v217, v217, v238
	v_mul_f32_e32 v72, v217, v72
	v_mul_f32_e32 v73, v217, v73
	v_mul_f32_e32 v74, v217, v74
	v_mul_f32_e32 v75, v217, v75
	v_mul_f32_e32 v234, v217, v234
	v_mul_f32_e32 v235, v217, v235
	v_mul_f32_e32 v236, v217, v236
	v_mul_f32_e32 v237, v217, v237
	v_mul_f32_e32 v72, v227, v72
	v_mul_f32_e32 v73, v229, v73
	v_mul_f32_e32 v74, v231, v74
	v_mul_f32_e32 v75, v233, v75
	v_mul_f32_e32 v244, v226, v234
	v_mul_f32_e32 v245, v228, v235
	v_mul_f32_e32 v246, v230, v236
	v_mul_f32_e32 v247, v232, v237
	v_cvt_pk_bf16_f32 v72, v244, v72
	v_cvt_pk_bf16_f32 v73, v245, v73
	v_cvt_pk_bf16_f32 v74, v246, v74
	v_cvt_pk_bf16_f32 v75, v247, v75
	v_add_u32_e32 v2, 0x800, v216
	v_ashrrev_i32_e32 v3, 31, v2
	v_lshl_add_u64 v[14:15], v[2:3], 1, v[0:1]
	global_store_dwordx4 v[14:15], v[72:75], off sc1
	s_add_u32 s0, s2, 3
	s_addc_u32 s1, s79, 0
	s_mul_i32 s4, s1, 0x2200
	v_mad_u64_u32 v[0:1], s[0:1], s0, v212, v[118:119]
	v_add_u32_e32 v1, s4, v1
	s_waitcnt vmcnt(19)
	v_mov_b32_e32 v217, v211
	v_lshlrev_b32_e32 v234, 16, v76
	v_and_b32_e32 v76, 0xffff0000, v76
	v_mul_f32_e32 v238, v76, v76
	v_lshlrev_b32_e32 v235, 16, v77
	v_fmac_f32_e32 v238, v234, v234
	v_and_b32_e32 v77, 0xffff0000, v77
	v_fmac_f32_e32 v238, v235, v235
	v_lshlrev_b32_e32 v236, 16, v78
	v_fmac_f32_e32 v238, v77, v77
	v_and_b32_e32 v78, 0xffff0000, v78
	v_fmac_f32_e32 v238, v236, v236
	v_lshlrev_b32_e32 v237, 16, v79
	v_fmac_f32_e32 v238, v78, v78
	v_and_b32_e32 v79, 0xffff0000, v79
	v_fmac_f32_e32 v238, v237, v237
	v_fmac_f32_e32 v238, v79, v79
	ds_bpermute_b32 v239, v204, v238
	s_waitcnt lgkmcnt(0)
	v_add_f32_e32 v238, v238, v239
	ds_bpermute_b32 v239, v205, v238
	s_waitcnt lgkmcnt(0)
	v_add_f32_e32 v238, v238, v239
	ds_bpermute_b32 v239, v214, v238
	s_waitcnt lgkmcnt(0)
	v_add_f32_e32 v238, v238, v239
	ds_bpermute_b32 v239, v215, v238
	s_waitcnt lgkmcnt(0)
	v_add_f32_e32 v238, v238, v239
	v_fmamk_f32 v238, v238, 0x3c000000, v208
	v_mul_f32_e32 v239, 0x4f800000, v238
	v_cmp_gt_f32_e32 vcc, s33, v238
	s_nop 1
	v_cndmask_b32_e32 v238, v238, v239, vcc
	v_sqrt_f32_e32 v239, v238
	s_nop 0
	v_add_u32_e32 v240, -1, v239
	v_add_u32_e32 v241, 1, v239
	v_fma_f32 v242, -v240, v239, v238
	v_fma_f32 v243, -v241, v239, v238
	v_cmp_ge_f32_e64 s[0:1], 0, v242
	s_nop 1
	v_cndmask_b32_e64 v239, v239, v240, s[0:1]
	v_cmp_lt_f32_e64 s[0:1], 0, v243
	s_nop 1
	v_cndmask_b32_e64 v239, v239, v241, s[0:1]
	v_mul_f32_e32 v240, 0x37800000, v239
	v_cndmask_b32_e32 v239, v239, v240, vcc
	v_cmp_class_f32_e32 vcc, v238, v209
	s_nop 1
	v_cndmask_b32_e32 v238, v239, v238, vcc
	v_div_scale_f32 v239, s[0:1], v238, v238, 1.0
	v_rcp_f32_e32 v241, v239
	v_div_scale_f32 v240, vcc, 1.0, v238, 1.0
	v_fma_f32 v242, -v239, v241, 1.0
	v_fmac_f32_e32 v241, v242, v241
	v_mul_f32_e32 v242, v240, v241
	v_fma_f32 v243, -v239, v242, v240
	v_fmac_f32_e32 v242, v243, v241
	v_fma_f32 v239, -v239, v242, v240
	v_div_fmas_f32 v239, v239, v241, v242
	v_div_fixup_f32 v238, v239, v238, 1.0
	v_mul_f32_e32 v217, v217, v238
	v_mul_f32_e32 v76, v217, v76
	v_mul_f32_e32 v77, v217, v77
	v_mul_f32_e32 v78, v217, v78
	v_mul_f32_e32 v79, v217, v79
	v_mul_f32_e32 v234, v217, v234
	v_mul_f32_e32 v235, v217, v235
	v_mul_f32_e32 v236, v217, v236
	v_mul_f32_e32 v237, v217, v237
	v_mul_f32_e32 v76, v219, v76
	v_mul_f32_e32 v77, v221, v77
	v_mul_f32_e32 v78, v223, v78
	v_mul_f32_e32 v79, v225, v79
	v_mul_f32_e32 v244, v218, v234
	v_mul_f32_e32 v245, v220, v235
	v_mul_f32_e32 v246, v222, v236
	v_mul_f32_e32 v247, v224, v237
	v_cvt_pk_bf16_f32 v76, v244, v76
	v_cvt_pk_bf16_f32 v77, v245, v77
	v_cvt_pk_bf16_f32 v78, v246, v78
	v_cvt_pk_bf16_f32 v79, v247, v79
	v_mov_b32_e32 v2, v216
	v_ashrrev_i32_e32 v3, 31, v2
	v_lshl_add_u64 v[14:15], v[2:3], 1, v[0:1]
	global_store_dwordx4 v[14:15], v[76:79], off sc1
	s_waitcnt vmcnt(19)
	v_mov_b32_e32 v217, v211
	v_lshlrev_b32_e32 v234, 16, v80
	v_and_b32_e32 v80, 0xffff0000, v80
	v_mul_f32_e32 v238, v80, v80
	v_lshlrev_b32_e32 v235, 16, v81
	v_fmac_f32_e32 v238, v234, v234
	v_and_b32_e32 v81, 0xffff0000, v81
	v_fmac_f32_e32 v238, v235, v235
	v_lshlrev_b32_e32 v236, 16, v82
	v_fmac_f32_e32 v238, v81, v81
	v_and_b32_e32 v82, 0xffff0000, v82
	v_fmac_f32_e32 v238, v236, v236
	v_lshlrev_b32_e32 v237, 16, v83
	v_fmac_f32_e32 v238, v82, v82
	v_and_b32_e32 v83, 0xffff0000, v83
	v_fmac_f32_e32 v238, v237, v237
	v_fmac_f32_e32 v238, v83, v83
	ds_bpermute_b32 v239, v204, v238
	s_waitcnt lgkmcnt(0)
; __device__ __forceinline__ unsigned pk2(float lo, float hi) { return pg8::cvt_pk_bf16(lo, hi); }
; __device__ __forceinline__ void idx_unit(bf16* QB, float* SC, int* SEL, const float* qg, const float* kg, int b, int tp, LAS unsigned char* wl, int lane, bool do_norm) {
;     ...
;     for (int a = 0; a < 4; ++a)
; #pragma unroll 1
;         for (int p = 0; p < 5; ++p) {
;             const int col = (p < 4) ? (CQ + (4 * p + lg) * 128) : (CK + lg * 128);
;             bf16* ptr = QB + (row + a) * NBP + col + 8 * li;
;             const u32x4 w = *(const u32x4*)ptr;
;             float v[8] = {bflo(w.x), bfhi(w.x), bflo(w.y), bfhi(w.y), bflo(w.z), bfhi(w.z), bflo(w.w), bfhi(w.w)};
;             float s = 0.f;
; #pragma unroll
;             for (int e = 0; e < 8; ++e) s += v[e] * v[e];
;             s += __shfl_xor(s, 1); s += __shfl_xor(s, 2); s += __shfl_xor(s, 4); s += __shfl_xor(s, 8);
;             const float rstd = (1.0f / sqrtf(s * (1.f / 128.f) + RMS_EPS)) * ((p < 4) ? C2 : 1.f);
;             const float* gp = ((p < 4) ? qg : kg) + 8 * li;
;             const f32x4 g0 = *(const f32x4*)gp, g1 = *(const f32x4*)(gp + 4);
;             u32x4 o; o.x = pk2(v[0] * rstd * g0.x, v[1] * rstd * g0.y); o.y = pk2(v[2] * rstd * g0.z, v[3] * rstd * g0.w);
;             o.z = pk2(v[4] * rstd * g1.x, v[5] * rstd * g1.y); o.w = pk2(v[6] * rstd * g1.z, v[7] * rstd * g1.w);
;             *(u32x4*)ptr = o;
;         }
	v_add_f32_e32 v238, v238, v239
	ds_bpermute_b32 v239, v205, v238
	s_waitcnt lgkmcnt(0)
	v_add_f32_e32 v238, v238, v239
	ds_bpermute_b32 v239, v214, v238
	s_waitcnt lgkmcnt(0)
	v_add_f32_e32 v238, v238, v239
	ds_bpermute_b32 v239, v215, v238
	s_waitcnt lgkmcnt(0)
	v_add_f32_e32 v238, v238, v239
	v_fmamk_f32 v238, v238, 0x3c000000, v208
	v_mul_f32_e32 v239, 0x4f800000, v238
	v_cmp_gt_f32_e32 vcc, s33, v238
	s_nop 1
	v_cndmask_b32_e32 v238, v238, v239, vcc
	v_sqrt_f32_e32 v239, v238
	s_nop 0
	v_add_u32_e32 v240, -1, v239
	v_add_u32_e32 v241, 1, v239
	v_fma_f32 v242, -v240, v239, v238
	v_fma_f32 v243, -v241, v239, v238
	v_cmp_ge_f32_e64 s[0:1], 0, v242
	s_nop 1
	v_cndmask_b32_e64 v239, v239, v240, s[0:1]
	v_cmp_lt_f32_e64 s[0:1], 0, v243
	s_nop 1
	v_cndmask_b32_e64 v239, v239, v241, s[0:1]
	v_mul_f32_e32 v240, 0x37800000, v239
	v_cndmask_b32_e32 v239, v239, v240, vcc
	v_cmp_class_f32_e32 vcc, v238, v209
	s_nop 1
	v_cndmask_b32_e32 v238, v239, v238, vcc
	v_div_scale_f32 v239, s[0:1], v238, v238, 1.0
	v_rcp_f32_e32 v241, v239
	v_div_scale_f32 v240, vcc, 1.0, v238, 1.0
	v_fma_f32 v242, -v239, v241, 1.0
	v_fmac_f32_e32 v241, v242, v241
	v_mul_f32_e32 v242, v240, v241
	v_fma_f32 v243, -v239, v242, v240
	v_fmac_f32_e32 v242, v243, v241
	v_fma_f32 v239, -v239, v242, v240
	v_div_fmas_f32 v239, v239, v241, v242
	v_div_fixup_f32 v238, v239, v238, 1.0
	v_mul_f32_e32 v217, v217, v238
	v_mul_f32_e32 v80, v217, v80
	v_mul_f32_e32 v81, v217, v81
	v_mul_f32_e32 v82, v217, v82
	v_mul_f32_e32 v83, v217, v83
	v_mul_f32_e32 v234, v217, v234
	v_mul_f32_e32 v235, v217, v235
	v_mul_f32_e32 v236, v217, v236
	v_mul_f32_e32 v237, v217, v237
	v_mul_f32_e32 v80, v219, v80
	v_mul_f32_e32 v81, v221, v81
	v_mul_f32_e32 v82, v223, v82
	v_mul_f32_e32 v83, v225, v83
	v_mul_f32_e32 v244, v218, v234
	v_mul_f32_e32 v245, v220, v235
	v_mul_f32_e32 v246, v222, v236
	v_mul_f32_e32 v247, v224, v237
	v_cvt_pk_bf16_f32 v80, v244, v80
	v_cvt_pk_bf16_f32 v81, v245, v81
	v_cvt_pk_bf16_f32 v82, v246, v82
	v_cvt_pk_bf16_f32 v83, v247, v83
	v_add_u32_e32 v2, 0x200, v216
	v_ashrrev_i32_e32 v3, 31, v2
	v_lshl_add_u64 v[14:15], v[2:3], 1, v[0:1]
	global_store_dwordx4 v[14:15], v[80:83], off sc1
	s_waitcnt vmcnt(19)
	v_mov_b32_e32 v217, v211
	v_lshlrev_b32_e32 v234, 16, v84
	v_and_b32_e32 v84, 0xffff0000, v84
	v_mul_f32_e32 v238, v84, v84
	v_lshlrev_b32_e32 v235, 16, v85
	v_fmac_f32_e32 v238, v234, v234
	v_and_b32_e32 v85, 0xffff0000, v85
	v_fmac_f32_e32 v238, v235, v235
	v_lshlrev_b32_e32 v236, 16, v86
	v_fmac_f32_e32 v238, v85, v85
	v_and_b32_e32 v86, 0xffff0000, v86
	v_fmac_f32_e32 v238, v236, v236
	v_lshlrev_b32_e32 v237, 16, v87
	v_fmac_f32_e32 v238, v86, v86
	v_and_b32_e32 v87, 0xffff0000, v87
	v_fmac_f32_e32 v238, v237, v237
	v_fmac_f32_e32 v238, v87, v87
	ds_bpermute_b32 v239, v204, v238
	s_waitcnt lgkmcnt(0)
	v_add_f32_e32 v238, v238, v239
	ds_bpermute_b32 v239, v205, v238
	s_waitcnt lgkmcnt(0)
	v_add_f32_e32 v238, v238, v239
	ds_bpermute_b32 v239, v214, v238
	s_waitcnt lgkmcnt(0)
	v_add_f32_e32 v238, v238, v239
	ds_bpermute_b32 v239, v215, v238
	s_waitcnt lgkmcnt(0)
	v_add_f32_e32 v238, v238, v239
	v_fmamk_f32 v238, v238, 0x3c000000, v208
	v_mul_f32_e32 v239, 0x4f800000, v238
	v_cmp_gt_f32_e32 vcc, s33, v238
	s_nop 1
	v_cndmask_b32_e32 v238, v238, v239, vcc
	v_sqrt_f32_e32 v239, v238
	s_nop 0
	v_add_u32_e32 v240, -1, v239
	v_add_u32_e32 v241, 1, v239
	v_fma_f32 v242, -v240, v239, v238
	v_fma_f32 v243, -v241, v239, v238
	v_cmp_ge_f32_e64 s[0:1], 0, v242
	s_nop 1
	v_cndmask_b32_e64 v239, v239, v240, s[0:1]
	v_cmp_lt_f32_e64 s[0:1], 0, v243
	s_nop 1
	v_cndmask_b32_e64 v239, v239, v241, s[0:1]
	v_mul_f32_e32 v240, 0x37800000, v239
	v_cndmask_b32_e32 v239, v239, v240, vcc
	v_cmp_class_f32_e32 vcc, v238, v209
	s_nop 1
	v_cndmask_b32_e32 v238, v239, v238, vcc
	v_div_scale_f32 v239, s[0:1], v238, v238, 1.0
	v_rcp_f32_e32 v241, v239
	v_div_scale_f32 v240, vcc, 1.0, v238, 1.0
	v_fma_f32 v242, -v239, v241, 1.0
	v_fmac_f32_e32 v241, v242, v241
	v_mul_f32_e32 v242, v240, v241
	v_fma_f32 v243, -v239, v242, v240
	v_fmac_f32_e32 v242, v243, v241
	v_fma_f32 v239, -v239, v242, v240
	v_div_fmas_f32 v239, v239, v241, v242
	v_div_fixup_f32 v238, v239, v238, 1.0
	v_mul_f32_e32 v217, v217, v238
	v_mul_f32_e32 v84, v217, v84
	v_mul_f32_e32 v85, v217, v85
	v_mul_f32_e32 v86, v217, v86
	v_mul_f32_e32 v87, v217, v87
	v_mul_f32_e32 v234, v217, v234
	v_mul_f32_e32 v235, v217, v235
	v_mul_f32_e32 v236, v217, v236
	v_mul_f32_e32 v237, v217, v237
	v_mul_f32_e32 v84, v219, v84
	v_mul_f32_e32 v85, v221, v85
	v_mul_f32_e32 v86, v223, v86
	v_mul_f32_e32 v87, v225, v87
	v_mul_f32_e32 v244, v218, v234
	v_mul_f32_e32 v245, v220, v235
	v_mul_f32_e32 v246, v222, v236
	v_mul_f32_e32 v247, v224, v237
	v_cvt_pk_bf16_f32 v84, v244, v84
	v_cvt_pk_bf16_f32 v85, v245, v85
	v_cvt_pk_bf16_f32 v86, v246, v86
	v_cvt_pk_bf16_f32 v87, v247, v87
	v_add_u32_e32 v2, 0x400, v216
	v_ashrrev_i32_e32 v3, 31, v2
	v_lshl_add_u64 v[14:15], v[2:3], 1, v[0:1]
	global_store_dwordx4 v[14:15], v[84:87], off sc1
	s_waitcnt vmcnt(19)
	v_mov_b32_e32 v217, v211
	v_lshlrev_b32_e32 v234, 16, v88
	v_and_b32_e32 v88, 0xffff0000, v88
	v_mul_f32_e32 v238, v88, v88
	v_lshlrev_b32_e32 v235, 16, v89
	v_fmac_f32_e32 v238, v234, v234
	v_and_b32_e32 v89, 0xffff0000, v89
	v_fmac_f32_e32 v238, v235, v235
	v_lshlrev_b32_e32 v236, 16, v90
	v_fmac_f32_e32 v238, v89, v89
	v_and_b32_e32 v90, 0xffff0000, v90
	v_fmac_f32_e32 v238, v236, v236
	v_lshlrev_b32_e32 v237, 16, v91
	v_fmac_f32_e32 v238, v90, v90
	v_and_b32_e32 v91, 0xffff0000, v91
	v_fmac_f32_e32 v238, v237, v237
	v_fmac_f32_e32 v238, v91, v91
	ds_bpermute_b32 v239, v204, v238
	s_waitcnt lgkmcnt(0)
; __device__ __forceinline__ unsigned pk2(float lo, float hi) { return pg8::cvt_pk_bf16(lo, hi); }
; __device__ __forceinline__ void idx_unit(bf16* QB, float* SC, int* SEL, const float* qg, const float* kg, int b, int tp, LAS unsigned char* wl, int lane, bool do_norm) {
;     ...
;     for (int a = 0; a < 4; ++a)
; #pragma unroll 1
;         for (int p = 0; p < 5; ++p) {
;             const int col = (p < 4) ? (CQ + (4 * p + lg) * 128) : (CK + lg * 128);
;             bf16* ptr = QB + (row + a) * NBP + col + 8 * li;
;             const u32x4 w = *(const u32x4*)ptr;
;             float v[8] = {bflo(w.x), bfhi(w.x), bflo(w.y), bfhi(w.y), bflo(w.z), bfhi(w.z), bflo(w.w), bfhi(w.w)};
;             float s = 0.f;
; #pragma unroll
;             for (int e = 0; e < 8; ++e) s += v[e] * v[e];
;             s += __shfl_xor(s, 1); s += __shfl_xor(s, 2); s += __shfl_xor(s, 4); s += __shfl_xor(s, 8);
;             const float rstd = (1.0f / sqrtf(s * (1.f / 128.f) + RMS_EPS)) * ((p < 4) ? C2 : 1.f);
;             const float* gp = ((p < 4) ? qg : kg) + 8 * li;
;             const f32x4 g0 = *(const f32x4*)gp, g1 = *(const f32x4*)(gp + 4);
;             u32x4 o; o.x = pk2(v[0] * rstd * g0.x, v[1] * rstd * g0.y); o.y = pk2(v[2] * rstd * g0.z, v[3] * rstd * g0.w);
;             o.z = pk2(v[4] * rstd * g1.x, v[5] * rstd * g1.y); o.w = pk2(v[6] * rstd * g1.z, v[7] * rstd * g1.w);
;             *(u32x4*)ptr = o;
;         }
	v_add_f32_e32 v238, v238, v239
	ds_bpermute_b32 v239, v205, v238
	s_waitcnt lgkmcnt(0)
	v_add_f32_e32 v238, v238, v239
	ds_bpermute_b32 v239, v214, v238
	s_waitcnt lgkmcnt(0)
	v_add_f32_e32 v238, v238, v239
	ds_bpermute_b32 v239, v215, v238
	s_waitcnt lgkmcnt(0)
	v_add_f32_e32 v238, v238, v239
	v_fmamk_f32 v238, v238, 0x3c000000, v208
	v_mul_f32_e32 v239, 0x4f800000, v238
	v_cmp_gt_f32_e32 vcc, s33, v238
	s_nop 1
	v_cndmask_b32_e32 v238, v238, v239, vcc
	v_sqrt_f32_e32 v239, v238
	s_nop 0
	v_add_u32_e32 v240, -1, v239
	v_add_u32_e32 v241, 1, v239
	v_fma_f32 v242, -v240, v239, v238
	v_fma_f32 v243, -v241, v239, v238
	v_cmp_ge_f32_e64 s[0:1], 0, v242
	s_nop 1
	v_cndmask_b32_e64 v239, v239, v240, s[0:1]
	v_cmp_lt_f32_e64 s[0:1], 0, v243
	s_nop 1
	v_cndmask_b32_e64 v239, v239, v241, s[0:1]
	v_mul_f32_e32 v240, 0x37800000, v239
	v_cndmask_b32_e32 v239, v239, v240, vcc
	v_cmp_class_f32_e32 vcc, v238, v209
	s_nop 1
	v_cndmask_b32_e32 v238, v239, v238, vcc
	v_div_scale_f32 v239, s[0:1], v238, v238, 1.0
	v_rcp_f32_e32 v241, v239
	v_div_scale_f32 v240, vcc, 1.0, v238, 1.0
	v_fma_f32 v242, -v239, v241, 1.0
	v_fmac_f32_e32 v241, v242, v241
	v_mul_f32_e32 v242, v240, v241
	v_fma_f32 v243, -v239, v242, v240
	v_fmac_f32_e32 v242, v243, v241
	v_fma_f32 v239, -v239, v242, v240
	v_div_fmas_f32 v239, v239, v241, v242
	v_div_fixup_f32 v238, v239, v238, 1.0
	v_mul_f32_e32 v217, v217, v238
	v_mul_f32_e32 v88, v217, v88
	v_mul_f32_e32 v89, v217, v89
	v_mul_f32_e32 v90, v217, v90
	v_mul_f32_e32 v91, v217, v91
	v_mul_f32_e32 v234, v217, v234
	v_mul_f32_e32 v235, v217, v235
	v_mul_f32_e32 v236, v217, v236
	v_mul_f32_e32 v237, v217, v237
	v_mul_f32_e32 v88, v219, v88
	v_mul_f32_e32 v89, v221, v89
	v_mul_f32_e32 v90, v223, v90
	v_mul_f32_e32 v91, v225, v91
	v_mul_f32_e32 v244, v218, v234
	v_mul_f32_e32 v245, v220, v235
	v_mul_f32_e32 v246, v222, v236
	v_mul_f32_e32 v247, v224, v237
	v_cvt_pk_bf16_f32 v88, v244, v88
	v_cvt_pk_bf16_f32 v89, v245, v89
	v_cvt_pk_bf16_f32 v90, v246, v90
	v_cvt_pk_bf16_f32 v91, v247, v91
	v_add_u32_e32 v2, 0x600, v216
	v_ashrrev_i32_e32 v3, 31, v2
	v_lshl_add_u64 v[14:15], v[2:3], 1, v[0:1]
	global_store_dwordx4 v[14:15], v[88:91], off sc1
	s_waitcnt vmcnt(19)
	v_mov_b32_e32 v217, 1.0
	v_lshlrev_b32_e32 v234, 16, v92
	v_and_b32_e32 v92, 0xffff0000, v92
	v_mul_f32_e32 v238, v92, v92
	v_lshlrev_b32_e32 v235, 16, v93
	v_fmac_f32_e32 v238, v234, v234
	v_and_b32_e32 v93, 0xffff0000, v93
	v_fmac_f32_e32 v238, v235, v235
	v_lshlrev_b32_e32 v236, 16, v94
	v_fmac_f32_e32 v238, v93, v93
	v_and_b32_e32 v94, 0xffff0000, v94
	v_fmac_f32_e32 v238, v236, v236
	v_lshlrev_b32_e32 v237, 16, v95
	v_fmac_f32_e32 v238, v94, v94
	v_and_b32_e32 v95, 0xffff0000, v95
	v_fmac_f32_e32 v238, v237, v237
	v_fmac_f32_e32 v238, v95, v95
	ds_bpermute_b32 v239, v204, v238
	s_waitcnt lgkmcnt(0)
	v_add_f32_e32 v238, v238, v239
	ds_bpermute_b32 v239, v205, v238
	s_waitcnt lgkmcnt(0)
	v_add_f32_e32 v238, v238, v239
	ds_bpermute_b32 v239, v214, v238
	s_waitcnt lgkmcnt(0)
	v_add_f32_e32 v238, v238, v239
	ds_bpermute_b32 v239, v215, v238
	s_waitcnt lgkmcnt(0)
	v_add_f32_e32 v238, v238, v239
	v_fmamk_f32 v238, v238, 0x3c000000, v208
	v_mul_f32_e32 v239, 0x4f800000, v238
	v_cmp_gt_f32_e32 vcc, s33, v238
	s_nop 1
	v_cndmask_b32_e32 v238, v238, v239, vcc
	v_sqrt_f32_e32 v239, v238
	s_nop 0
	v_add_u32_e32 v240, -1, v239
	v_add_u32_e32 v241, 1, v239
	v_fma_f32 v242, -v240, v239, v238
	v_fma_f32 v243, -v241, v239, v238
	v_cmp_ge_f32_e64 s[0:1], 0, v242
	s_nop 1
	v_cndmask_b32_e64 v239, v239, v240, s[0:1]
	v_cmp_lt_f32_e64 s[0:1], 0, v243
	s_nop 1
	v_cndmask_b32_e64 v239, v239, v241, s[0:1]
	v_mul_f32_e32 v240, 0x37800000, v239
	v_cndmask_b32_e32 v239, v239, v240, vcc
	v_cmp_class_f32_e32 vcc, v238, v209
	s_nop 1
	v_cndmask_b32_e32 v238, v239, v238, vcc
	v_div_scale_f32 v239, s[0:1], v238, v238, 1.0
	v_rcp_f32_e32 v241, v239
	v_div_scale_f32 v240, vcc, 1.0, v238, 1.0
	v_fma_f32 v242, -v239, v241, 1.0
	v_fmac_f32_e32 v241, v242, v241
	v_mul_f32_e32 v242, v240, v241
	v_fma_f32 v243, -v239, v242, v240
	v_fmac_f32_e32 v242, v243, v241
	v_fma_f32 v239, -v239, v242, v240
	v_div_fmas_f32 v239, v239, v241, v242
	v_div_fixup_f32 v238, v239, v238, 1.0
	v_mul_f32_e32 v217, v217, v238
	v_mul_f32_e32 v92, v217, v92
	v_mul_f32_e32 v93, v217, v93
	v_mul_f32_e32 v94, v217, v94
	v_mul_f32_e32 v95, v217, v95
	v_mul_f32_e32 v234, v217, v234
	v_mul_f32_e32 v235, v217, v235
	v_mul_f32_e32 v236, v217, v236
	v_mul_f32_e32 v237, v217, v237
	v_mul_f32_e32 v92, v227, v92
	v_mul_f32_e32 v93, v229, v93
	v_mul_f32_e32 v94, v231, v94
	v_mul_f32_e32 v95, v233, v95
	v_mul_f32_e32 v244, v226, v234
	v_mul_f32_e32 v245, v228, v235
	v_mul_f32_e32 v246, v230, v236
	v_mul_f32_e32 v247, v232, v237
	v_cvt_pk_bf16_f32 v92, v244, v92
	v_cvt_pk_bf16_f32 v93, v245, v93
	v_cvt_pk_bf16_f32 v94, v246, v94
	v_cvt_pk_bf16_f32 v95, v247, v95
	v_add_u32_e32 v2, 0x800, v216
	v_ashrrev_i32_e32 v3, 31, v2
	v_lshl_add_u64 v[14:15], v[2:3], 1, v[0:1]
	global_store_dwordx4 v[14:15], v[92:95], off sc1
	s_mov_b32 s3, 4
	s_add_i32 s11, s11, 1
	s_mul_i32 s2, s11, s84
	s_cmpk_gt_i32 s2, 0xfff
	v_readlane_b32 s78, v253, 53
	s_cselect_b64 s[0:1], -1, 0
	v_readlane_b32 s79, v253, 54
	s_movk_i32 s90, 0x2000
	s_movk_i32 s91, 0x2200
	s_mov_b64 s[96:97], 0x2000
	s_branch .LBB0_229

; #define LAS __attribute__((address_space(3)))
; #define LDS_WAIT() asm volatile("s_waitcnt lgkmcnt(0)" ::: "memory")
; __device__ __forceinline__ s16x4 vtr(const LAS unsigned char* p) { return __builtin_bit_cast(s16x4, __builtin_amdgcn_ds_read_tr16_b64_v4i16((LAS s16x4*)p)); }
; __device__ __forceinline__ void dsa_unit(const bf16* QB, const int* SEL, bf16* AO, int b, int kvh, int t, LAS unsigned char* wl, int lane) {
;     ...
;         f32x4v a0 = {0.f, 0.f, 0.f, 0.f}, a1 = {0.f, 0.f, 0.f, 0.f};
; #pragma unroll
;         for (int ks = 0; ks < 4; ++ks) { const bf16x8 b0 = *(const LAS bf16x8*)(kfb + 64 * ks), b1 = *(const LAS bf16x8*)(kfb + 16 * 272 + 64 * ks);
;             a0 = __builtin_amdgcn_mfma_f32_16x16x32_bf16(qf[ks], b0, a0, 0, 0, 0); a1 = __builtin_amdgcn_mfma_f32_16x16x32_bf16(qf[ks], b1, a1, 0, 0, 0); }
;         LDS_WAIT();
;         const int bk = t5_bucket(sidx[kb] - t);
;         const bool valid = (32 * kb + n) < nsel;
; #pragma unroll
;         for (int g = 0; g < 4; ++g) { const float raw = upper ? a1[g] : a0[g]; const float v = valid ? raw + bl[g * 32 + bk] : -__builtin_inff(); lg[kb][g] = v; mx[g] = __builtin_fmaxf(mx[g], v); }
;     ...
;     for (int ch = 0; ch < 8; ++ch) {
; #pragma unroll
;         for (int i = 0; i < 8; ++i) *(LAS bf16x8*)(vdst + (4 * i) * 288) = vr[ch % 3][i];
;         if (ch + 3 < 8) {
; #pragma unroll
;             for (int i = 0; i < 8; ++i) vr[ch % 3][i] = *(const bf16x8*)(vg + (size_t)il[32 * (ch + 3) + 4 * i + r4] * NBP);
;         }
;         const bf16x8 pf = *(const LAS bf16x8*)(pfp + 32 * ch);
;         LDS_WAIT();
; #pragma unroll
;         for (int c = 0; c < 8; ++c) {
;             const s16x4 lo = vtr(vtb + c * 32), hh = vtr(vtb + 4 * 288 + c * 32);
;             o[c] = __builtin_amdgcn_mfma_f32_16x16x32_bf16(pf, (bf16x8){lo[0], lo[1], lo[2], lo[3], hh[0], hh[1], hh[2], hh[3]}, o[c], 0, 0, 0);
;         }
.Ldsa_farB:
	ds_read_b32 v174, v172 offset:8
	ds_read_b32 v182, v172 offset:12
	s_nop 1
	s_waitcnt lgkmcnt(5)
	v_mfma_f32_32x32x16_bf16 v[128:143], v[112:115], v[80:83], v[128:143]
	ds_read_b128 v[112:115], v168 offset:8832
	v_exp_f32_e32 v64, v64
	v_exp_f32_e32 v65, v65
	v_add_f32_e32 v173, v173, v64
	v_add_f32_e32 v173, v173, v65
	v_cvt_pk_bf16_f32 v64, v64, v65
	s_waitcnt lgkmcnt(5)
	v_mfma_f32_32x32x16_bf16 v[128:143], v[116:119], v[84:87], v[128:143]
	ds_read_b128 v[116:119], v168 offset:8864
	v_exp_f32_e32 v66, v66
	v_exp_f32_e32 v67, v67
	v_add_f32_e32 v173, v173, v66
	v_add_f32_e32 v173, v173, v67
	v_cvt_pk_bf16_f32 v65, v66, v67
	s_waitcnt lgkmcnt(5)
	v_mfma_f32_32x32x16_bf16 v[128:143], v[120:123], v[88:91], v[128:143]
	ds_read_b128 v[120:123], v168 offset:8896
	v_exp_f32_e32 v68, v68
	v_exp_f32_e32 v69, v69
	v_add_f32_e32 v173, v173, v68
	v_add_f32_e32 v173, v173, v69
	v_cvt_pk_bf16_f32 v66, v68, v69
	s_waitcnt lgkmcnt(5)
	v_mfma_f32_32x32x16_bf16 v[128:143], v[124:127], v[92:95], v[128:143]
	ds_read_b128 v[124:127], v168 offset:8928
	v_exp_f32_e32 v70, v70
	v_exp_f32_e32 v71, v71
	v_add_f32_e32 v173, v173, v70
	v_add_f32_e32 v173, v173, v71
	v_cvt_pk_bf16_f32 v67, v70, v71
	s_waitcnt lgkmcnt(3)
	v_mfma_f32_32x32x16_bf16 v[128:143], v[112:115], v[96:99], v[128:143]
	ds_read_b64_tr_b16 v[112:113], v169 offset:0
	ds_read_b64_tr_b16 v[114:115], v169 offset:1152
	v_exp_f32_e32 v72, v72
	v_exp_f32_e32 v73, v73
	v_add_f32_e32 v173, v173, v72
	v_add_f32_e32 v173, v173, v73
	v_cvt_pk_bf16_f32 v68, v72, v73
	s_waitcnt lgkmcnt(4)
	v_mfma_f32_32x32x16_bf16 v[128:143], v[116:119], v[100:103], v[128:143]
	ds_read_b64_tr_b16 v[116:117], v169 offset:64
	ds_read_b64_tr_b16 v[118:119], v169 offset:1216
	v_exp_f32_e32 v74, v74
	v_exp_f32_e32 v75, v75
	v_add_f32_e32 v173, v173, v74
	v_add_f32_e32 v173, v173, v75
	v_cvt_pk_bf16_f32 v69, v74, v75
	s_waitcnt lgkmcnt(5)
	v_mfma_f32_32x32x16_bf16 v[128:143], v[120:123], v[104:107], v[128:143]
	ds_read_b64_tr_b16 v[120:121], v169 offset:128
	ds_read_b64_tr_b16 v[122:123], v169 offset:1280
	v_exp_f32_e32 v76, v76
	v_exp_f32_e32 v77, v77
	v_add_f32_e32 v173, v173, v76
	v_add_f32_e32 v173, v173, v77
	v_cvt_pk_bf16_f32 v70, v76, v77
	s_waitcnt lgkmcnt(6)
	v_mfma_f32_32x32x16_bf16 v[128:143], v[124:127], v[108:111], v[128:143]
	ds_read_b64_tr_b16 v[124:125], v169 offset:192
	ds_read_b64_tr_b16 v[126:127], v169 offset:1344
	v_exp_f32_e32 v78, v78
	v_exp_f32_e32 v79, v79
	v_add_f32_e32 v173, v173, v78
	v_add_f32_e32 v173, v173, v79
	v_cvt_pk_bf16_f32 v71, v78, v79
	s_waitcnt lgkmcnt(6)
	v_mfma_f32_32x32x16_bf16 v[0:15], v[64:67], v[112:115], v[0:15]
	ds_read_b64_tr_b16 v[112:113], v169 offset:4608
	ds_read_b64_tr_b16 v[114:115], v169 offset:5760
	s_waitcnt vmcnt(0)
	ds_write_b128 v170, v[144:147]
	v_exp_f32_e32 v128, v128
	v_exp_f32_e32 v129, v129
	v_add_f32_e32 v173, v173, v128
	v_add_f32_e32 v173, v173, v129
	v_cvt_pk_bf16_f32 v128, v128, v129
	s_waitcnt lgkmcnt(7)
	v_mfma_f32_32x32x16_bf16 v[16:31], v[64:67], v[116:119], v[16:31]
	ds_read_b64_tr_b16 v[116:117], v169 offset:4672
	ds_read_b64_tr_b16 v[118:119], v169 offset:5824
	ds_write_b128 v171, v[148:151]
	v_exp_f32_e32 v130, v130
	v_exp_f32_e32 v131, v131
	v_add_f32_e32 v173, v173, v130
	v_add_f32_e32 v173, v173, v131
	v_cvt_pk_bf16_f32 v129, v130, v131
	s_waitcnt lgkmcnt(8)
	v_mfma_f32_32x32x16_bf16 v[32:47], v[64:67], v[120:123], v[32:47]
	ds_read_b64_tr_b16 v[120:121], v169 offset:4736
	ds_read_b64_tr_b16 v[122:123], v169 offset:5888
	ds_write_b128 v170, v[152:155] offset:8704
	v_exp_f32_e32 v132, v132
	v_exp_f32_e32 v133, v133
	v_add_f32_e32 v173, v173, v132
	v_add_f32_e32 v173, v173, v133
	v_cvt_pk_bf16_f32 v130, v132, v133
	s_waitcnt lgkmcnt(9)
	v_mfma_f32_32x32x16_bf16 v[48:63], v[64:67], v[124:127], v[48:63]
	ds_read_b64_tr_b16 v[124:125], v169 offset:4800
	ds_read_b64_tr_b16 v[126:127], v169 offset:5952
	ds_write_b128 v171, v[156:159] offset:9216
	v_exp_f32_e32 v134, v134
	v_exp_f32_e32 v135, v135
	v_add_f32_e32 v173, v173, v134
	v_add_f32_e32 v173, v173, v135
	v_cvt_pk_bf16_f32 v131, v134, v135
	s_waitcnt lgkmcnt(10)
	v_mfma_f32_32x32x16_bf16 v[0:15], v[68:71], v[112:115], v[0:15]
	ds_read_b64_tr_b16 v[112:113], v169 offset:9216
	ds_read_b64_tr_b16 v[114:115], v169 offset:10368
	s_nop 0
	v_exp_f32_e32 v136, v136
	v_exp_f32_e32 v137, v137
	v_add_f32_e32 v173, v173, v136
	v_add_f32_e32 v173, v173, v137
	v_cvt_pk_bf16_f32 v132, v136, v137
	s_waitcnt lgkmcnt(9)
	v_mfma_f32_32x32x16_bf16 v[16:31], v[68:71], v[116:119], v[16:31]
	ds_read_b64_tr_b16 v[116:117], v169 offset:9280
	ds_read_b64_tr_b16 v[118:119], v169 offset:10432
	s_nop 0
	v_exp_f32_e32 v138, v138
	v_exp_f32_e32 v139, v139
	v_add_f32_e32 v173, v173, v138
	v_add_f32_e32 v173, v173, v139
	v_cvt_pk_bf16_f32 v133, v138, v139
	s_waitcnt lgkmcnt(8)
	v_mfma_f32_32x32x16_bf16 v[32:47], v[68:71], v[120:123], v[32:47]
	ds_read_b64_tr_b16 v[120:121], v169 offset:9344
	ds_read_b64_tr_b16 v[122:123], v169 offset:10496
	s_nop 0
	v_exp_f32_e32 v140, v140
	v_exp_f32_e32 v141, v141
	v_add_f32_e32 v173, v173, v140
	v_add_f32_e32 v173, v173, v141
	v_cvt_pk_bf16_f32 v134, v140, v141
	s_waitcnt lgkmcnt(7)
	v_mfma_f32_32x32x16_bf16 v[48:63], v[68:71], v[124:127], v[48:63]
	ds_read_b64_tr_b16 v[124:125], v169 offset:9408
	ds_read_b64_tr_b16 v[126:127], v169 offset:10560
	s_nop 0
	v_exp_f32_e32 v142, v142
	v_exp_f32_e32 v143, v143
	v_add_f32_e32 v173, v173, v142
	v_add_f32_e32 v173, v173, v143
	v_cvt_pk_bf16_f32 v135, v142, v143
	v_lshrrev_b32_e32 v174, v175, v174
	s_waitcnt lgkmcnt(6)
; #define LAS __attribute__((address_space(3)))
; #define LDS_WAIT() asm volatile("s_waitcnt lgkmcnt(0)" ::: "memory")
; __device__ __forceinline__ s16x4 vtr(const LAS unsigned char* p) { return __builtin_bit_cast(s16x4, __builtin_amdgcn_ds_read_tr16_b64_v4i16((LAS s16x4*)p)); }
; __device__ __forceinline__ void dsa_unit(const bf16* QB, const int* SEL, bf16* AO, int b, int kvh, int t, LAS unsigned char* wl, int lane) {
;     ...
;         const bool valid = (32 * kb + n) < nsel;
; #pragma unroll
;         for (int g = 0; g < 4; ++g) { const float raw = upper ? a1[g] : a0[g]; const float v = valid ? raw + bl[g * 32 + bk] : -__builtin_inff(); lg[kb][g] = v; mx[g] = __builtin_fmaxf(mx[g], v); }
;     ...
;     for (int ch = 0; ch < 8; ++ch) {
; #pragma unroll
;         for (int i = 0; i < 8; ++i) *(LAS bf16x8*)(vdst + (4 * i) * 288) = vr[ch % 3][i];
;         if (ch + 3 < 8) {
; #pragma unroll
;             for (int i = 0; i < 8; ++i) vr[ch % 3][i] = *(const bf16x8*)(vg + (size_t)il[32 * (ch + 3) + 4 * i + r4] * NBP);
;         }
;         const bf16x8 pf = *(const LAS bf16x8*)(pfp + 32 * ch);
;         LDS_WAIT();
; #pragma unroll
;         for (int c = 0; c < 8; ++c) {
;             const s16x4 lo = vtr(vtb + c * 32), hh = vtr(vtb + 4 * 288 + c * 32);
;             o[c] = __builtin_amdgcn_mfma_f32_16x16x32_bf16(pf, (bf16x8){lo[0], lo[1], lo[2], lo[3], hh[0], hh[1], hh[2], hh[3]}, o[c], 0, 0, 0);
;         }
	v_mfma_f32_32x32x16_bf16 v[0:15], v[128:131], v[112:115], v[0:15]
	ds_read_b64_tr_b16 v[112:113], v169 offset:13824
	ds_read_b64_tr_b16 v[114:115], v169 offset:14976
	v_bfe_i32 v178, v174, 0, 1
	v_bfi_b32 v64, v178, v176, s13
	v_bfe_i32 v179, v174, 1, 1
	v_bfi_b32 v65, v179, v176, s13
	s_waitcnt lgkmcnt(6)
	v_mfma_f32_32x32x16_bf16 v[16:31], v[128:131], v[116:119], v[16:31]
	ds_read_b64_tr_b16 v[116:117], v169 offset:13888
	ds_read_b64_tr_b16 v[118:119], v169 offset:15040
	v_bfe_i32 v178, v174, 2, 1
	v_bfi_b32 v66, v178, v176, s13
	v_bfe_i32 v179, v174, 3, 1
	v_bfi_b32 v67, v179, v176, s13
	s_waitcnt lgkmcnt(6)
	v_mfma_f32_32x32x16_bf16 v[32:47], v[128:131], v[120:123], v[32:47]
	ds_read_b64_tr_b16 v[120:121], v169 offset:13952
	ds_read_b64_tr_b16 v[122:123], v169 offset:15104
	v_bfe_i32 v178, v174, 4, 1
	v_bfi_b32 v68, v178, v176, s13
	v_bfe_i32 v179, v174, 5, 1
	v_bfi_b32 v69, v179, v176, s13
	s_waitcnt lgkmcnt(6)
	v_mfma_f32_32x32x16_bf16 v[48:63], v[128:131], v[124:127], v[48:63]
	ds_read_b64_tr_b16 v[124:125], v169 offset:14016
	ds_read_b64_tr_b16 v[126:127], v169 offset:15168
	v_bfe_i32 v178, v174, 6, 1
	v_bfi_b32 v70, v178, v176, s13
	v_bfe_i32 v179, v174, 7, 1
	v_bfi_b32 v71, v179, v176, s13
	s_waitcnt lgkmcnt(6)
	v_mfma_f32_32x32x16_bf16 v[0:15], v[132:135], v[112:115], v[0:15]
	v_bfe_i32 v178, v174, 16, 1
	v_bfi_b32 v72, v178, v176, s13
	v_bfe_i32 v179, v174, 17, 1
	v_bfi_b32 v73, v179, v176, s13
	s_waitcnt lgkmcnt(4)
	v_mfma_f32_32x32x16_bf16 v[16:31], v[132:135], v[116:119], v[16:31]
	v_bfe_i32 v178, v174, 18, 1
	v_bfi_b32 v74, v178, v176, s13
	v_bfe_i32 v179, v174, 19, 1
	v_bfi_b32 v75, v179, v176, s13
	s_waitcnt lgkmcnt(2)
	v_mfma_f32_32x32x16_bf16 v[32:47], v[132:135], v[120:123], v[32:47]
	v_bfe_i32 v178, v174, 20, 1
	v_bfi_b32 v76, v178, v176, s13
	v_bfe_i32 v179, v174, 21, 1
	v_bfi_b32 v77, v179, v176, s13
	s_waitcnt lgkmcnt(0)
	v_mfma_f32_32x32x16_bf16 v[48:63], v[132:135], v[124:127], v[48:63]
	v_bfe_i32 v178, v174, 22, 1
	v_bfi_b32 v78, v178, v176, s13
	v_bfe_i32 v179, v174, 23, 1
	v_bfi_b32 v79, v179, v176, s13
	s_waitcnt lgkmcnt(0)
	s_barrier
	s_mov_b32 s25, s10
	s_mov_b32 s10, s11
	s_mov_b32 s11, s25
	v_add_u32_e32 v172, 8, v172
	s_mov_b32 s9, s24
	s_cmp_lt_u32 s9, s8
	s_cbranch_scc1 .Ldsa_it
	v_xor_b32_e32 v178, 32, v206
	v_lshlrev_b32_e32 v178, 2, v178
	ds_bpermute_b32 v179, v178, v173
	s_waitcnt lgkmcnt(0)
	v_add_f32_e32 v173, v173, v179
	v_rcp_f32_e32 v173, v173
	s_nop 0
	v_and_b32_e32 v178, 31, v206
	v_lshlrev_b32_e32 v178, 2, v178
	s_lshl_b32 s24, s0, 7
	s_add_u32 s24, s24, 0x1a000
	v_add_u32_e32 v178, s24, v178
	ds_write_b32 v178, v173
	v_lshl_add_u32 v179, v175, 1, s24
	s_waitcnt lgkmcnt(0)
	ds_read_b128 v[112:115], v179 offset:0
	ds_read_b128 v[116:119], v179 offset:32
	ds_read_b128 v[120:123], v179 offset:64
	ds_read_b128 v[124:127], v179 offset:96
	v_and_b32_e32 v178, 31, v206
	v_lshlrev_b32_e32 v178, 1, v178
	v_mul_u32_u24_e32 v179, 0x88, v175
	v_add3_u32 v178, v178, v179, s45
	v_lshrrev_b32_e32 v179, 4, v206
	v_mul_u32_u24_e32 v182, 0x110, v179
	v_and_b32_e32 v172, 15, v206
	v_lshl_add_u32 v182, v172, 4, v182
	v_add_u32_e32 v174, s45, v182
	s_add_u32 s24, s44, s7
	s_add_u32 s24, s24, s4
	s_lshr_b32 s25, s24, 20
	s_lshl_b32 s24, s24, 12
	s_add_u32 s24, s24, s67
	s_addc_u32 s25, s25, s85
	s_lshl_b32 s26, s5, 10
	s_add_u32 s24, s24, s26
	s_addc_u32 s25, s25, 0
	v_lshlrev_b32_e32 v179, 8, v179
	v_lshl_add_u32 v182, v172, 4, v179
	v_lshl_add_u64 v[144:145], s[24:25], 0, v[182:183]
	s_movk_i32 s26, 0x1000
	s_mov_b32 s27, 0
	s_waitcnt lgkmcnt(0)
; #define LAS __attribute__((address_space(3)))
; __device__ __forceinline__ unsigned pk2(float lo, float hi) { return pg8::cvt_pk_bf16(lo, hi); }
; #define LDS_WAIT() asm volatile("s_waitcnt lgkmcnt(0)" ::: "memory")
; __device__ __forceinline__ void dsa_unit(const bf16* QB, const int* SEL, bf16* AO, int b, int kvh, int t, LAS unsigned char* wl, int lane) {
;     ...
;         for (int kb = 0; kb < 8; ++kb) { const float e = __builtin_amdgcn_exp2f(lg[kb][g] - m); lg[kb][g] = e; s += e; }
;         s += __shfl_xor(s, 1); s += __shfl_xor(s, 2); s += __shfl_xor(s, 4); s += __shfl_xor(s, 8); s += __shfl_xor(s, 16);
;         const float inv = 1.0f / s;
; #pragma unroll
;         for (int kb = 0; kb < 8; ++kb) if ((kb >> 2) == hi) pT[g * 256 + 32 * kb + n] = (bf16)(pk2(lg[kb][g] * inv, 0.f) & 0xffffu);
;     }
;     f32x4v o[8];
; #pragma unroll
;     for (int c = 0; c < 8; ++c) o[c] = (f32x4v){0.f, 0.f, 0.f, 0.f};
;     const LAS unsigned char* vtb = buf + (8 * kq + (l15 >> 2)) * 288 + (lane & 3) * 8;
;     LAS unsigned char* vdst = buf + r4 * 288 + c16 * 16;
;     const LAS bf16* pfp = pT + (l15 & 3) * 256 + 8 * kq;
; #pragma unroll
;     for (int ch = 0; ch < 8; ++ch) {
; #pragma unroll
;         for (int i = 0; i < 8; ++i) *(LAS bf16x8*)(vdst + (4 * i) * 288) = vr[ch % 3][i];
;         if (ch + 3 < 8) {
; #pragma unroll
;             for (int i = 0; i < 8; ++i) vr[ch % 3][i] = *(const bf16x8*)(vg + (size_t)il[32 * (ch + 3) + 4 * i + r4] * NBP);
;         }
;         const bf16x8 pf = *(const LAS bf16x8*)(pfp + 32 * ch);
;         LDS_WAIT();
; #pragma unroll
;         for (int c = 0; c < 8; ++c) {
;             const s16x4 lo = vtr(vtb + c * 32), hh = vtr(vtb + 4 * 288 + c * 32);
;             o[c] = __builtin_amdgcn_mfma_f32_16x16x32_bf16(pf, (bf16x8){lo[0], lo[1], lo[2], lo[3], hh[0], hh[1], hh[2], hh[3]}, o[c], 0, 0, 0);
;         }
;         LDS_WAIT();
;     }
;     bf16* op = AO + row * D + (kvh * 4) * 128 + 16 * kq + l15;
; #pragma unroll
;     for (int i = 0; i < 2; ++i)
; #pragma unroll
;         for (int g = 0; g < 4; ++g) {
;             const float v = (kq == 0) ? o[4 * i][g] : (kq == 1) ? o[4 * i + 1][g] : (kq == 2) ? o[4 * i + 2][g] : o[4 * i + 3][g];
;             op[g * 128 + 64 * i] = (bf16)(pk2(v, 0.f) & 0xffffu);
;         }
	v_pk_mul_f32 v[0:1], v[0:1], v[112:113]
	v_pk_mul_f32 v[2:3], v[2:3], v[114:115]
	v_pk_mul_f32 v[4:5], v[4:5], v[116:117]
	v_pk_mul_f32 v[6:7], v[6:7], v[118:119]
	v_pk_mul_f32 v[8:9], v[8:9], v[120:121]
	v_pk_mul_f32 v[10:11], v[10:11], v[122:123]
	v_pk_mul_f32 v[12:13], v[12:13], v[124:125]
	v_pk_mul_f32 v[14:15], v[14:15], v[126:127]
	v_pk_mul_f32 v[16:17], v[16:17], v[112:113]
	v_pk_mul_f32 v[18:19], v[18:19], v[114:115]
	v_pk_mul_f32 v[20:21], v[20:21], v[116:117]
	v_pk_mul_f32 v[22:23], v[22:23], v[118:119]
	v_pk_mul_f32 v[24:25], v[24:25], v[120:121]
	v_pk_mul_f32 v[26:27], v[26:27], v[122:123]
	v_pk_mul_f32 v[28:29], v[28:29], v[124:125]
	v_pk_mul_f32 v[30:31], v[30:31], v[126:127]
	v_pk_mul_f32 v[32:33], v[32:33], v[112:113]
	v_pk_mul_f32 v[34:35], v[34:35], v[114:115]
	v_pk_mul_f32 v[36:37], v[36:37], v[116:117]
	v_pk_mul_f32 v[38:39], v[38:39], v[118:119]
	v_pk_mul_f32 v[40:41], v[40:41], v[120:121]
	v_pk_mul_f32 v[42:43], v[42:43], v[122:123]
	v_pk_mul_f32 v[44:45], v[44:45], v[124:125]
	v_pk_mul_f32 v[46:47], v[46:47], v[126:127]
	v_pk_mul_f32 v[48:49], v[48:49], v[112:113]
	v_pk_mul_f32 v[50:51], v[50:51], v[114:115]
	v_pk_mul_f32 v[52:53], v[52:53], v[116:117]
	v_pk_mul_f32 v[54:55], v[54:55], v[118:119]
	v_pk_mul_f32 v[56:57], v[56:57], v[120:121]
	v_pk_mul_f32 v[58:59], v[58:59], v[122:123]
	v_pk_mul_f32 v[60:61], v[60:61], v[124:125]
	v_pk_mul_f32 v[62:63], v[62:63], v[126:127]
	v_cvt_pk_bf16_f32 v64, v0, v1
	v_cvt_pk_bf16_f32 v65, v2, v3
	v_cvt_pk_bf16_f32 v66, v4, v5
	v_cvt_pk_bf16_f32 v67, v6, v7
	v_cvt_pk_bf16_f32 v68, v8, v9
	v_cvt_pk_bf16_f32 v69, v10, v11
	v_cvt_pk_bf16_f32 v70, v12, v13
	v_cvt_pk_bf16_f32 v71, v14, v15
	ds_write_b16 v178, v64 offset:0
	ds_write_b16_d16_hi v178, v64 offset:272
	ds_write_b16 v178, v65 offset:544
	ds_write_b16_d16_hi v178, v65 offset:816
	ds_write_b16 v178, v66 offset:2176
	ds_write_b16_d16_hi v178, v66 offset:2448
	ds_write_b16 v178, v67 offset:2720
	ds_write_b16_d16_hi v178, v67 offset:2992
	ds_write_b16 v178, v68 offset:4352
	ds_write_b16_d16_hi v178, v68 offset:4624
	ds_write_b16 v178, v69 offset:4896
	ds_write_b16_d16_hi v178, v69 offset:5168
	ds_write_b16 v178, v70 offset:6528
	ds_write_b16_d16_hi v178, v70 offset:6800
	ds_write_b16 v178, v71 offset:7072
	ds_write_b16_d16_hi v178, v71 offset:7344
	v_cvt_pk_bf16_f32 v72, v16, v17
	v_cvt_pk_bf16_f32 v73, v18, v19
	v_cvt_pk_bf16_f32 v74, v20, v21
	v_cvt_pk_bf16_f32 v75, v22, v23
	v_cvt_pk_bf16_f32 v76, v24, v25
	v_cvt_pk_bf16_f32 v77, v26, v27
	v_cvt_pk_bf16_f32 v78, v28, v29
	v_cvt_pk_bf16_f32 v79, v30, v31
	ds_write_b16 v178, v72 offset:64
	ds_write_b16_d16_hi v178, v72 offset:336
	ds_write_b16 v178, v73 offset:608
	ds_write_b16_d16_hi v178, v73 offset:880
	ds_write_b16 v178, v74 offset:2240
	ds_write_b16_d16_hi v178, v74 offset:2512
	ds_write_b16 v178, v75 offset:2784
	ds_write_b16_d16_hi v178, v75 offset:3056
	ds_write_b16 v178, v76 offset:4416
	ds_write_b16_d16_hi v178, v76 offset:4688
	ds_write_b16 v178, v77 offset:4960
	ds_write_b16_d16_hi v178, v77 offset:5232
	ds_write_b16 v178, v78 offset:6592
	ds_write_b16_d16_hi v178, v78 offset:6864
	ds_write_b16 v178, v79 offset:7136
	ds_write_b16_d16_hi v178, v79 offset:7408
	v_cvt_pk_bf16_f32 v128, v32, v33
	v_cvt_pk_bf16_f32 v129, v34, v35
	v_cvt_pk_bf16_f32 v130, v36, v37
	v_cvt_pk_bf16_f32 v131, v38, v39
	v_cvt_pk_bf16_f32 v132, v40, v41
	v_cvt_pk_bf16_f32 v133, v42, v43
	v_cvt_pk_bf16_f32 v134, v44, v45
	v_cvt_pk_bf16_f32 v135, v46, v47
	ds_write_b16 v178, v128 offset:128
	ds_write_b16_d16_hi v178, v128 offset:400
	ds_write_b16 v178, v129 offset:672
	ds_write_b16_d16_hi v178, v129 offset:944
	ds_write_b16 v178, v130 offset:2304
	ds_write_b16_d16_hi v178, v130 offset:2576
	ds_write_b16 v178, v131 offset:2848
	ds_write_b16_d16_hi v178, v131 offset:3120
	ds_write_b16 v178, v132 offset:4480
	ds_write_b16_d16_hi v178, v132 offset:4752
	ds_write_b16 v178, v133 offset:5024
	ds_write_b16_d16_hi v178, v133 offset:5296
	ds_write_b16 v178, v134 offset:6656
	ds_write_b16_d16_hi v178, v134 offset:6928
	ds_write_b16 v178, v135 offset:7200
	ds_write_b16_d16_hi v178, v135 offset:7472
	v_cvt_pk_bf16_f32 v136, v48, v49
	v_cvt_pk_bf16_f32 v137, v50, v51
	v_cvt_pk_bf16_f32 v138, v52, v53
	v_cvt_pk_bf16_f32 v139, v54, v55
	v_cvt_pk_bf16_f32 v140, v56, v57
	v_cvt_pk_bf16_f32 v141, v58, v59
	v_cvt_pk_bf16_f32 v142, v60, v61
	v_cvt_pk_bf16_f32 v143, v62, v63
	ds_write_b16 v178, v136 offset:192
	ds_write_b16_d16_hi v178, v136 offset:464
	ds_write_b16 v178, v137 offset:736
	ds_write_b16_d16_hi v178, v137 offset:1008
	ds_write_b16 v178, v138 offset:2368
	ds_write_b16_d16_hi v178, v138 offset:2640
	ds_write_b16 v178, v139 offset:2912
	ds_write_b16_d16_hi v178, v139 offset:3184
	ds_write_b16 v178, v140 offset:4544
	ds_write_b16_d16_hi v178, v140 offset:4816
	ds_write_b16 v178, v141 offset:5088
	ds_write_b16_d16_hi v178, v141 offset:5360
	ds_write_b16 v178, v142 offset:6720
	ds_write_b16_d16_hi v178, v142 offset:6992
	ds_write_b16 v178, v143 offset:7264
	ds_write_b16_d16_hi v178, v143 offset:7536
	s_waitcnt lgkmcnt(0)
	ds_read_b128 v[80:83], v174 offset:0
	ds_read_b128 v[84:87], v174 offset:1088
	ds_read_b128 v[88:91], v174 offset:2176
	ds_read_b128 v[92:95], v174 offset:3264
	ds_read_b128 v[96:99], v174 offset:4352
	ds_read_b128 v[100:103], v174 offset:5440
	ds_read_b128 v[104:107], v174 offset:6528
	ds_read_b128 v[108:111], v174 offset:7616
	s_waitcnt lgkmcnt(7)
	global_store_dwordx4 v[144:145], v[80:83], off sc1
	v_lshl_add_u64 v[144:145], v[144:145], 0, s[26:27]
	s_waitcnt lgkmcnt(6)
	global_store_dwordx4 v[144:145], v[84:87], off sc1
	v_lshl_add_u64 v[144:145], v[144:145], 0, s[26:27]
	s_waitcnt lgkmcnt(5)
	global_store_dwordx4 v[144:145], v[88:91], off sc1
	v_lshl_add_u64 v[144:145], v[144:145], 0, s[26:27]
	s_waitcnt lgkmcnt(4)
	global_store_dwordx4 v[144:145], v[92:95], off sc1
	v_lshl_add_u64 v[144:145], v[144:145], 0, s[26:27]
	s_waitcnt lgkmcnt(3)
	global_store_dwordx4 v[144:145], v[96:99], off sc1
	v_lshl_add_u64 v[144:145], v[144:145], 0, s[26:27]
	s_waitcnt lgkmcnt(2)
	global_store_dwordx4 v[144:145], v[100:103], off sc1
	v_lshl_add_u64 v[144:145], v[144:145], 0, s[26:27]
	s_waitcnt lgkmcnt(1)
	global_store_dwordx4 v[144:145], v[104:107], off sc1
	v_lshl_add_u64 v[144:145], v[144:145], 0, s[26:27]
	s_waitcnt lgkmcnt(0)
	global_store_dwordx4 v[144:145], v[108:111], off sc1
	s_add_u32 s21, s21, 1
	s_cmp_lt_u32 s21, 2
	s_cbranch_scc1 .Ldsa_half
	s_add_u32 s3, s3, s2
	s_branch .Ldsa_unit

; __device__ __forceinline__ unsigned pk2(float lo, float hi) { return pg8::cvt_pk_bf16(lo, hi); }
; __device__ __forceinline__ void sb_unit(const bf16* QKV, bf16* AO, int b, int h, int qblk, LAS unsigned char* wl, int lane) {
;     ...
;     bf16* op = AO + (rowbase + t0) * D + h * 128 + (lane & 31);
; #pragma unroll
;     for (int c = 0; c < 4; ++c)
; #pragma unroll
;         for (int r = 0; r < 16; ++r) { const int row = (r & 3) + 8 * (r >> 2) + 4 * hi; op[(size_t)row * D + 32 * c] = (bf16)(pk2(o[c][r], 0.f) & 0xffffu); }
.LBB0_1042:
	s_lshl_b64 s[2:3], s[2:3], 12
	s_add_u32 s2, s67, s2
	s_addc_u32 s3, s85, s3
	s_lshl_b32 s4, s39, 1
	s_add_u32 s2, s2, s4
	s_addc_u32 s3, s3, 0
	v_lshlrev_b32_e32 v64, 1, v112
	v_mov_b32_e32 v65, v183
	v_lshl_add_u64 v[64:65], s[2:3], 0, v[64:65]
	v_cvt_pk_bf16_f32 v48, v48, v183
	v_lshl_add_u64 v[66:67], v[64:65], 0, v[118:119]
	global_store_short v[66:67], v48, off sc1
	v_cvt_pk_bf16_f32 v68, v49, v183
	v_lshl_add_u64 v[48:49], v[64:65], 0, v[120:121]
	global_store_short v[48:49], v68, off sc1
	v_cvt_pk_bf16_f32 v50, v50, v183
	v_lshl_add_u64 v[68:69], v[64:65], 0, v[122:123]
	global_store_short v[68:69], v50, off sc1
	v_cvt_pk_bf16_f32 v70, v51, v183
	v_lshl_add_u64 v[50:51], v[64:65], 0, v[124:125]
	global_store_short v[50:51], v70, off sc1
	v_cvt_pk_bf16_f32 v52, v52, v183
	v_lshl_add_u64 v[70:71], v[64:65], 0, v[126:127]
	global_store_short v[70:71], v52, off sc1
	v_cvt_pk_bf16_f32 v72, v53, v183
	v_lshl_add_u64 v[52:53], v[64:65], 0, v[128:129]
	global_store_short v[52:53], v72, off sc1
	v_cvt_pk_bf16_f32 v54, v54, v183
	v_lshl_add_u64 v[72:73], v[64:65], 0, v[130:131]
	global_store_short v[72:73], v54, off sc1
	v_cvt_pk_bf16_f32 v74, v55, v183
	v_lshl_add_u64 v[54:55], v[64:65], 0, v[132:133]
	global_store_short v[54:55], v74, off sc1
	v_cvt_pk_bf16_f32 v56, v56, v183
	v_lshl_add_u64 v[74:75], v[64:65], 0, v[134:135]
	global_store_short v[74:75], v56, off sc1
	v_cvt_pk_bf16_f32 v76, v57, v183
	v_lshl_add_u64 v[56:57], v[64:65], 0, v[136:137]
	global_store_short v[56:57], v76, off sc1
	v_cvt_pk_bf16_f32 v58, v58, v183
	v_lshl_add_u64 v[76:77], v[64:65], 0, v[138:139]
	global_store_short v[76:77], v58, off sc1
	v_cvt_pk_bf16_f32 v78, v59, v183
	v_lshl_add_u64 v[58:59], v[64:65], 0, v[140:141]
	global_store_short v[58:59], v78, off sc1
	v_cvt_pk_bf16_f32 v60, v60, v183
	v_lshl_add_u64 v[78:79], v[64:65], 0, v[142:143]
	global_store_short v[78:79], v60, off sc1
	v_cvt_pk_bf16_f32 v80, v61, v183
	v_lshl_add_u64 v[60:61], v[64:65], 0, v[144:145]
	global_store_short v[60:61], v80, off sc1
	v_cvt_pk_bf16_f32 v62, v62, v183
	v_lshl_add_u64 v[80:81], v[64:65], 0, v[146:147]
	global_store_short v[80:81], v62, off sc1
	v_cvt_pk_bf16_f32 v82, v63, v183
	v_lshl_add_u64 v[62:63], v[64:65], 0, v[148:149]
	global_store_short v[62:63], v82, off sc1
	v_cvt_pk_bf16_f32 v32, v32, v183
	global_store_short v[66:67], v32, off offset:64 sc1
	v_cvt_pk_bf16_f32 v32, v33, v183
	global_store_short v[48:49], v32, off offset:64 sc1
	v_cvt_pk_bf16_f32 v32, v34, v183
	global_store_short v[68:69], v32, off offset:64 sc1
	v_cvt_pk_bf16_f32 v32, v35, v183
	global_store_short v[50:51], v32, off offset:64 sc1
	v_cvt_pk_bf16_f32 v32, v36, v183
	global_store_short v[70:71], v32, off offset:64 sc1
	v_cvt_pk_bf16_f32 v32, v37, v183
	global_store_short v[52:53], v32, off offset:64 sc1
	v_cvt_pk_bf16_f32 v32, v38, v183
	global_store_short v[72:73], v32, off offset:64 sc1
	v_cvt_pk_bf16_f32 v32, v39, v183
	global_store_short v[54:55], v32, off offset:64 sc1
	v_cvt_pk_bf16_f32 v32, v40, v183
	global_store_short v[74:75], v32, off offset:64 sc1
	v_cvt_pk_bf16_f32 v32, v41, v183
	global_store_short v[56:57], v32, off offset:64 sc1
	v_cvt_pk_bf16_f32 v32, v42, v183
	global_store_short v[76:77], v32, off offset:64 sc1
	v_cvt_pk_bf16_f32 v32, v43, v183
	global_store_short v[58:59], v32, off offset:64 sc1
	v_cvt_pk_bf16_f32 v32, v44, v183
	global_store_short v[78:79], v32, off offset:64 sc1
	v_cvt_pk_bf16_f32 v32, v45, v183
	global_store_short v[60:61], v32, off offset:64 sc1
	v_cvt_pk_bf16_f32 v32, v46, v183
	global_store_short v[80:81], v32, off offset:64 sc1
	v_cvt_pk_bf16_f32 v32, v47, v183
	global_store_short v[62:63], v32, off offset:64 sc1
	v_cvt_pk_bf16_f32 v16, v16, v183
	global_store_short v[66:67], v16, off offset:128 sc1
	v_cvt_pk_bf16_f32 v16, v17, v183
	global_store_short v[48:49], v16, off offset:128 sc1
	v_cvt_pk_bf16_f32 v16, v18, v183
	global_store_short v[68:69], v16, off offset:128 sc1
	v_cvt_pk_bf16_f32 v16, v19, v183
	global_store_short v[50:51], v16, off offset:128 sc1
	v_cvt_pk_bf16_f32 v16, v20, v183
	global_store_short v[70:71], v16, off offset:128 sc1
	v_cvt_pk_bf16_f32 v16, v21, v183
	global_store_short v[52:53], v16, off offset:128 sc1
	v_cvt_pk_bf16_f32 v16, v22, v183
	global_store_short v[72:73], v16, off offset:128 sc1
	v_cvt_pk_bf16_f32 v16, v23, v183
	global_store_short v[54:55], v16, off offset:128 sc1
	v_cvt_pk_bf16_f32 v16, v24, v183
	global_store_short v[74:75], v16, off offset:128 sc1
	v_cvt_pk_bf16_f32 v16, v25, v183
	global_store_short v[56:57], v16, off offset:128 sc1
	v_cvt_pk_bf16_f32 v16, v26, v183
	global_store_short v[76:77], v16, off offset:128 sc1
	v_cvt_pk_bf16_f32 v16, v27, v183
	global_store_short v[58:59], v16, off offset:128 sc1
	v_cvt_pk_bf16_f32 v16, v28, v183
	global_store_short v[78:79], v16, off offset:128 sc1
	v_cvt_pk_bf16_f32 v16, v29, v183
	global_store_short v[60:61], v16, off offset:128 sc1
	v_cvt_pk_bf16_f32 v16, v30, v183
	global_store_short v[80:81], v16, off offset:128 sc1
	v_cvt_pk_bf16_f32 v16, v31, v183
	global_store_short v[62:63], v16, off offset:128 sc1
	v_cvt_pk_bf16_f32 v0, v0, v183
	global_store_short v[66:67], v0, off offset:192 sc1
	v_cvt_pk_bf16_f32 v0, v1, v183
	global_store_short v[48:49], v0, off offset:192 sc1
	v_cvt_pk_bf16_f32 v0, v2, v183
	global_store_short v[68:69], v0, off offset:192 sc1
	v_cvt_pk_bf16_f32 v0, v3, v183
	global_store_short v[50:51], v0, off offset:192 sc1
	v_cvt_pk_bf16_f32 v0, v4, v183
	global_store_short v[70:71], v0, off offset:192 sc1
	v_cvt_pk_bf16_f32 v0, v5, v183
	global_store_short v[52:53], v0, off offset:192 sc1
	v_cvt_pk_bf16_f32 v0, v6, v183
	global_store_short v[72:73], v0, off offset:192 sc1
	v_cvt_pk_bf16_f32 v0, v7, v183
	global_store_short v[54:55], v0, off offset:192 sc1
	v_cvt_pk_bf16_f32 v0, v8, v183
	global_store_short v[74:75], v0, off offset:192 sc1
	v_cvt_pk_bf16_f32 v0, v9, v183
	global_store_short v[56:57], v0, off offset:192 sc1
	v_cvt_pk_bf16_f32 v0, v10, v183
	global_store_short v[76:77], v0, off offset:192 sc1
	v_cvt_pk_bf16_f32 v0, v11, v183
	global_store_short v[58:59], v0, off offset:192 sc1
	v_cvt_pk_bf16_f32 v0, v12, v183
	global_store_short v[78:79], v0, off offset:192 sc1
	v_cvt_pk_bf16_f32 v0, v13, v183
	s_add_i32 s38, s38, s84
	global_store_short v[60:61], v0, off offset:192 sc1
	v_cvt_pk_bf16_f32 v0, v14, v183
	s_cmpk_gt_i32 s38, 0x1fff
	global_store_short v[80:81], v0, off offset:192 sc1
	v_cvt_pk_bf16_f32 v0, v15, v183
	global_store_short v[62:63], v0, off offset:192 sc1
	s_cbranch_scc1 .LBB0_1048
